# removed every s_setprio from the 8 GEMM K-loops (on top of previous cleanup)
# speedup vs baseline: 1.0121x; 1.0096x over previous
;     __device__ __forceinline__ int nt(const Unit& u) const { return (u.pn >> 1) < 2 ? 22 : 20; }
; #define PG8_STAGE(bufoff, gbase, voff) do { _Pragma("unroll") for (int _i = 0; _i < 2; ++_i) \
;         __builtin_amdgcn_global_load_lds((const unsigned*)((const char*)(gbase) + (voff)[_i]), (LAS unsigned*)(lds + (bufoff) + ldsw + _i * 8192), 16, 0, 0); } while (0)
; #define PG8_LDA(dst, b, h) do { _Pragma("unroll") for (int m = 0; m < 4; ++m) _Pragma("unroll") for (int k = 0; k < 2; ++k) dst[m][k] = *(const LAS bf16x8*)(pA + PG8_SA(b, h) + m * 2048 + k * 1024); } while (0)
; #define PG8_LDB(dst, b, h) do { _Pragma("unroll") for (int n = 0; n < 2; ++n) _Pragma("unroll") for (int k = 0; k < 2; ++k) dst[n][k] = *(const LAS bf16x8*)(pB + (PG8_SB(b, h) - 4 * HTB) + n * 2048 + k * 1024); } while (0)
; #define PG8_MMA(ai, bj, At, Bt) do { __builtin_amdgcn_s_setprio(1); _Pragma("unroll") for (int m = 0; m < 4; ++m) _Pragma("unroll") for (int n = 0; n < 2; ++n) _Pragma("unroll") for (int k = 0; k < 2; ++k) \
;         acc[ai][bj][m][n] = __builtin_amdgcn_mfma_f32_16x16x32_bf16(Bt[n][k], At[m][k], acc[ai][bj][m][n], 0, 0, 0); __builtin_amdgcn_s_setprio(0); } while (0)
; #define PG8_WAIT_V(n) asm volatile("s_waitcnt vmcnt(" #n ")" ::: "memory")
; #define PG8_WAIT_L(n) asm volatile("s_waitcnt lgkmcnt(" #n ")" ::: "memory")
; template <class Desc, class Epi, bool ALIGN_EPI>
; __device__ __forceinline__ void gemm_phase(LAS unsigned char* lds, const Desc& D, const Epi& E, int G, int c) {
;     ...
;             const bool last = (t == nt - 2);
;             if (last && has_next) PG8_AWAIT(nxt);
;             const char* a1 = cA + (size_t)(t + 1) * kstep;
;             const char* a2 = last ? nA : cA + (size_t)(t + 2) * kstep; const char* b2 = last ? nB : cB + (size_t)(t + 2) * kstep;
;             const char* a3 = a2 + kstep; const char* b3 = b2 + kstep;
;             PG8_LDB(B0, 0, 0); PG8_LDB(B1, 0, 1); PG8_SCHED; PG8_LDA(At, 0, 0); PG8_STAGE(PG8_SA(1, 1), a1 + hstepA, voffA);
;             PG8_WAIT_V(8); PG8_WAIT_L(0); PG8_BAR; PG8_MMA(0, 0, At, B0); PG8_MMA(0, 1, At, B1); PG8_BAR; PG8_SCHED;
;             PG8_LDA(At, 0, 1); PG8_STAGE(PG8_SB(0, 0), b2, voffB); PG8_STAGE(PG8_SB(0, 1), b2 + hstepB, voffB); PG8_STAGE(PG8_SA(0, 0), a2, voffA);
;             PG8_WAIT_V(8); PG8_WAIT_L(0); PG8_BAR; PG8_MMA(1, 0, At, B0); PG8_MMA(1, 1, At, B1); PG8_BAR; PG8_SCHED;
.LBB0_172:
	s_or_b32 s14, s17, 1
	s_lshl_b64 s[26:27], s[14:15], 7
	s_add_i32 s14, s17, 2
	s_lshl_b64 s[40:41], s[14:15], 7
	s_add_u32 s17, s12, s40
	ds_read_b128 v[134:137], v169
	ds_read_b128 v[138:141], v169 offset:1024
	ds_read_b128 v[142:145], v169 offset:2048
	ds_read_b128 v[146:149], v169 offset:3072
	ds_read_b128 v[160:163], v169 offset:16384
	ds_read_b128 v[164:167], v169 offset:17408
	ds_read_b128 v[174:177], v169 offset:18432
	ds_read_b128 v[178:181], v169 offset:19456
	s_addc_u32 s21, s13, s41
	s_and_b64 s[38:39], s[30:31], exec
	s_cselect_b32 s39, s61, s21
	s_cselect_b32 s38, s60, s17
	s_add_u32 s17, s18, s40
	s_addc_u32 s21, s19, s41
	s_and_b64 s[30:31], s[30:31], exec
	s_cselect_b32 s31, s63, s21
	s_cselect_b32 s30, s62, s17
	s_add_u32 s17, s12, s26
	s_addc_u32 s21, s13, s27
	s_add_u32 s26, s17, 0x100000
	s_addc_u32 s27, s21, 0
	s_mov_b32 m0, s50
	v_lshl_add_u64 v[150:151], s[26:27], 0, v[152:153]
	ds_read_b128 v[182:185], v168
	ds_read_b128 v[186:189], v168 offset:1024
	ds_read_b128 v[190:193], v168 offset:2048
	ds_read_b128 v[194:197], v168 offset:3072
	ds_read_b128 v[198:201], v168 offset:4096
	ds_read_b128 v[202:205], v168 offset:5120
	ds_read_b128 v[206:209], v168 offset:6144
	ds_read_b128 v[210:213], v168 offset:7168
	global_load_lds_dwordx4 v[150:151], off
	v_lshl_add_u64 v[150:151], s[26:27], 0, v[156:157]
	s_mov_b32 m0, s51
	s_nop 0
	global_load_lds_dwordx4 v[150:151], off
	s_waitcnt vmcnt(8)
	s_waitcnt lgkmcnt(0)
	s_barrier
	v_mfma_f32_16x16x32_bf16 v[128:131], v[134:137], v[182:185], v[128:131]
	v_mfma_f32_16x16x32_bf16 v[124:127], v[142:145], v[182:185], v[124:127]
	v_mfma_f32_16x16x32_bf16 v[120:123], v[134:137], v[190:193], v[120:123]
	v_mfma_f32_16x16x32_bf16 v[116:119], v[142:145], v[190:193], v[116:119]
	v_mfma_f32_16x16x32_bf16 v[112:115], v[134:137], v[198:201], v[112:115]
	v_mfma_f32_16x16x32_bf16 v[108:111], v[142:145], v[198:201], v[108:111]
	v_mfma_f32_16x16x32_bf16 v[104:107], v[134:137], v[206:209], v[104:107]
	v_mfma_f32_16x16x32_bf16 v[100:103], v[142:145], v[206:209], v[100:103]
	v_mfma_f32_16x16x32_bf16 v[128:131], v[138:141], v[186:189], v[128:131]
	v_mfma_f32_16x16x32_bf16 v[124:127], v[146:149], v[186:189], v[124:127]
	v_mfma_f32_16x16x32_bf16 v[120:123], v[138:141], v[194:197], v[120:123]
	v_mfma_f32_16x16x32_bf16 v[116:119], v[146:149], v[194:197], v[116:119]
	v_mfma_f32_16x16x32_bf16 v[112:115], v[138:141], v[202:205], v[112:115]
	v_mfma_f32_16x16x32_bf16 v[108:111], v[146:149], v[202:205], v[108:111]
	v_mfma_f32_16x16x32_bf16 v[104:107], v[138:141], v[210:213], v[104:107]
	v_mfma_f32_16x16x32_bf16 v[100:103], v[146:149], v[210:213], v[100:103]
	v_mfma_f32_16x16x32_bf16 v[96:99], v[160:163], v[182:185], v[96:99]
	v_mfma_f32_16x16x32_bf16 v[92:95], v[174:177], v[182:185], v[92:95]
	v_mfma_f32_16x16x32_bf16 v[88:91], v[160:163], v[190:193], v[88:91]
	v_mfma_f32_16x16x32_bf16 v[84:87], v[174:177], v[190:193], v[84:87]
	v_mfma_f32_16x16x32_bf16 v[80:83], v[160:163], v[198:201], v[80:83]
	v_mfma_f32_16x16x32_bf16 v[76:79], v[174:177], v[198:201], v[76:79]
	v_mfma_f32_16x16x32_bf16 v[72:75], v[160:163], v[206:209], v[72:75]
	v_mfma_f32_16x16x32_bf16 v[68:71], v[174:177], v[206:209], v[68:71]
	v_mfma_f32_16x16x32_bf16 v[96:99], v[164:167], v[186:189], v[96:99]
	v_mfma_f32_16x16x32_bf16 v[92:95], v[178:181], v[186:189], v[92:95]
	v_mfma_f32_16x16x32_bf16 v[88:91], v[164:167], v[194:197], v[88:91]
	v_mfma_f32_16x16x32_bf16 v[84:87], v[178:181], v[194:197], v[84:87]
	v_mfma_f32_16x16x32_bf16 v[80:83], v[164:167], v[202:205], v[80:83]
	v_mfma_f32_16x16x32_bf16 v[76:79], v[178:181], v[202:205], v[76:79]
	v_mfma_f32_16x16x32_bf16 v[72:75], v[164:167], v[210:213], v[72:75]
	v_mfma_f32_16x16x32_bf16 v[68:71], v[178:181], v[210:213], v[68:71]
	s_barrier
	s_mov_b32 m0, s84
	v_lshl_add_u64 v[150:151], s[30:31], 0, v[154:155]
	s_add_u32 s26, s30, 0x100000
	ds_read_b128 v[182:185], v168 offset:16384
	ds_read_b128 v[186:189], v168 offset:17408
	ds_read_b128 v[190:193], v168 offset:18432
	ds_read_b128 v[194:197], v168 offset:19456
	ds_read_b128 v[198:201], v168 offset:20480
	ds_read_b128 v[202:205], v168 offset:21504
	ds_read_b128 v[206:209], v168 offset:22528
	ds_read_b128 v[210:213], v168 offset:23552
	global_load_lds_dwordx4 v[150:151], off
	v_lshl_add_u64 v[214:215], s[30:31], 0, v[158:159]
	s_mov_b32 m0, s85
	s_addc_u32 s27, s31, 0
	global_load_lds_dwordx4 v[214:215], off
	v_lshl_add_u64 v[216:217], s[26:27], 0, v[154:155]
	s_mov_b32 m0, s86
	v_lshl_add_u64 v[218:219], s[38:39], 0, v[156:157]
	global_load_lds_dwordx4 v[216:217], off
	v_lshl_add_u64 v[216:217], s[26:27], 0, v[158:159]
	s_mov_b32 m0, s87
	s_nop 0
	global_load_lds_dwordx4 v[216:217], off
	v_lshl_add_u64 v[216:217], s[38:39], 0, v[152:153]
	s_mov_b32 m0, s83
	s_nop 0
	global_load_lds_dwordx4 v[216:217], off
	s_mov_b32 m0, s88
	s_nop 0
	global_load_lds_dwordx4 v[218:219], off
	s_waitcnt vmcnt(8)
	s_waitcnt lgkmcnt(0)
	s_barrier
; #define PG8_STAGE(bufoff, gbase, voff) do { _Pragma("unroll") for (int _i = 0; _i < 2; ++_i) \
;         __builtin_amdgcn_global_load_lds((const unsigned*)((const char*)(gbase) + (voff)[_i]), (LAS unsigned*)(lds + (bufoff) + ldsw + _i * 8192), 16, 0, 0); } while (0)
; #define PG8_LDA(dst, b, h) do { _Pragma("unroll") for (int m = 0; m < 4; ++m) _Pragma("unroll") for (int k = 0; k < 2; ++k) dst[m][k] = *(const LAS bf16x8*)(pA + PG8_SA(b, h) + m * 2048 + k * 1024); } while (0)
; #define PG8_LDB(dst, b, h) do { _Pragma("unroll") for (int n = 0; n < 2; ++n) _Pragma("unroll") for (int k = 0; k < 2; ++k) dst[n][k] = *(const LAS bf16x8*)(pB + (PG8_SB(b, h) - 4 * HTB) + n * 2048 + k * 1024); } while (0)
; #define PG8_MMA(ai, bj, At, Bt) do { __builtin_amdgcn_s_setprio(1); _Pragma("unroll") for (int m = 0; m < 4; ++m) _Pragma("unroll") for (int n = 0; n < 2; ++n) _Pragma("unroll") for (int k = 0; k < 2; ++k) \
;         acc[ai][bj][m][n] = __builtin_amdgcn_mfma_f32_16x16x32_bf16(Bt[n][k], At[m][k], acc[ai][bj][m][n], 0, 0, 0); __builtin_amdgcn_s_setprio(0); } while (0)
; #define PG8_WAIT_V(n) asm volatile("s_waitcnt vmcnt(" #n ")" ::: "memory")
; #define PG8_WAIT_L(n) asm volatile("s_waitcnt lgkmcnt(" #n ")" ::: "memory")
; #define PG8_BAR __builtin_amdgcn_s_barrier()
; #define PG8_SCHED __builtin_amdgcn_sched_barrier(0)
; template <class Desc, class Epi, bool ALIGN_EPI>
; __device__ __forceinline__ void gemm_phase(LAS unsigned char* lds, const Desc& D, const Epi& E, int G, int c) {
;     ...
;             PG8_WAIT_V(8); PG8_WAIT_L(0); PG8_BAR; PG8_MMA(1, 0, At, B0); PG8_MMA(1, 1, At, B1); PG8_BAR; PG8_SCHED;
;             PG8_LDB(B0, 1, 0); PG8_LDB(B1, 1, 1); PG8_SCHED; PG8_LDA(At, 1, 0); PG8_STAGE(PG8_SA(0, 1), a2 + hstepA, voffA);
;             PG8_WAIT_V(8); PG8_WAIT_L(0); PG8_BAR; PG8_MMA(0, 0, At, B0); PG8_MMA(0, 1, At, B1); PG8_BAR; PG8_SCHED;
	v_mfma_f32_16x16x32_bf16 v[64:67], v[134:137], v[182:185], v[64:67]
	v_mfma_f32_16x16x32_bf16 v[52:55], v[142:145], v[182:185], v[52:55]
	v_mfma_f32_16x16x32_bf16 v[32:35], v[134:137], v[190:193], v[32:35]
	v_mfma_f32_16x16x32_bf16 v[20:23], v[142:145], v[190:193], v[20:23]
	v_mfma_f32_16x16x32_bf16 v[16:19], v[134:137], v[198:201], v[16:19]
	v_mfma_f32_16x16x32_bf16 v[12:15], v[142:145], v[198:201], v[12:15]
	v_mfma_f32_16x16x32_bf16 v[8:11], v[134:137], v[206:209], v[8:11]
	v_mfma_f32_16x16x32_bf16 v[4:7], v[142:145], v[206:209], v[4:7]
	v_mfma_f32_16x16x32_bf16 v[64:67], v[138:141], v[186:189], v[64:67]
	v_mfma_f32_16x16x32_bf16 v[52:55], v[146:149], v[186:189], v[52:55]
	v_mfma_f32_16x16x32_bf16 v[32:35], v[138:141], v[194:197], v[32:35]
	v_mfma_f32_16x16x32_bf16 v[20:23], v[146:149], v[194:197], v[20:23]
	v_mfma_f32_16x16x32_bf16 v[16:19], v[138:141], v[202:205], v[16:19]
	v_mfma_f32_16x16x32_bf16 v[12:15], v[146:149], v[202:205], v[12:15]
	v_mfma_f32_16x16x32_bf16 v[8:11], v[138:141], v[210:213], v[8:11]
	v_mfma_f32_16x16x32_bf16 v[4:7], v[146:149], v[210:213], v[4:7]
	v_mfma_f32_16x16x32_bf16 v[60:63], v[160:163], v[182:185], v[60:63]
	v_mfma_f32_16x16x32_bf16 v[56:59], v[174:177], v[182:185], v[56:59]
	v_mfma_f32_16x16x32_bf16 v[48:51], v[160:163], v[190:193], v[48:51]
	v_mfma_f32_16x16x32_bf16 v[44:47], v[174:177], v[190:193], v[44:47]
	v_mfma_f32_16x16x32_bf16 v[40:43], v[160:163], v[198:201], v[40:43]
	v_mfma_f32_16x16x32_bf16 v[36:39], v[174:177], v[198:201], v[36:39]
	v_mfma_f32_16x16x32_bf16 v[28:31], v[160:163], v[206:209], v[28:31]
	v_mfma_f32_16x16x32_bf16 v[24:27], v[174:177], v[206:209], v[24:27]
	v_mfma_f32_16x16x32_bf16 v[60:63], v[164:167], v[186:189], v[60:63]
	v_mfma_f32_16x16x32_bf16 v[56:59], v[178:181], v[186:189], v[56:59]
	v_mfma_f32_16x16x32_bf16 v[48:51], v[164:167], v[194:197], v[48:51]
	v_mfma_f32_16x16x32_bf16 v[44:47], v[178:181], v[194:197], v[44:47]
	v_mfma_f32_16x16x32_bf16 v[40:43], v[164:167], v[202:205], v[40:43]
	v_mfma_f32_16x16x32_bf16 v[36:39], v[178:181], v[202:205], v[36:39]
	v_mfma_f32_16x16x32_bf16 v[28:31], v[164:167], v[210:213], v[28:31]
	v_mfma_f32_16x16x32_bf16 v[24:27], v[178:181], v[210:213], v[24:27]
	s_barrier
	ds_read_b128 v[134:137], v169 offset:32768
	ds_read_b128 v[138:141], v169 offset:33792
	ds_read_b128 v[142:145], v169 offset:34816
	ds_read_b128 v[146:149], v169 offset:35840
	ds_read_b128 v[160:163], v169 offset:49152
	ds_read_b128 v[164:167], v169 offset:50176
	ds_read_b128 v[174:177], v169 offset:51200
	ds_read_b128 v[178:181], v169 offset:52224
	s_add_u32 s26, s38, 0x100000
	s_addc_u32 s27, s39, 0
	s_mov_b32 m0, s89
	v_lshl_add_u64 v[220:221], s[26:27], 0, v[152:153]
	ds_read_b128 v[182:185], v168 offset:32768
	ds_read_b128 v[186:189], v168 offset:33792
	ds_read_b128 v[190:193], v168 offset:34816
	ds_read_b128 v[194:197], v168 offset:35840
	ds_read_b128 v[198:201], v168 offset:36864
	ds_read_b128 v[202:205], v168 offset:37888
	ds_read_b128 v[206:209], v168 offset:38912
	ds_read_b128 v[210:213], v168 offset:39936
	global_load_lds_dwordx4 v[220:221], off
	v_lshl_add_u64 v[220:221], s[26:27], 0, v[156:157]
	s_mov_b32 m0, s90
	s_nop 0
	global_load_lds_dwordx4 v[220:221], off
	s_waitcnt vmcnt(8)
	s_waitcnt lgkmcnt(0)
	s_barrier
	v_mfma_f32_16x16x32_bf16 v[128:131], v[134:137], v[182:185], v[128:131]
	v_mfma_f32_16x16x32_bf16 v[124:127], v[142:145], v[182:185], v[124:127]
	v_mfma_f32_16x16x32_bf16 v[120:123], v[134:137], v[190:193], v[120:123]
	v_mfma_f32_16x16x32_bf16 v[116:119], v[142:145], v[190:193], v[116:119]
	v_mfma_f32_16x16x32_bf16 v[112:115], v[134:137], v[198:201], v[112:115]
	v_mfma_f32_16x16x32_bf16 v[108:111], v[142:145], v[198:201], v[108:111]
	v_mfma_f32_16x16x32_bf16 v[104:107], v[134:137], v[206:209], v[104:107]
	v_mfma_f32_16x16x32_bf16 v[100:103], v[142:145], v[206:209], v[100:103]
	v_mfma_f32_16x16x32_bf16 v[128:131], v[138:141], v[186:189], v[128:131]
	v_mfma_f32_16x16x32_bf16 v[124:127], v[146:149], v[186:189], v[124:127]
	v_mfma_f32_16x16x32_bf16 v[120:123], v[138:141], v[194:197], v[120:123]
	v_mfma_f32_16x16x32_bf16 v[116:119], v[146:149], v[194:197], v[116:119]
	v_mfma_f32_16x16x32_bf16 v[112:115], v[138:141], v[202:205], v[112:115]
	v_mfma_f32_16x16x32_bf16 v[108:111], v[146:149], v[202:205], v[108:111]
	v_mfma_f32_16x16x32_bf16 v[104:107], v[138:141], v[210:213], v[104:107]
	v_mfma_f32_16x16x32_bf16 v[100:103], v[146:149], v[210:213], v[100:103]
	v_mfma_f32_16x16x32_bf16 v[96:99], v[160:163], v[182:185], v[96:99]
	v_mfma_f32_16x16x32_bf16 v[92:95], v[174:177], v[182:185], v[92:95]
	v_mfma_f32_16x16x32_bf16 v[88:91], v[160:163], v[190:193], v[88:91]
	v_mfma_f32_16x16x32_bf16 v[84:87], v[174:177], v[190:193], v[84:87]
	v_mfma_f32_16x16x32_bf16 v[80:83], v[160:163], v[198:201], v[80:83]
	v_mfma_f32_16x16x32_bf16 v[76:79], v[174:177], v[198:201], v[76:79]
	v_mfma_f32_16x16x32_bf16 v[72:75], v[160:163], v[206:209], v[72:75]
	v_mfma_f32_16x16x32_bf16 v[68:71], v[174:177], v[206:209], v[68:71]
	v_mfma_f32_16x16x32_bf16 v[96:99], v[164:167], v[186:189], v[96:99]
	v_mfma_f32_16x16x32_bf16 v[92:95], v[178:181], v[186:189], v[92:95]
	v_mfma_f32_16x16x32_bf16 v[88:91], v[164:167], v[194:197], v[88:91]
	v_mfma_f32_16x16x32_bf16 v[84:87], v[178:181], v[194:197], v[84:87]
	v_mfma_f32_16x16x32_bf16 v[80:83], v[164:167], v[202:205], v[80:83]
	v_mfma_f32_16x16x32_bf16 v[76:79], v[178:181], v[202:205], v[76:79]
	v_mfma_f32_16x16x32_bf16 v[72:75], v[164:167], v[210:213], v[72:75]
	v_mfma_f32_16x16x32_bf16 v[68:71], v[178:181], v[210:213], v[68:71]
	s_barrier
; #define PG8_STAGE(bufoff, gbase, voff) do { _Pragma("unroll") for (int _i = 0; _i < 2; ++_i) \
;         __builtin_amdgcn_global_load_lds((const unsigned*)((const char*)(gbase) + (voff)[_i]), (LAS unsigned*)(lds + (bufoff) + ldsw + _i * 8192), 16, 0, 0); } while (0)
; #define PG8_LDA(dst, b, h) do { _Pragma("unroll") for (int m = 0; m < 4; ++m) _Pragma("unroll") for (int k = 0; k < 2; ++k) dst[m][k] = *(const LAS bf16x8*)(pA + PG8_SA(b, h) + m * 2048 + k * 1024); } while (0)
; #define PG8_MMA(ai, bj, At, Bt) do { __builtin_amdgcn_s_setprio(1); _Pragma("unroll") for (int m = 0; m < 4; ++m) _Pragma("unroll") for (int n = 0; n < 2; ++n) _Pragma("unroll") for (int k = 0; k < 2; ++k) \
;         acc[ai][bj][m][n] = __builtin_amdgcn_mfma_f32_16x16x32_bf16(Bt[n][k], At[m][k], acc[ai][bj][m][n], 0, 0, 0); __builtin_amdgcn_s_setprio(0); } while (0)
; #define PG8_WAIT_V(n) asm volatile("s_waitcnt vmcnt(" #n ")" ::: "memory")
; #define PG8_WAIT_L(n) asm volatile("s_waitcnt lgkmcnt(" #n ")" ::: "memory")
; #define PG8_BAR __builtin_amdgcn_s_barrier()
; #define PG8_SCHED __builtin_amdgcn_sched_barrier(0)
; template <class Desc, class Epi, bool ALIGN_EPI>
; __device__ __forceinline__ void gemm_phase(LAS unsigned char* lds, const Desc& D, const Epi& E, int G, int c) {
;     ...
;             PG8_LDA(At, 1, 1); PG8_STAGE(PG8_SB(1, 0), b3, voffB); PG8_STAGE(PG8_SB(1, 1), b3 + hstepB, voffB); PG8_STAGE(PG8_SA(1, 0), a3, voffA);
;             PG8_WAIT_V(8); PG8_WAIT_L(0); PG8_BAR; PG8_MMA(1, 0, At, B0); PG8_MMA(1, 1, At, B1); PG8_BAR; PG8_SCHED;
;         }
	s_mov_b32 m0, s92
	v_lshl_add_u64 v[150:151], v[150:151], 0, s[76:77]
	s_add_u32 s26, s30, 0x100080
	ds_read_b128 v[182:185], v168 offset:49152
	ds_read_b128 v[186:189], v168 offset:50176
	ds_read_b128 v[190:193], v168 offset:51200
	ds_read_b128 v[194:197], v168 offset:52224
	ds_read_b128 v[198:201], v168 offset:53248
	ds_read_b128 v[202:205], v168 offset:54272
	ds_read_b128 v[206:209], v168 offset:55296
	ds_read_b128 v[210:213], v168 offset:56320
	global_load_lds_dwordx4 v[150:151], off
	v_lshl_add_u64 v[150:151], v[214:215], 0, s[76:77]
	s_mov_b32 m0, s93
	s_addc_u32 s27, s31, 0
	global_load_lds_dwordx4 v[150:151], off
	v_lshl_add_u64 v[150:151], s[26:27], 0, v[154:155]
	s_mov_b32 m0, s97
	s_nop 0
	global_load_lds_dwordx4 v[150:151], off
	v_lshl_add_u64 v[150:151], s[26:27], 0, v[158:159]
	s_mov_b32 m0, s82
	s_nop 0
	global_load_lds_dwordx4 v[150:151], off
	v_lshl_add_u64 v[150:151], v[216:217], 0, s[76:77]
	s_mov_b32 m0, s94
	s_nop 0
	global_load_lds_dwordx4 v[150:151], off
	v_lshl_add_u64 v[150:151], v[218:219], 0, s[76:77]
	s_mov_b32 m0, s95
	s_nop 0
	global_load_lds_dwordx4 v[150:151], off
	s_waitcnt vmcnt(8)
	s_waitcnt lgkmcnt(0)
	s_barrier
	v_mfma_f32_16x16x32_bf16 v[64:67], v[134:137], v[182:185], v[64:67]
	v_mfma_f32_16x16x32_bf16 v[52:55], v[142:145], v[182:185], v[52:55]
	v_mfma_f32_16x16x32_bf16 v[32:35], v[134:137], v[190:193], v[32:35]
	v_mfma_f32_16x16x32_bf16 v[20:23], v[142:145], v[190:193], v[20:23]
	v_mfma_f32_16x16x32_bf16 v[16:19], v[134:137], v[198:201], v[16:19]
	v_mfma_f32_16x16x32_bf16 v[12:15], v[142:145], v[198:201], v[12:15]
	v_mfma_f32_16x16x32_bf16 v[8:11], v[134:137], v[206:209], v[8:11]
	v_mfma_f32_16x16x32_bf16 v[4:7], v[142:145], v[206:209], v[4:7]
	v_mfma_f32_16x16x32_bf16 v[64:67], v[138:141], v[186:189], v[64:67]
	v_mfma_f32_16x16x32_bf16 v[52:55], v[146:149], v[186:189], v[52:55]
	v_mfma_f32_16x16x32_bf16 v[32:35], v[138:141], v[194:197], v[32:35]
	v_mfma_f32_16x16x32_bf16 v[20:23], v[146:149], v[194:197], v[20:23]
	v_mfma_f32_16x16x32_bf16 v[16:19], v[138:141], v[202:205], v[16:19]
	v_mfma_f32_16x16x32_bf16 v[12:15], v[146:149], v[202:205], v[12:15]
	v_mfma_f32_16x16x32_bf16 v[8:11], v[138:141], v[210:213], v[8:11]
	v_mfma_f32_16x16x32_bf16 v[4:7], v[146:149], v[210:213], v[4:7]
	v_mfma_f32_16x16x32_bf16 v[60:63], v[160:163], v[182:185], v[60:63]
	v_mfma_f32_16x16x32_bf16 v[56:59], v[174:177], v[182:185], v[56:59]
	v_mfma_f32_16x16x32_bf16 v[48:51], v[160:163], v[190:193], v[48:51]
	v_mfma_f32_16x16x32_bf16 v[44:47], v[174:177], v[190:193], v[44:47]
	v_mfma_f32_16x16x32_bf16 v[40:43], v[160:163], v[198:201], v[40:43]
	v_mfma_f32_16x16x32_bf16 v[36:39], v[174:177], v[198:201], v[36:39]
	v_mfma_f32_16x16x32_bf16 v[28:31], v[160:163], v[206:209], v[28:31]
	v_mfma_f32_16x16x32_bf16 v[24:27], v[174:177], v[206:209], v[24:27]
	v_mfma_f32_16x16x32_bf16 v[60:63], v[164:167], v[186:189], v[60:63]
	v_mfma_f32_16x16x32_bf16 v[56:59], v[178:181], v[186:189], v[56:59]
	v_mfma_f32_16x16x32_bf16 v[48:51], v[164:167], v[194:197], v[48:51]
	v_mfma_f32_16x16x32_bf16 v[44:47], v[178:181], v[194:197], v[44:47]
	v_mfma_f32_16x16x32_bf16 v[40:43], v[164:167], v[202:205], v[40:43]
	v_mfma_f32_16x16x32_bf16 v[36:39], v[178:181], v[202:205], v[36:39]
	v_mfma_f32_16x16x32_bf16 v[28:31], v[164:167], v[210:213], v[28:31]
	v_mfma_f32_16x16x32_bf16 v[24:27], v[178:181], v[210:213], v[24:27]
	s_barrier
	s_cmp_ge_u32 s14, s3
	s_mov_b32 s17, s14
	s_cbranch_scc1 .LBB0_183

;     __device__ __forceinline__ int nt(const Unit& u) const { return (u.pn >> 1) < 2 ? 22 : 20; }
; #define PG8_STAGE(bufoff, gbase, voff) do { _Pragma("unroll") for (int _i = 0; _i < 2; ++_i) \
;         __builtin_amdgcn_global_load_lds((const unsigned*)((const char*)(gbase) + (voff)[_i]), (LAS unsigned*)(lds + (bufoff) + ldsw + _i * 8192), 16, 0, 0); } while (0)
; #define PG8_LDA(dst, b, h) do { _Pragma("unroll") for (int m = 0; m < 4; ++m) _Pragma("unroll") for (int k = 0; k < 2; ++k) dst[m][k] = *(const LAS bf16x8*)(pA + PG8_SA(b, h) + m * 2048 + k * 1024); } while (0)
; #define PG8_LDB(dst, b, h) do { _Pragma("unroll") for (int n = 0; n < 2; ++n) _Pragma("unroll") for (int k = 0; k < 2; ++k) dst[n][k] = *(const LAS bf16x8*)(pB + (PG8_SB(b, h) - 4 * HTB) + n * 2048 + k * 1024); } while (0)
; #define PG8_MMA(ai, bj, At, Bt) do { __builtin_amdgcn_s_setprio(1); _Pragma("unroll") for (int m = 0; m < 4; ++m) _Pragma("unroll") for (int n = 0; n < 2; ++n) _Pragma("unroll") for (int k = 0; k < 2; ++k) \
;         acc[ai][bj][m][n] = __builtin_amdgcn_mfma_f32_16x16x32_bf16(Bt[n][k], At[m][k], acc[ai][bj][m][n], 0, 0, 0); __builtin_amdgcn_s_setprio(0); } while (0)
; #define PG8_WAIT_V(n) asm volatile("s_waitcnt vmcnt(" #n ")" ::: "memory")
; #define PG8_WAIT_L(n) asm volatile("s_waitcnt lgkmcnt(" #n ")" ::: "memory")
; template <class Desc, class Epi, bool ALIGN_EPI>
; __device__ __forceinline__ void gemm_phase(LAS unsigned char* lds, const Desc& D, const Epi& E, int G, int c) {
;     ...
;             const bool last = (t == nt - 2);
;             if (last && has_next) PG8_AWAIT(nxt);
;             const char* a1 = cA + (size_t)(t + 1) * kstep;
;             const char* a2 = last ? nA : cA + (size_t)(t + 2) * kstep; const char* b2 = last ? nB : cB + (size_t)(t + 2) * kstep;
;             const char* a3 = a2 + kstep; const char* b3 = b2 + kstep;
;             PG8_LDB(B0, 0, 0); PG8_LDB(B1, 0, 1); PG8_SCHED; PG8_LDA(At, 0, 0); PG8_STAGE(PG8_SA(1, 1), a1 + hstepA, voffA);
;             PG8_WAIT_V(8); PG8_WAIT_L(0); PG8_BAR; PG8_MMA(0, 0, At, B0); PG8_MMA(0, 1, At, B1); PG8_BAR; PG8_SCHED;
;             PG8_LDA(At, 0, 1); PG8_STAGE(PG8_SB(0, 0), b2, voffB); PG8_STAGE(PG8_SB(0, 1), b2 + hstepB, voffB); PG8_STAGE(PG8_SA(0, 0), a2, voffA);
;             PG8_WAIT_V(8); PG8_WAIT_L(0); PG8_BAR; PG8_MMA(1, 0, At, B0); PG8_MMA(1, 1, At, B1); PG8_BAR; PG8_SCHED;
.LBB0_603:
	ds_read_b128 v[144:147], v149
	ds_read_b128 v[152:155], v149 offset:1024
	ds_read_b128 v[156:159], v149 offset:2048
	ds_read_b128 v[160:163], v149 offset:3072
	ds_read_b128 v[164:167], v149 offset:16384
	ds_read_b128 v[168:171], v149 offset:17408
	ds_read_b128 v[172:175], v149 offset:18432
	ds_read_b128 v[176:179], v149 offset:19456
	s_add_u32 s16, s12, 0xfff80080
	s_addc_u32 s17, s13, -1
	s_cmp_eq_u32 s46, 4
	s_cselect_b32 s19, s9, s17
	s_cselect_b32 s18, s8, s16
	s_cselect_b32 s17, s11, s45
	s_cselect_b32 s16, s10, s7
	v_lshl_add_u64 v[212:213], s[12:13], 0, v[140:141]
	s_add_i32 m0, s20, 0xc000
	ds_read_b128 v[180:183], v148
	ds_read_b128 v[184:187], v148 offset:1024
	ds_read_b128 v[188:191], v148 offset:2048
	ds_read_b128 v[192:195], v148 offset:3072
	ds_read_b128 v[196:199], v148 offset:4096
	ds_read_b128 v[200:203], v148 offset:5120
	ds_read_b128 v[204:207], v148 offset:6144
	ds_read_b128 v[208:211], v148 offset:7168
	global_load_lds_dwordx4 v[212:213], off
	v_lshl_add_u64 v[212:213], s[12:13], 0, v[142:143]
	s_add_i32 m0, s20, 0xe000
	s_nop 0
	global_load_lds_dwordx4 v[212:213], off
	s_waitcnt vmcnt(8)
	s_waitcnt lgkmcnt(0)
	s_barrier
	v_mfma_f32_16x16x32_bf16 v[128:131], v[144:147], v[180:183], v[128:131]
	v_mfma_f32_16x16x32_bf16 v[124:127], v[156:159], v[180:183], v[124:127]
	v_mfma_f32_16x16x32_bf16 v[116:119], v[144:147], v[188:191], v[116:119]
	v_mfma_f32_16x16x32_bf16 v[108:111], v[156:159], v[188:191], v[108:111]
	v_mfma_f32_16x16x32_bf16 v[100:103], v[144:147], v[196:199], v[100:103]
	v_mfma_f32_16x16x32_bf16 v[92:95], v[156:159], v[196:199], v[92:95]
	v_mfma_f32_16x16x32_bf16 v[84:87], v[144:147], v[204:207], v[84:87]
	v_mfma_f32_16x16x32_bf16 v[76:79], v[156:159], v[204:207], v[76:79]
	v_mfma_f32_16x16x32_bf16 v[128:131], v[152:155], v[184:187], v[128:131]
	v_mfma_f32_16x16x32_bf16 v[124:127], v[160:163], v[184:187], v[124:127]
	v_mfma_f32_16x16x32_bf16 v[116:119], v[152:155], v[192:195], v[116:119]
	v_mfma_f32_16x16x32_bf16 v[108:111], v[160:163], v[192:195], v[108:111]
	v_mfma_f32_16x16x32_bf16 v[100:103], v[152:155], v[200:203], v[100:103]
	v_mfma_f32_16x16x32_bf16 v[92:95], v[160:163], v[200:203], v[92:95]
	v_mfma_f32_16x16x32_bf16 v[84:87], v[152:155], v[208:211], v[84:87]
	v_mfma_f32_16x16x32_bf16 v[76:79], v[160:163], v[208:211], v[76:79]
	v_mfma_f32_16x16x32_bf16 v[120:123], v[164:167], v[180:183], v[120:123]
	v_mfma_f32_16x16x32_bf16 v[112:115], v[172:175], v[180:183], v[112:115]
	v_mfma_f32_16x16x32_bf16 v[104:107], v[164:167], v[188:191], v[104:107]
	v_mfma_f32_16x16x32_bf16 v[96:99], v[172:175], v[188:191], v[96:99]
	v_mfma_f32_16x16x32_bf16 v[88:91], v[164:167], v[196:199], v[88:91]
	v_mfma_f32_16x16x32_bf16 v[80:83], v[172:175], v[196:199], v[80:83]
	v_mfma_f32_16x16x32_bf16 v[72:75], v[164:167], v[204:207], v[72:75]
	v_mfma_f32_16x16x32_bf16 v[68:71], v[172:175], v[204:207], v[68:71]
	v_mfma_f32_16x16x32_bf16 v[120:123], v[168:171], v[184:187], v[120:123]
	v_mfma_f32_16x16x32_bf16 v[112:115], v[176:179], v[184:187], v[112:115]
	v_mfma_f32_16x16x32_bf16 v[104:107], v[168:171], v[192:195], v[104:107]
	v_mfma_f32_16x16x32_bf16 v[96:99], v[176:179], v[192:195], v[96:99]
	v_mfma_f32_16x16x32_bf16 v[88:91], v[168:171], v[200:203], v[88:91]
	v_mfma_f32_16x16x32_bf16 v[80:83], v[176:179], v[200:203], v[80:83]
	v_mfma_f32_16x16x32_bf16 v[72:75], v[168:171], v[208:211], v[72:75]
	v_mfma_f32_16x16x32_bf16 v[68:71], v[176:179], v[208:211], v[68:71]
	s_barrier
	s_mov_b32 m0, s21
	v_lshl_add_u64 v[212:213], s[16:17], 0, v[136:137]
	s_add_u32 s48, s16, 0x20000
	ds_read_b128 v[180:183], v148 offset:16384
	ds_read_b128 v[184:187], v148 offset:17408
	ds_read_b128 v[188:191], v148 offset:18432
	ds_read_b128 v[192:195], v148 offset:19456
	ds_read_b128 v[196:199], v148 offset:20480
	ds_read_b128 v[200:203], v148 offset:21504
	ds_read_b128 v[204:207], v148 offset:22528
	ds_read_b128 v[208:211], v148 offset:23552
	global_load_lds_dwordx4 v[212:213], off
	v_lshl_add_u64 v[214:215], s[16:17], 0, v[132:133]
	s_mov_b32 m0, s23
	s_addc_u32 s49, s17, 0
	global_load_lds_dwordx4 v[214:215], off
	v_lshl_add_u64 v[216:217], s[48:49], 0, v[136:137]
	s_mov_b32 m0, s24
	v_lshl_add_u64 v[218:219], s[18:19], 0, v[134:135]
	global_load_lds_dwordx4 v[216:217], off
	v_lshl_add_u64 v[216:217], s[48:49], 0, v[132:133]
	s_mov_b32 m0, s25
	s_nop 0
	global_load_lds_dwordx4 v[216:217], off
	v_lshl_add_u64 v[216:217], s[18:19], 0, v[138:139]
	s_mov_b32 m0, s20
	s_nop 0
	global_load_lds_dwordx4 v[216:217], off
	s_mov_b32 m0, s26
	s_nop 0
	global_load_lds_dwordx4 v[218:219], off
	s_waitcnt vmcnt(8)
	s_waitcnt lgkmcnt(0)
	s_barrier
; #define PG8_STAGE(bufoff, gbase, voff) do { _Pragma("unroll") for (int _i = 0; _i < 2; ++_i) \
;         __builtin_amdgcn_global_load_lds((const unsigned*)((const char*)(gbase) + (voff)[_i]), (LAS unsigned*)(lds + (bufoff) + ldsw + _i * 8192), 16, 0, 0); } while (0)
; #define PG8_LDA(dst, b, h) do { _Pragma("unroll") for (int m = 0; m < 4; ++m) _Pragma("unroll") for (int k = 0; k < 2; ++k) dst[m][k] = *(const LAS bf16x8*)(pA + PG8_SA(b, h) + m * 2048 + k * 1024); } while (0)
; #define PG8_LDB(dst, b, h) do { _Pragma("unroll") for (int n = 0; n < 2; ++n) _Pragma("unroll") for (int k = 0; k < 2; ++k) dst[n][k] = *(const LAS bf16x8*)(pB + (PG8_SB(b, h) - 4 * HTB) + n * 2048 + k * 1024); } while (0)
; #define PG8_MMA(ai, bj, At, Bt) do { __builtin_amdgcn_s_setprio(1); _Pragma("unroll") for (int m = 0; m < 4; ++m) _Pragma("unroll") for (int n = 0; n < 2; ++n) _Pragma("unroll") for (int k = 0; k < 2; ++k) \
;         acc[ai][bj][m][n] = __builtin_amdgcn_mfma_f32_16x16x32_bf16(Bt[n][k], At[m][k], acc[ai][bj][m][n], 0, 0, 0); __builtin_amdgcn_s_setprio(0); } while (0)
; #define PG8_WAIT_V(n) asm volatile("s_waitcnt vmcnt(" #n ")" ::: "memory")
; #define PG8_WAIT_L(n) asm volatile("s_waitcnt lgkmcnt(" #n ")" ::: "memory")
; #define PG8_BAR __builtin_amdgcn_s_barrier()
; #define PG8_SCHED __builtin_amdgcn_sched_barrier(0)
; template <class Desc, class Epi, bool ALIGN_EPI>
; __device__ __forceinline__ void gemm_phase(LAS unsigned char* lds, const Desc& D, const Epi& E, int G, int c) {
;     ...
;             PG8_WAIT_V(8); PG8_WAIT_L(0); PG8_BAR; PG8_MMA(1, 0, At, B0); PG8_MMA(1, 1, At, B1); PG8_BAR; PG8_SCHED;
;             PG8_LDB(B0, 1, 0); PG8_LDB(B1, 1, 1); PG8_SCHED; PG8_LDA(At, 1, 0); PG8_STAGE(PG8_SA(0, 1), a2 + hstepA, voffA);
;             PG8_WAIT_V(8); PG8_WAIT_L(0); PG8_BAR; PG8_MMA(0, 0, At, B0); PG8_MMA(0, 1, At, B1); PG8_BAR; PG8_SCHED;
	v_mfma_f32_16x16x32_bf16 v[64:67], v[144:147], v[180:183], v[64:67]
	v_mfma_f32_16x16x32_bf16 v[60:63], v[156:159], v[180:183], v[60:63]
	v_mfma_f32_16x16x32_bf16 v[52:55], v[144:147], v[188:191], v[52:55]
	v_mfma_f32_16x16x32_bf16 v[44:47], v[156:159], v[188:191], v[44:47]
	v_mfma_f32_16x16x32_bf16 v[36:39], v[144:147], v[196:199], v[36:39]
	v_mfma_f32_16x16x32_bf16 v[28:31], v[156:159], v[196:199], v[28:31]
	v_mfma_f32_16x16x32_bf16 v[20:23], v[144:147], v[204:207], v[20:23]
	v_mfma_f32_16x16x32_bf16 v[12:15], v[156:159], v[204:207], v[12:15]
	v_mfma_f32_16x16x32_bf16 v[64:67], v[152:155], v[184:187], v[64:67]
	v_mfma_f32_16x16x32_bf16 v[60:63], v[160:163], v[184:187], v[60:63]
	v_mfma_f32_16x16x32_bf16 v[52:55], v[152:155], v[192:195], v[52:55]
	v_mfma_f32_16x16x32_bf16 v[44:47], v[160:163], v[192:195], v[44:47]
	v_mfma_f32_16x16x32_bf16 v[36:39], v[152:155], v[200:203], v[36:39]
	v_mfma_f32_16x16x32_bf16 v[28:31], v[160:163], v[200:203], v[28:31]
	v_mfma_f32_16x16x32_bf16 v[20:23], v[152:155], v[208:211], v[20:23]
	v_mfma_f32_16x16x32_bf16 v[12:15], v[160:163], v[208:211], v[12:15]
	v_mfma_f32_16x16x32_bf16 v[56:59], v[164:167], v[180:183], v[56:59]
	v_mfma_f32_16x16x32_bf16 v[48:51], v[172:175], v[180:183], v[48:51]
	v_mfma_f32_16x16x32_bf16 v[40:43], v[164:167], v[188:191], v[40:43]
	v_mfma_f32_16x16x32_bf16 v[32:35], v[172:175], v[188:191], v[32:35]
	v_mfma_f32_16x16x32_bf16 v[24:27], v[164:167], v[196:199], v[24:27]
	v_mfma_f32_16x16x32_bf16 v[16:19], v[172:175], v[196:199], v[16:19]
	v_mfma_f32_16x16x32_bf16 v[8:11], v[164:167], v[204:207], v[8:11]
	v_mfma_f32_16x16x32_bf16 v[4:7], v[172:175], v[204:207], v[4:7]
	v_mfma_f32_16x16x32_bf16 v[56:59], v[168:171], v[184:187], v[56:59]
	v_mfma_f32_16x16x32_bf16 v[48:51], v[176:179], v[184:187], v[48:51]
	v_mfma_f32_16x16x32_bf16 v[40:43], v[168:171], v[192:195], v[40:43]
	v_mfma_f32_16x16x32_bf16 v[32:35], v[176:179], v[192:195], v[32:35]
	v_mfma_f32_16x16x32_bf16 v[24:27], v[168:171], v[200:203], v[24:27]
	v_mfma_f32_16x16x32_bf16 v[16:19], v[176:179], v[200:203], v[16:19]
	v_mfma_f32_16x16x32_bf16 v[8:11], v[168:171], v[208:211], v[8:11]
	v_mfma_f32_16x16x32_bf16 v[4:7], v[176:179], v[208:211], v[4:7]
	s_barrier
	ds_read_b128 v[144:147], v149 offset:32768
	ds_read_b128 v[152:155], v149 offset:33792
	ds_read_b128 v[156:159], v149 offset:34816
	ds_read_b128 v[160:163], v149 offset:35840
	ds_read_b128 v[164:167], v149 offset:49152
	ds_read_b128 v[168:171], v149 offset:50176
	ds_read_b128 v[172:175], v149 offset:51200
	ds_read_b128 v[176:179], v149 offset:52224
	s_add_u32 s18, s18, 0x80000
	s_addc_u32 s19, s19, 0
	s_mov_b32 m0, s27
	v_lshl_add_u64 v[220:221], s[18:19], 0, v[138:139]
	ds_read_b128 v[180:183], v148 offset:32768
	ds_read_b128 v[184:187], v148 offset:33792
	ds_read_b128 v[188:191], v148 offset:34816
	ds_read_b128 v[192:195], v148 offset:35840
	ds_read_b128 v[196:199], v148 offset:36864
	ds_read_b128 v[200:203], v148 offset:37888
	ds_read_b128 v[204:207], v148 offset:38912
	ds_read_b128 v[208:211], v148 offset:39936
	global_load_lds_dwordx4 v[220:221], off
	v_lshl_add_u64 v[220:221], s[18:19], 0, v[134:135]
	s_mov_b32 m0, s30
	s_nop 0
	global_load_lds_dwordx4 v[220:221], off
	s_waitcnt vmcnt(8)
	s_waitcnt lgkmcnt(0)
	s_barrier
	v_mfma_f32_16x16x32_bf16 v[128:131], v[144:147], v[180:183], v[128:131]
	v_mfma_f32_16x16x32_bf16 v[124:127], v[156:159], v[180:183], v[124:127]
	v_mfma_f32_16x16x32_bf16 v[116:119], v[144:147], v[188:191], v[116:119]
	v_mfma_f32_16x16x32_bf16 v[108:111], v[156:159], v[188:191], v[108:111]
	v_mfma_f32_16x16x32_bf16 v[100:103], v[144:147], v[196:199], v[100:103]
	v_mfma_f32_16x16x32_bf16 v[92:95], v[156:159], v[196:199], v[92:95]
	v_mfma_f32_16x16x32_bf16 v[84:87], v[144:147], v[204:207], v[84:87]
	v_mfma_f32_16x16x32_bf16 v[76:79], v[156:159], v[204:207], v[76:79]
	v_mfma_f32_16x16x32_bf16 v[128:131], v[152:155], v[184:187], v[128:131]
	v_mfma_f32_16x16x32_bf16 v[124:127], v[160:163], v[184:187], v[124:127]
	v_mfma_f32_16x16x32_bf16 v[116:119], v[152:155], v[192:195], v[116:119]
	v_mfma_f32_16x16x32_bf16 v[108:111], v[160:163], v[192:195], v[108:111]
	v_mfma_f32_16x16x32_bf16 v[100:103], v[152:155], v[200:203], v[100:103]
	v_mfma_f32_16x16x32_bf16 v[92:95], v[160:163], v[200:203], v[92:95]
	v_mfma_f32_16x16x32_bf16 v[84:87], v[152:155], v[208:211], v[84:87]
	v_mfma_f32_16x16x32_bf16 v[76:79], v[160:163], v[208:211], v[76:79]
	v_mfma_f32_16x16x32_bf16 v[120:123], v[164:167], v[180:183], v[120:123]
	v_mfma_f32_16x16x32_bf16 v[112:115], v[172:175], v[180:183], v[112:115]
	v_mfma_f32_16x16x32_bf16 v[104:107], v[164:167], v[188:191], v[104:107]
	v_mfma_f32_16x16x32_bf16 v[96:99], v[172:175], v[188:191], v[96:99]
	v_mfma_f32_16x16x32_bf16 v[88:91], v[164:167], v[196:199], v[88:91]
	v_mfma_f32_16x16x32_bf16 v[80:83], v[172:175], v[196:199], v[80:83]
	v_mfma_f32_16x16x32_bf16 v[72:75], v[164:167], v[204:207], v[72:75]
	v_mfma_f32_16x16x32_bf16 v[68:71], v[172:175], v[204:207], v[68:71]
	v_mfma_f32_16x16x32_bf16 v[120:123], v[168:171], v[184:187], v[120:123]
	v_mfma_f32_16x16x32_bf16 v[112:115], v[176:179], v[184:187], v[112:115]
	v_mfma_f32_16x16x32_bf16 v[104:107], v[168:171], v[192:195], v[104:107]
	v_mfma_f32_16x16x32_bf16 v[96:99], v[176:179], v[192:195], v[96:99]
	v_mfma_f32_16x16x32_bf16 v[88:91], v[168:171], v[200:203], v[88:91]
	v_mfma_f32_16x16x32_bf16 v[80:83], v[176:179], v[200:203], v[80:83]
	v_mfma_f32_16x16x32_bf16 v[72:75], v[168:171], v[208:211], v[72:75]
	v_mfma_f32_16x16x32_bf16 v[68:71], v[176:179], v[208:211], v[68:71]
	s_barrier
; #define PG8_STAGE(bufoff, gbase, voff) do { _Pragma("unroll") for (int _i = 0; _i < 2; ++_i) \
;         __builtin_amdgcn_global_load_lds((const unsigned*)((const char*)(gbase) + (voff)[_i]), (LAS unsigned*)(lds + (bufoff) + ldsw + _i * 8192), 16, 0, 0); } while (0)
; #define PG8_LDA(dst, b, h) do { _Pragma("unroll") for (int m = 0; m < 4; ++m) _Pragma("unroll") for (int k = 0; k < 2; ++k) dst[m][k] = *(const LAS bf16x8*)(pA + PG8_SA(b, h) + m * 2048 + k * 1024); } while (0)
; #define PG8_MMA(ai, bj, At, Bt) do { __builtin_amdgcn_s_setprio(1); _Pragma("unroll") for (int m = 0; m < 4; ++m) _Pragma("unroll") for (int n = 0; n < 2; ++n) _Pragma("unroll") for (int k = 0; k < 2; ++k) \
;         acc[ai][bj][m][n] = __builtin_amdgcn_mfma_f32_16x16x32_bf16(Bt[n][k], At[m][k], acc[ai][bj][m][n], 0, 0, 0); __builtin_amdgcn_s_setprio(0); } while (0)
; #define PG8_WAIT_V(n) asm volatile("s_waitcnt vmcnt(" #n ")" ::: "memory")
; #define PG8_WAIT_L(n) asm volatile("s_waitcnt lgkmcnt(" #n ")" ::: "memory")
; #define PG8_BAR __builtin_amdgcn_s_barrier()
; #define PG8_SCHED __builtin_amdgcn_sched_barrier(0)
; template <class Desc, class Epi, bool ALIGN_EPI>
; __device__ __forceinline__ void gemm_phase(LAS unsigned char* lds, const Desc& D, const Epi& E, int G, int c) {
;     ...
;             PG8_LDA(At, 1, 1); PG8_STAGE(PG8_SB(1, 0), b3, voffB); PG8_STAGE(PG8_SB(1, 1), b3 + hstepB, voffB); PG8_STAGE(PG8_SA(1, 0), a3, voffA);
;             PG8_WAIT_V(8); PG8_WAIT_L(0); PG8_BAR; PG8_MMA(1, 0, At, B0); PG8_MMA(1, 1, At, B1); PG8_BAR; PG8_SCHED;
;         }
	s_mov_b32 m0, s31
	v_lshl_add_u64 v[212:213], v[212:213], 0, s[76:77]
	s_add_u32 s16, s16, 0x20080
	ds_read_b128 v[180:183], v148 offset:49152
	ds_read_b128 v[184:187], v148 offset:50176
	ds_read_b128 v[188:191], v148 offset:51200
	ds_read_b128 v[192:195], v148 offset:52224
	ds_read_b128 v[196:199], v148 offset:53248
	ds_read_b128 v[200:203], v148 offset:54272
	ds_read_b128 v[204:207], v148 offset:55296
	ds_read_b128 v[208:211], v148 offset:56320
	global_load_lds_dwordx4 v[212:213], off
	v_lshl_add_u64 v[212:213], v[214:215], 0, s[76:77]
	s_mov_b32 m0, s33
	s_addc_u32 s17, s17, 0
	global_load_lds_dwordx4 v[212:213], off
	v_lshl_add_u64 v[212:213], s[16:17], 0, v[136:137]
	s_mov_b32 m0, s38
	s_nop 0
	global_load_lds_dwordx4 v[212:213], off
	v_lshl_add_u64 v[212:213], s[16:17], 0, v[132:133]
	s_mov_b32 m0, s39
	s_nop 0
	global_load_lds_dwordx4 v[212:213], off
	v_lshl_add_u64 v[212:213], v[216:217], 0, s[76:77]
	s_mov_b32 m0, s34
	s_nop 0
	global_load_lds_dwordx4 v[212:213], off
	v_lshl_add_u64 v[212:213], v[218:219], 0, s[76:77]
	s_mov_b32 m0, s35
	s_nop 0
	global_load_lds_dwordx4 v[212:213], off
	s_waitcnt vmcnt(8)
	s_waitcnt lgkmcnt(0)
	s_barrier
	v_mfma_f32_16x16x32_bf16 v[64:67], v[144:147], v[180:183], v[64:67]
	v_mfma_f32_16x16x32_bf16 v[60:63], v[156:159], v[180:183], v[60:63]
	v_mfma_f32_16x16x32_bf16 v[52:55], v[144:147], v[188:191], v[52:55]
	v_mfma_f32_16x16x32_bf16 v[44:47], v[156:159], v[188:191], v[44:47]
	v_mfma_f32_16x16x32_bf16 v[36:39], v[144:147], v[196:199], v[36:39]
	v_mfma_f32_16x16x32_bf16 v[28:31], v[156:159], v[196:199], v[28:31]
	v_mfma_f32_16x16x32_bf16 v[20:23], v[144:147], v[204:207], v[20:23]
	v_mfma_f32_16x16x32_bf16 v[12:15], v[156:159], v[204:207], v[12:15]
	v_mfma_f32_16x16x32_bf16 v[64:67], v[152:155], v[184:187], v[64:67]
	v_mfma_f32_16x16x32_bf16 v[60:63], v[160:163], v[184:187], v[60:63]
	v_mfma_f32_16x16x32_bf16 v[52:55], v[152:155], v[192:195], v[52:55]
	v_mfma_f32_16x16x32_bf16 v[44:47], v[160:163], v[192:195], v[44:47]
	v_mfma_f32_16x16x32_bf16 v[36:39], v[152:155], v[200:203], v[36:39]
	v_mfma_f32_16x16x32_bf16 v[28:31], v[160:163], v[200:203], v[28:31]
	v_mfma_f32_16x16x32_bf16 v[20:23], v[152:155], v[208:211], v[20:23]
	v_mfma_f32_16x16x32_bf16 v[12:15], v[160:163], v[208:211], v[12:15]
	v_mfma_f32_16x16x32_bf16 v[56:59], v[164:167], v[180:183], v[56:59]
	v_mfma_f32_16x16x32_bf16 v[48:51], v[172:175], v[180:183], v[48:51]
	v_mfma_f32_16x16x32_bf16 v[40:43], v[164:167], v[188:191], v[40:43]
	v_mfma_f32_16x16x32_bf16 v[32:35], v[172:175], v[188:191], v[32:35]
	v_mfma_f32_16x16x32_bf16 v[24:27], v[164:167], v[196:199], v[24:27]
	v_mfma_f32_16x16x32_bf16 v[16:19], v[172:175], v[196:199], v[16:19]
	v_mfma_f32_16x16x32_bf16 v[8:11], v[164:167], v[204:207], v[8:11]
	v_mfma_f32_16x16x32_bf16 v[4:7], v[172:175], v[204:207], v[4:7]
	v_mfma_f32_16x16x32_bf16 v[56:59], v[168:171], v[184:187], v[56:59]
	v_mfma_f32_16x16x32_bf16 v[48:51], v[176:179], v[184:187], v[48:51]
	v_mfma_f32_16x16x32_bf16 v[40:43], v[168:171], v[192:195], v[40:43]
	v_mfma_f32_16x16x32_bf16 v[32:35], v[176:179], v[192:195], v[32:35]
	v_mfma_f32_16x16x32_bf16 v[24:27], v[168:171], v[200:203], v[24:27]
	v_mfma_f32_16x16x32_bf16 v[16:19], v[176:179], v[200:203], v[16:19]
	v_mfma_f32_16x16x32_bf16 v[8:11], v[168:171], v[208:211], v[8:11]
	v_mfma_f32_16x16x32_bf16 v[4:7], v[176:179], v[208:211], v[4:7]
	s_barrier
	s_add_i32 s46, s46, 2
	s_add_u32 s12, s12, 0x100
	s_addc_u32 s13, s13, 0
	s_add_u32 s7, s7, 0x100
	s_addc_u32 s45, s45, 0
	s_cmp_gt_u32 s46, 5
	s_cbranch_scc0 .LBB0_603
	v_readlane_b32 s46, v255, 36
	s_and_b64 vcc, exec, s[4:5]
	v_readlane_b32 s47, v255, 37
	s_cbranch_vccz .LBB0_606
	s_barrier

;     __device__ __forceinline__ int nt(const Unit& u) const { return (u.pn >> 1) < 2 ? 22 : 20; }
; #define PG8_STAGE(bufoff, gbase, voff) do { _Pragma("unroll") for (int _i = 0; _i < 2; ++_i) \
;         __builtin_amdgcn_global_load_lds((const unsigned*)((const char*)(gbase) + (voff)[_i]), (LAS unsigned*)(lds + (bufoff) + ldsw + _i * 8192), 16, 0, 0); } while (0)
; #define PG8_LDA(dst, b, h) do { _Pragma("unroll") for (int m = 0; m < 4; ++m) _Pragma("unroll") for (int k = 0; k < 2; ++k) dst[m][k] = *(const LAS bf16x8*)(pA + PG8_SA(b, h) + m * 2048 + k * 1024); } while (0)
; #define PG8_LDB(dst, b, h) do { _Pragma("unroll") for (int n = 0; n < 2; ++n) _Pragma("unroll") for (int k = 0; k < 2; ++k) dst[n][k] = *(const LAS bf16x8*)(pB + (PG8_SB(b, h) - 4 * HTB) + n * 2048 + k * 1024); } while (0)
; #define PG8_MMA(ai, bj, At, Bt) do { __builtin_amdgcn_s_setprio(1); _Pragma("unroll") for (int m = 0; m < 4; ++m) _Pragma("unroll") for (int n = 0; n < 2; ++n) _Pragma("unroll") for (int k = 0; k < 2; ++k) \
;         acc[ai][bj][m][n] = __builtin_amdgcn_mfma_f32_16x16x32_bf16(Bt[n][k], At[m][k], acc[ai][bj][m][n], 0, 0, 0); __builtin_amdgcn_s_setprio(0); } while (0)
; #define PG8_WAIT_V(n) asm volatile("s_waitcnt vmcnt(" #n ")" ::: "memory")
; #define PG8_WAIT_L(n) asm volatile("s_waitcnt lgkmcnt(" #n ")" ::: "memory")
; template <class Desc, class Epi, bool ALIGN_EPI>
; __device__ __forceinline__ void gemm_phase(LAS unsigned char* lds, const Desc& D, const Epi& E, int G, int c) {
;     ...
;             const bool last = (t == nt - 2);
;             if (last && has_next) PG8_AWAIT(nxt);
;             const char* a1 = cA + (size_t)(t + 1) * kstep;
;             const char* a2 = last ? nA : cA + (size_t)(t + 2) * kstep; const char* b2 = last ? nB : cB + (size_t)(t + 2) * kstep;
;             const char* a3 = a2 + kstep; const char* b3 = b2 + kstep;
;             PG8_LDB(B0, 0, 0); PG8_LDB(B1, 0, 1); PG8_SCHED; PG8_LDA(At, 0, 0); PG8_STAGE(PG8_SA(1, 1), a1 + hstepA, voffA);
;             PG8_WAIT_V(8); PG8_WAIT_L(0); PG8_BAR; PG8_MMA(0, 0, At, B0); PG8_MMA(0, 1, At, B1); PG8_BAR; PG8_SCHED;
;             PG8_LDA(At, 0, 1); PG8_STAGE(PG8_SB(0, 0), b2, voffB); PG8_STAGE(PG8_SB(0, 1), b2 + hstepB, voffB); PG8_STAGE(PG8_SA(0, 0), a2, voffA);
;             PG8_WAIT_V(8); PG8_WAIT_L(0); PG8_BAR; PG8_MMA(1, 0, At, B0); PG8_MMA(1, 1, At, B1); PG8_BAR; PG8_SCHED;
.LBB0_1164:
	s_waitcnt lgkmcnt(0)
	ds_read_b128 v[132:135], v229
	ds_read_b128 v[136:139], v229 offset:1024
	ds_read_b128 v[140:143], v229 offset:2048
	ds_read_b128 v[144:147], v229 offset:3072
	ds_read_b128 v[148:151], v229 offset:16384
	ds_read_b128 v[152:155], v229 offset:17408
	ds_read_b128 v[156:159], v229 offset:18432
	ds_read_b128 v[160:163], v229 offset:19456
	s_add_i32 s20, s14, 2
	s_add_u32 s16, s12, 0xfff00080
	s_addc_u32 s17, s13, -1
	s_cmp_eq_u32 s1, s14
	s_cselect_b32 s19, s39, s17
	s_cselect_b32 s18, s38, s16
	s_cselect_b32 s17, s41, s11
	s_cselect_b32 s16, s40, s3
	v_lshl_add_u64 v[208:209], s[12:13], 0, v[204:205]
	s_add_i32 m0, s35, 0xc000
	ds_read_b128 v[164:167], v228
	ds_read_b128 v[168:171], v228 offset:1024
	ds_read_b128 v[172:175], v228 offset:2048
	ds_read_b128 v[176:179], v228 offset:3072
	ds_read_b128 v[180:183], v228 offset:4096
	ds_read_b128 v[184:187], v228 offset:5120
	ds_read_b128 v[188:191], v228 offset:6144
	ds_read_b128 v[192:195], v228 offset:7168
	global_load_lds_dwordx4 v[208:209], off
	v_lshl_add_u64 v[208:209], s[12:13], 0, v[206:207]
	s_add_i32 m0, s35, 0xe000
	s_nop 0
	global_load_lds_dwordx4 v[208:209], off
	s_waitcnt vmcnt(8)
	s_waitcnt lgkmcnt(0)
	s_barrier
	v_mfma_f32_16x16x32_bf16 v[128:131], v[132:135], v[164:167], v[128:131]
	v_mfma_f32_16x16x32_bf16 v[124:127], v[140:143], v[164:167], v[124:127]
	v_mfma_f32_16x16x32_bf16 v[120:123], v[132:135], v[172:175], v[120:123]
	v_mfma_f32_16x16x32_bf16 v[116:119], v[140:143], v[172:175], v[116:119]
	v_mfma_f32_16x16x32_bf16 v[112:115], v[132:135], v[180:183], v[112:115]
	v_mfma_f32_16x16x32_bf16 v[108:111], v[140:143], v[180:183], v[108:111]
	v_mfma_f32_16x16x32_bf16 v[104:107], v[132:135], v[188:191], v[104:107]
	v_mfma_f32_16x16x32_bf16 v[100:103], v[140:143], v[188:191], v[100:103]
	v_mfma_f32_16x16x32_bf16 v[128:131], v[136:139], v[168:171], v[128:131]
	v_mfma_f32_16x16x32_bf16 v[124:127], v[144:147], v[168:171], v[124:127]
	v_mfma_f32_16x16x32_bf16 v[120:123], v[136:139], v[176:179], v[120:123]
	v_mfma_f32_16x16x32_bf16 v[116:119], v[144:147], v[176:179], v[116:119]
	v_mfma_f32_16x16x32_bf16 v[112:115], v[136:139], v[184:187], v[112:115]
	v_mfma_f32_16x16x32_bf16 v[108:111], v[144:147], v[184:187], v[108:111]
	v_mfma_f32_16x16x32_bf16 v[104:107], v[136:139], v[192:195], v[104:107]
	v_mfma_f32_16x16x32_bf16 v[100:103], v[144:147], v[192:195], v[100:103]
	v_mfma_f32_16x16x32_bf16 v[96:99], v[148:151], v[164:167], v[96:99]
	v_mfma_f32_16x16x32_bf16 v[92:95], v[156:159], v[164:167], v[92:95]
	v_mfma_f32_16x16x32_bf16 v[88:91], v[148:151], v[172:175], v[88:91]
	v_mfma_f32_16x16x32_bf16 v[80:83], v[156:159], v[172:175], v[80:83]
	v_mfma_f32_16x16x32_bf16 v[64:67], v[148:151], v[180:183], v[64:67]
	v_mfma_f32_16x16x32_bf16 v[52:55], v[156:159], v[180:183], v[52:55]
	v_mfma_f32_16x16x32_bf16 v[32:35], v[148:151], v[188:191], v[32:35]
	v_mfma_f32_16x16x32_bf16 v[20:23], v[156:159], v[188:191], v[20:23]
	v_mfma_f32_16x16x32_bf16 v[96:99], v[152:155], v[168:171], v[96:99]
	v_mfma_f32_16x16x32_bf16 v[92:95], v[160:163], v[168:171], v[92:95]
	v_mfma_f32_16x16x32_bf16 v[88:91], v[152:155], v[176:179], v[88:91]
	v_mfma_f32_16x16x32_bf16 v[80:83], v[160:163], v[176:179], v[80:83]
	v_mfma_f32_16x16x32_bf16 v[64:67], v[152:155], v[184:187], v[64:67]
	v_mfma_f32_16x16x32_bf16 v[52:55], v[160:163], v[184:187], v[52:55]
	v_mfma_f32_16x16x32_bf16 v[32:35], v[152:155], v[192:195], v[32:35]
	v_mfma_f32_16x16x32_bf16 v[20:23], v[160:163], v[192:195], v[20:23]
	s_barrier
	s_mov_b32 m0, s44
	v_lshl_add_u64 v[208:209], s[16:17], 0, v[198:199]
	s_add_u32 s62, s16, 0x100000
	ds_read_b128 v[164:167], v228 offset:16384
	ds_read_b128 v[168:171], v228 offset:17408
	ds_read_b128 v[172:175], v228 offset:18432
	ds_read_b128 v[176:179], v228 offset:19456
	ds_read_b128 v[180:183], v228 offset:20480
	ds_read_b128 v[184:187], v228 offset:21504
	ds_read_b128 v[188:191], v228 offset:22528
	ds_read_b128 v[192:195], v228 offset:23552
	global_load_lds_dwordx4 v[208:209], off
	v_lshl_add_u64 v[210:211], s[16:17], 0, v[202:203]
	s_mov_b32 m0, s45
	s_addc_u32 s63, s17, 0
	global_load_lds_dwordx4 v[210:211], off
	v_lshl_add_u64 v[212:213], s[62:63], 0, v[198:199]
	s_mov_b32 m0, s46
	v_lshl_add_u64 v[214:215], s[18:19], 0, v[200:201]
	global_load_lds_dwordx4 v[212:213], off
	v_lshl_add_u64 v[212:213], s[62:63], 0, v[202:203]
	s_mov_b32 m0, s47
	s_nop 0
	global_load_lds_dwordx4 v[212:213], off
	v_lshl_add_u64 v[212:213], s[18:19], 0, v[196:197]
	s_mov_b32 m0, s35
	s_nop 0
	global_load_lds_dwordx4 v[212:213], off
	s_mov_b32 m0, s48
	s_nop 0
	global_load_lds_dwordx4 v[214:215], off
	s_waitcnt vmcnt(8)
	s_waitcnt lgkmcnt(0)
	s_barrier
; #define PG8_STAGE(bufoff, gbase, voff) do { _Pragma("unroll") for (int _i = 0; _i < 2; ++_i) \
;         __builtin_amdgcn_global_load_lds((const unsigned*)((const char*)(gbase) + (voff)[_i]), (LAS unsigned*)(lds + (bufoff) + ldsw + _i * 8192), 16, 0, 0); } while (0)
; #define PG8_LDA(dst, b, h) do { _Pragma("unroll") for (int m = 0; m < 4; ++m) _Pragma("unroll") for (int k = 0; k < 2; ++k) dst[m][k] = *(const LAS bf16x8*)(pA + PG8_SA(b, h) + m * 2048 + k * 1024); } while (0)
; #define PG8_LDB(dst, b, h) do { _Pragma("unroll") for (int n = 0; n < 2; ++n) _Pragma("unroll") for (int k = 0; k < 2; ++k) dst[n][k] = *(const LAS bf16x8*)(pB + (PG8_SB(b, h) - 4 * HTB) + n * 2048 + k * 1024); } while (0)
; #define PG8_MMA(ai, bj, At, Bt) do { __builtin_amdgcn_s_setprio(1); _Pragma("unroll") for (int m = 0; m < 4; ++m) _Pragma("unroll") for (int n = 0; n < 2; ++n) _Pragma("unroll") for (int k = 0; k < 2; ++k) \
;         acc[ai][bj][m][n] = __builtin_amdgcn_mfma_f32_16x16x32_bf16(Bt[n][k], At[m][k], acc[ai][bj][m][n], 0, 0, 0); __builtin_amdgcn_s_setprio(0); } while (0)
; #define PG8_WAIT_V(n) asm volatile("s_waitcnt vmcnt(" #n ")" ::: "memory")
; #define PG8_WAIT_L(n) asm volatile("s_waitcnt lgkmcnt(" #n ")" ::: "memory")
; #define PG8_BAR __builtin_amdgcn_s_barrier()
; #define PG8_SCHED __builtin_amdgcn_sched_barrier(0)
; template <class Desc, class Epi, bool ALIGN_EPI>
; __device__ __forceinline__ void gemm_phase(LAS unsigned char* lds, const Desc& D, const Epi& E, int G, int c) {
;     ...
;             PG8_WAIT_V(8); PG8_WAIT_L(0); PG8_BAR; PG8_MMA(1, 0, At, B0); PG8_MMA(1, 1, At, B1); PG8_BAR; PG8_SCHED;
;             PG8_LDB(B0, 1, 0); PG8_LDB(B1, 1, 1); PG8_SCHED; PG8_LDA(At, 1, 0); PG8_STAGE(PG8_SA(0, 1), a2 + hstepA, voffA);
;             PG8_WAIT_V(8); PG8_WAIT_L(0); PG8_BAR; PG8_MMA(0, 0, At, B0); PG8_MMA(0, 1, At, B1); PG8_BAR; PG8_SCHED;
	v_mfma_f32_16x16x32_bf16 v[84:87], v[132:135], v[164:167], v[84:87]
	v_mfma_f32_16x16x32_bf16 v[76:79], v[140:143], v[164:167], v[76:79]
	v_mfma_f32_16x16x32_bf16 v[72:75], v[132:135], v[172:175], v[72:75]
	v_mfma_f32_16x16x32_bf16 v[68:71], v[140:143], v[172:175], v[68:71]
	v_mfma_f32_16x16x32_bf16 v[60:63], v[132:135], v[180:183], v[60:63]
	v_mfma_f32_16x16x32_bf16 v[56:59], v[140:143], v[180:183], v[56:59]
	v_mfma_f32_16x16x32_bf16 v[48:51], v[132:135], v[188:191], v[48:51]
	v_mfma_f32_16x16x32_bf16 v[44:47], v[140:143], v[188:191], v[44:47]
	v_mfma_f32_16x16x32_bf16 v[84:87], v[136:139], v[168:171], v[84:87]
	v_mfma_f32_16x16x32_bf16 v[76:79], v[144:147], v[168:171], v[76:79]
	v_mfma_f32_16x16x32_bf16 v[72:75], v[136:139], v[176:179], v[72:75]
	v_mfma_f32_16x16x32_bf16 v[68:71], v[144:147], v[176:179], v[68:71]
	v_mfma_f32_16x16x32_bf16 v[60:63], v[136:139], v[184:187], v[60:63]
	v_mfma_f32_16x16x32_bf16 v[56:59], v[144:147], v[184:187], v[56:59]
	v_mfma_f32_16x16x32_bf16 v[48:51], v[136:139], v[192:195], v[48:51]
	v_mfma_f32_16x16x32_bf16 v[44:47], v[144:147], v[192:195], v[44:47]
	v_mfma_f32_16x16x32_bf16 v[40:43], v[148:151], v[164:167], v[40:43]
	v_mfma_f32_16x16x32_bf16 v[36:39], v[156:159], v[164:167], v[36:39]
	v_mfma_f32_16x16x32_bf16 v[28:31], v[148:151], v[172:175], v[28:31]
	v_mfma_f32_16x16x32_bf16 v[24:27], v[156:159], v[172:175], v[24:27]
	v_mfma_f32_16x16x32_bf16 v[16:19], v[148:151], v[180:183], v[16:19]
	v_mfma_f32_16x16x32_bf16 v[12:15], v[156:159], v[180:183], v[12:15]
	v_mfma_f32_16x16x32_bf16 v[8:11], v[148:151], v[188:191], v[8:11]
	v_mfma_f32_16x16x32_bf16 v[4:7], v[156:159], v[188:191], v[4:7]
	v_mfma_f32_16x16x32_bf16 v[40:43], v[152:155], v[168:171], v[40:43]
	v_mfma_f32_16x16x32_bf16 v[36:39], v[160:163], v[168:171], v[36:39]
	v_mfma_f32_16x16x32_bf16 v[28:31], v[152:155], v[176:179], v[28:31]
	v_mfma_f32_16x16x32_bf16 v[24:27], v[160:163], v[176:179], v[24:27]
	v_mfma_f32_16x16x32_bf16 v[16:19], v[152:155], v[184:187], v[16:19]
	v_mfma_f32_16x16x32_bf16 v[12:15], v[160:163], v[184:187], v[12:15]
	v_mfma_f32_16x16x32_bf16 v[8:11], v[152:155], v[192:195], v[8:11]
	v_mfma_f32_16x16x32_bf16 v[4:7], v[160:163], v[192:195], v[4:7]
	s_barrier
	ds_read_b128 v[132:135], v229 offset:32768
	ds_read_b128 v[136:139], v229 offset:33792
	ds_read_b128 v[140:143], v229 offset:34816
	ds_read_b128 v[144:147], v229 offset:35840
	ds_read_b128 v[148:151], v229 offset:49152
	ds_read_b128 v[152:155], v229 offset:50176
	ds_read_b128 v[156:159], v229 offset:51200
	ds_read_b128 v[160:163], v229 offset:52224
	s_add_u32 s18, s18, 0x100000
	s_addc_u32 s19, s19, 0
	s_mov_b32 m0, s49
	v_lshl_add_u64 v[216:217], s[18:19], 0, v[196:197]
	ds_read_b128 v[164:167], v228 offset:32768
	ds_read_b128 v[168:171], v228 offset:33792
	ds_read_b128 v[172:175], v228 offset:34816
	ds_read_b128 v[176:179], v228 offset:35840
	ds_read_b128 v[180:183], v228 offset:36864
	ds_read_b128 v[184:187], v228 offset:37888
	ds_read_b128 v[188:191], v228 offset:38912
	ds_read_b128 v[192:195], v228 offset:39936
	global_load_lds_dwordx4 v[216:217], off
	v_lshl_add_u64 v[216:217], s[18:19], 0, v[200:201]
	s_mov_b32 m0, s50
	s_nop 0
	global_load_lds_dwordx4 v[216:217], off
	s_waitcnt vmcnt(8)
	s_waitcnt lgkmcnt(0)
	s_barrier
	v_mfma_f32_16x16x32_bf16 v[128:131], v[132:135], v[164:167], v[128:131]
	v_mfma_f32_16x16x32_bf16 v[124:127], v[140:143], v[164:167], v[124:127]
	v_mfma_f32_16x16x32_bf16 v[120:123], v[132:135], v[172:175], v[120:123]
	v_mfma_f32_16x16x32_bf16 v[116:119], v[140:143], v[172:175], v[116:119]
	v_mfma_f32_16x16x32_bf16 v[112:115], v[132:135], v[180:183], v[112:115]
	v_mfma_f32_16x16x32_bf16 v[108:111], v[140:143], v[180:183], v[108:111]
	v_mfma_f32_16x16x32_bf16 v[104:107], v[132:135], v[188:191], v[104:107]
	v_mfma_f32_16x16x32_bf16 v[100:103], v[140:143], v[188:191], v[100:103]
	v_mfma_f32_16x16x32_bf16 v[128:131], v[136:139], v[168:171], v[128:131]
	v_mfma_f32_16x16x32_bf16 v[124:127], v[144:147], v[168:171], v[124:127]
	v_mfma_f32_16x16x32_bf16 v[120:123], v[136:139], v[176:179], v[120:123]
	v_mfma_f32_16x16x32_bf16 v[116:119], v[144:147], v[176:179], v[116:119]
	v_mfma_f32_16x16x32_bf16 v[112:115], v[136:139], v[184:187], v[112:115]
	v_mfma_f32_16x16x32_bf16 v[108:111], v[144:147], v[184:187], v[108:111]
	v_mfma_f32_16x16x32_bf16 v[104:107], v[136:139], v[192:195], v[104:107]
	v_mfma_f32_16x16x32_bf16 v[100:103], v[144:147], v[192:195], v[100:103]
	v_mfma_f32_16x16x32_bf16 v[96:99], v[148:151], v[164:167], v[96:99]
	v_mfma_f32_16x16x32_bf16 v[92:95], v[156:159], v[164:167], v[92:95]
	v_mfma_f32_16x16x32_bf16 v[88:91], v[148:151], v[172:175], v[88:91]
	v_mfma_f32_16x16x32_bf16 v[80:83], v[156:159], v[172:175], v[80:83]
	v_mfma_f32_16x16x32_bf16 v[64:67], v[148:151], v[180:183], v[64:67]
	v_mfma_f32_16x16x32_bf16 v[52:55], v[156:159], v[180:183], v[52:55]
	v_mfma_f32_16x16x32_bf16 v[32:35], v[148:151], v[188:191], v[32:35]
	v_mfma_f32_16x16x32_bf16 v[20:23], v[156:159], v[188:191], v[20:23]
	v_mfma_f32_16x16x32_bf16 v[96:99], v[152:155], v[168:171], v[96:99]
	v_mfma_f32_16x16x32_bf16 v[92:95], v[160:163], v[168:171], v[92:95]
	v_mfma_f32_16x16x32_bf16 v[88:91], v[152:155], v[176:179], v[88:91]
	v_mfma_f32_16x16x32_bf16 v[80:83], v[160:163], v[176:179], v[80:83]
	v_mfma_f32_16x16x32_bf16 v[64:67], v[152:155], v[184:187], v[64:67]
	v_mfma_f32_16x16x32_bf16 v[52:55], v[160:163], v[184:187], v[52:55]
	v_mfma_f32_16x16x32_bf16 v[32:35], v[152:155], v[192:195], v[32:35]
	v_mfma_f32_16x16x32_bf16 v[20:23], v[160:163], v[192:195], v[20:23]
	s_barrier
; #define PG8_STAGE(bufoff, gbase, voff) do { _Pragma("unroll") for (int _i = 0; _i < 2; ++_i) \
;         __builtin_amdgcn_global_load_lds((const unsigned*)((const char*)(gbase) + (voff)[_i]), (LAS unsigned*)(lds + (bufoff) + ldsw + _i * 8192), 16, 0, 0); } while (0)
; #define PG8_LDA(dst, b, h) do { _Pragma("unroll") for (int m = 0; m < 4; ++m) _Pragma("unroll") for (int k = 0; k < 2; ++k) dst[m][k] = *(const LAS bf16x8*)(pA + PG8_SA(b, h) + m * 2048 + k * 1024); } while (0)
; #define PG8_MMA(ai, bj, At, Bt) do { __builtin_amdgcn_s_setprio(1); _Pragma("unroll") for (int m = 0; m < 4; ++m) _Pragma("unroll") for (int n = 0; n < 2; ++n) _Pragma("unroll") for (int k = 0; k < 2; ++k) \
;         acc[ai][bj][m][n] = __builtin_amdgcn_mfma_f32_16x16x32_bf16(Bt[n][k], At[m][k], acc[ai][bj][m][n], 0, 0, 0); __builtin_amdgcn_s_setprio(0); } while (0)
; #define PG8_WAIT_V(n) asm volatile("s_waitcnt vmcnt(" #n ")" ::: "memory")
; #define PG8_WAIT_L(n) asm volatile("s_waitcnt lgkmcnt(" #n ")" ::: "memory")
; #define PG8_BAR __builtin_amdgcn_s_barrier()
; #define PG8_SCHED __builtin_amdgcn_sched_barrier(0)
; template <class Desc, class Epi, bool ALIGN_EPI>
; __device__ __forceinline__ void gemm_phase(LAS unsigned char* lds, const Desc& D, const Epi& E, int G, int c) {
;     ...
;             PG8_LDA(At, 1, 1); PG8_STAGE(PG8_SB(1, 0), b3, voffB); PG8_STAGE(PG8_SB(1, 1), b3 + hstepB, voffB); PG8_STAGE(PG8_SA(1, 0), a3, voffA);
;             PG8_WAIT_V(8); PG8_WAIT_L(0); PG8_BAR; PG8_MMA(1, 0, At, B0); PG8_MMA(1, 1, At, B1); PG8_BAR; PG8_SCHED;
;         }
	s_mov_b32 m0, s52
	v_lshl_add_u64 v[208:209], v[208:209], 0, s[76:77]
	s_add_u32 s16, s16, 0x100080
	ds_read_b128 v[164:167], v228 offset:49152
	ds_read_b128 v[168:171], v228 offset:50176
	ds_read_b128 v[172:175], v228 offset:51200
	ds_read_b128 v[176:179], v228 offset:52224
	ds_read_b128 v[180:183], v228 offset:53248
	ds_read_b128 v[184:187], v228 offset:54272
	ds_read_b128 v[188:191], v228 offset:55296
	ds_read_b128 v[192:195], v228 offset:56320
	global_load_lds_dwordx4 v[208:209], off
	v_lshl_add_u64 v[208:209], v[210:211], 0, s[76:77]
	s_mov_b32 m0, s53
	s_addc_u32 s17, s17, 0
	global_load_lds_dwordx4 v[208:209], off
	v_lshl_add_u64 v[208:209], s[16:17], 0, v[198:199]
	s_mov_b32 m0, s56
	s_nop 0
	global_load_lds_dwordx4 v[208:209], off
	v_lshl_add_u64 v[208:209], s[16:17], 0, v[202:203]
	s_mov_b32 m0, s57
	s_nop 0
	global_load_lds_dwordx4 v[208:209], off
	v_lshl_add_u64 v[208:209], v[212:213], 0, s[76:77]
	s_mov_b32 m0, s54
	s_nop 0
	global_load_lds_dwordx4 v[208:209], off
	v_lshl_add_u64 v[208:209], v[214:215], 0, s[76:77]
	s_mov_b32 m0, s55
	s_nop 0
	global_load_lds_dwordx4 v[208:209], off
	s_waitcnt vmcnt(8)
	s_waitcnt lgkmcnt(0)
	s_barrier
	v_mfma_f32_16x16x32_bf16 v[84:87], v[132:135], v[164:167], v[84:87]
	v_mfma_f32_16x16x32_bf16 v[76:79], v[140:143], v[164:167], v[76:79]
	v_mfma_f32_16x16x32_bf16 v[72:75], v[132:135], v[172:175], v[72:75]
	v_mfma_f32_16x16x32_bf16 v[68:71], v[140:143], v[172:175], v[68:71]
	v_mfma_f32_16x16x32_bf16 v[60:63], v[132:135], v[180:183], v[60:63]
	v_mfma_f32_16x16x32_bf16 v[56:59], v[140:143], v[180:183], v[56:59]
	v_mfma_f32_16x16x32_bf16 v[48:51], v[132:135], v[188:191], v[48:51]
	v_mfma_f32_16x16x32_bf16 v[44:47], v[140:143], v[188:191], v[44:47]
	v_mfma_f32_16x16x32_bf16 v[84:87], v[136:139], v[168:171], v[84:87]
	v_mfma_f32_16x16x32_bf16 v[76:79], v[144:147], v[168:171], v[76:79]
	v_mfma_f32_16x16x32_bf16 v[72:75], v[136:139], v[176:179], v[72:75]
	v_mfma_f32_16x16x32_bf16 v[68:71], v[144:147], v[176:179], v[68:71]
	v_mfma_f32_16x16x32_bf16 v[60:63], v[136:139], v[184:187], v[60:63]
	v_mfma_f32_16x16x32_bf16 v[56:59], v[144:147], v[184:187], v[56:59]
	v_mfma_f32_16x16x32_bf16 v[48:51], v[136:139], v[192:195], v[48:51]
	v_mfma_f32_16x16x32_bf16 v[44:47], v[144:147], v[192:195], v[44:47]
	v_mfma_f32_16x16x32_bf16 v[40:43], v[148:151], v[164:167], v[40:43]
	v_mfma_f32_16x16x32_bf16 v[36:39], v[156:159], v[164:167], v[36:39]
	v_mfma_f32_16x16x32_bf16 v[28:31], v[148:151], v[172:175], v[28:31]
	v_mfma_f32_16x16x32_bf16 v[24:27], v[156:159], v[172:175], v[24:27]
	v_mfma_f32_16x16x32_bf16 v[16:19], v[148:151], v[180:183], v[16:19]
	v_mfma_f32_16x16x32_bf16 v[12:15], v[156:159], v[180:183], v[12:15]
	v_mfma_f32_16x16x32_bf16 v[8:11], v[148:151], v[188:191], v[8:11]
	v_mfma_f32_16x16x32_bf16 v[4:7], v[156:159], v[188:191], v[4:7]
	v_mfma_f32_16x16x32_bf16 v[40:43], v[152:155], v[168:171], v[40:43]
	v_mfma_f32_16x16x32_bf16 v[36:39], v[160:163], v[168:171], v[36:39]
	v_mfma_f32_16x16x32_bf16 v[28:31], v[152:155], v[176:179], v[28:31]
	v_mfma_f32_16x16x32_bf16 v[24:27], v[160:163], v[176:179], v[24:27]
	v_mfma_f32_16x16x32_bf16 v[16:19], v[152:155], v[184:187], v[16:19]
	v_mfma_f32_16x16x32_bf16 v[12:15], v[160:163], v[184:187], v[12:15]
	v_mfma_f32_16x16x32_bf16 v[8:11], v[152:155], v[192:195], v[8:11]
	v_mfma_f32_16x16x32_bf16 v[4:7], v[160:163], v[192:195], v[4:7]
	s_barrier
	s_add_u32 s12, s12, 0x100
	s_addc_u32 s13, s13, 0
	s_add_u32 s3, s3, 0x100
	s_addc_u32 s11, s11, 0
	s_cmp_ge_u32 s20, s2
	s_mov_b32 s14, s20
	s_cbranch_scc0 .LBB0_1164
	s_and_b64 vcc, exec, s[8:9]
	s_cbranch_vccz .LBB0_1167
	s_barrier

;     __device__ __forceinline__ int nt(const Unit& u) const { return (u.pn >> 1) < 2 ? 22 : 20; }
; #define PG8_STAGE(bufoff, gbase, voff) do { _Pragma("unroll") for (int _i = 0; _i < 2; ++_i) \
;         __builtin_amdgcn_global_load_lds((const unsigned*)((const char*)(gbase) + (voff)[_i]), (LAS unsigned*)(lds + (bufoff) + ldsw + _i * 8192), 16, 0, 0); } while (0)
; #define PG8_LDA(dst, b, h) do { _Pragma("unroll") for (int m = 0; m < 4; ++m) _Pragma("unroll") for (int k = 0; k < 2; ++k) dst[m][k] = *(const LAS bf16x8*)(pA + PG8_SA(b, h) + m * 2048 + k * 1024); } while (0)
; #define PG8_LDB(dst, b, h) do { _Pragma("unroll") for (int n = 0; n < 2; ++n) _Pragma("unroll") for (int k = 0; k < 2; ++k) dst[n][k] = *(const LAS bf16x8*)(pB + (PG8_SB(b, h) - 4 * HTB) + n * 2048 + k * 1024); } while (0)
; #define PG8_MMA(ai, bj, At, Bt) do { __builtin_amdgcn_s_setprio(1); _Pragma("unroll") for (int m = 0; m < 4; ++m) _Pragma("unroll") for (int n = 0; n < 2; ++n) _Pragma("unroll") for (int k = 0; k < 2; ++k) \
;         acc[ai][bj][m][n] = __builtin_amdgcn_mfma_f32_16x16x32_bf16(Bt[n][k], At[m][k], acc[ai][bj][m][n], 0, 0, 0); __builtin_amdgcn_s_setprio(0); } while (0)
; #define PG8_WAIT_V(n) asm volatile("s_waitcnt vmcnt(" #n ")" ::: "memory")
; #define PG8_WAIT_L(n) asm volatile("s_waitcnt lgkmcnt(" #n ")" ::: "memory")
; template <class Desc, class Epi, bool ALIGN_EPI>
; __device__ __forceinline__ void gemm_phase(LAS unsigned char* lds, const Desc& D, const Epi& E, int G, int c) {
;     ...
;             const bool last = (t == nt - 2);
;             if (last && has_next) PG8_AWAIT(nxt);
;             const char* a1 = cA + (size_t)(t + 1) * kstep;
;             const char* a2 = last ? nA : cA + (size_t)(t + 2) * kstep; const char* b2 = last ? nB : cB + (size_t)(t + 2) * kstep;
;             const char* a3 = a2 + kstep; const char* b3 = b2 + kstep;
;             PG8_LDB(B0, 0, 0); PG8_LDB(B1, 0, 1); PG8_SCHED; PG8_LDA(At, 0, 0); PG8_STAGE(PG8_SA(1, 1), a1 + hstepA, voffA);
;             PG8_WAIT_V(8); PG8_WAIT_L(0); PG8_BAR; PG8_MMA(0, 0, At, B0); PG8_MMA(0, 1, At, B1); PG8_BAR; PG8_SCHED;
;             PG8_LDA(At, 0, 1); PG8_STAGE(PG8_SB(0, 0), b2, voffB); PG8_STAGE(PG8_SB(0, 1), b2 + hstepB, voffB); PG8_STAGE(PG8_SA(0, 0), a2, voffA);
;             PG8_WAIT_V(8); PG8_WAIT_L(0); PG8_BAR; PG8_MMA(1, 0, At, B0); PG8_MMA(1, 1, At, B1); PG8_BAR; PG8_SCHED;
.LBB0_1324:
	ds_read_b128 v[144:147], v149
	ds_read_b128 v[152:155], v149 offset:1024
	ds_read_b128 v[156:159], v149 offset:2048
	ds_read_b128 v[160:163], v149 offset:3072
	ds_read_b128 v[164:167], v149 offset:16384
	ds_read_b128 v[168:171], v149 offset:17408
	ds_read_b128 v[172:175], v149 offset:18432
	ds_read_b128 v[176:179], v149 offset:19456
	s_add_i32 s50, s18, 2
	s_add_u32 s19, s16, 0xfff00080
	s_addc_u32 s20, s17, -1
	s_cmp_eq_u32 s9, s18
	s_cselect_b32 s18, s12, s48
	s_cselect_b32 s21, s11, s20
	s_cselect_b32 s20, s10, s19
	s_cselect_b32 s19, s13, s49
	v_lshl_add_u64 v[212:213], s[16:17], 0, v[140:141]
	s_add_i32 m0, s24, 0xc000
	ds_read_b128 v[180:183], v148
	ds_read_b128 v[184:187], v148 offset:1024
	ds_read_b128 v[188:191], v148 offset:2048
	ds_read_b128 v[192:195], v148 offset:3072
	ds_read_b128 v[196:199], v148 offset:4096
	ds_read_b128 v[200:203], v148 offset:5120
	ds_read_b128 v[204:207], v148 offset:6144
	ds_read_b128 v[208:211], v148 offset:7168
	global_load_lds_dwordx4 v[212:213], off
	v_lshl_add_u64 v[212:213], s[16:17], 0, v[142:143]
	s_add_i32 m0, s24, 0xe000
	s_nop 0
	global_load_lds_dwordx4 v[212:213], off
	s_waitcnt vmcnt(8)
	s_waitcnt lgkmcnt(0)
	s_barrier
	v_mfma_f32_16x16x32_bf16 v[128:131], v[144:147], v[180:183], v[128:131]
	v_mfma_f32_16x16x32_bf16 v[124:127], v[156:159], v[180:183], v[124:127]
	v_mfma_f32_16x16x32_bf16 v[120:123], v[144:147], v[188:191], v[120:123]
	v_mfma_f32_16x16x32_bf16 v[112:115], v[156:159], v[188:191], v[112:115]
	v_mfma_f32_16x16x32_bf16 v[104:107], v[144:147], v[196:199], v[104:107]
	v_mfma_f32_16x16x32_bf16 v[96:99], v[156:159], v[196:199], v[96:99]
	v_mfma_f32_16x16x32_bf16 v[88:91], v[144:147], v[204:207], v[88:91]
	v_mfma_f32_16x16x32_bf16 v[80:83], v[156:159], v[204:207], v[80:83]
	v_mfma_f32_16x16x32_bf16 v[128:131], v[152:155], v[184:187], v[128:131]
	v_mfma_f32_16x16x32_bf16 v[124:127], v[160:163], v[184:187], v[124:127]
	v_mfma_f32_16x16x32_bf16 v[120:123], v[152:155], v[192:195], v[120:123]
	v_mfma_f32_16x16x32_bf16 v[112:115], v[160:163], v[192:195], v[112:115]
	v_mfma_f32_16x16x32_bf16 v[104:107], v[152:155], v[200:203], v[104:107]
	v_mfma_f32_16x16x32_bf16 v[96:99], v[160:163], v[200:203], v[96:99]
	v_mfma_f32_16x16x32_bf16 v[88:91], v[152:155], v[208:211], v[88:91]
	v_mfma_f32_16x16x32_bf16 v[80:83], v[160:163], v[208:211], v[80:83]
	v_mfma_f32_16x16x32_bf16 v[116:119], v[164:167], v[180:183], v[116:119]
	v_mfma_f32_16x16x32_bf16 v[108:111], v[172:175], v[180:183], v[108:111]
	v_mfma_f32_16x16x32_bf16 v[100:103], v[164:167], v[188:191], v[100:103]
	v_mfma_f32_16x16x32_bf16 v[92:95], v[172:175], v[188:191], v[92:95]
	v_mfma_f32_16x16x32_bf16 v[84:87], v[164:167], v[196:199], v[84:87]
	v_mfma_f32_16x16x32_bf16 v[76:79], v[172:175], v[196:199], v[76:79]
	v_mfma_f32_16x16x32_bf16 v[72:75], v[164:167], v[204:207], v[72:75]
	v_mfma_f32_16x16x32_bf16 v[68:71], v[172:175], v[204:207], v[68:71]
	v_mfma_f32_16x16x32_bf16 v[116:119], v[168:171], v[184:187], v[116:119]
	v_mfma_f32_16x16x32_bf16 v[108:111], v[176:179], v[184:187], v[108:111]
	v_mfma_f32_16x16x32_bf16 v[100:103], v[168:171], v[192:195], v[100:103]
	v_mfma_f32_16x16x32_bf16 v[92:95], v[176:179], v[192:195], v[92:95]
	v_mfma_f32_16x16x32_bf16 v[84:87], v[168:171], v[200:203], v[84:87]
	v_mfma_f32_16x16x32_bf16 v[76:79], v[176:179], v[200:203], v[76:79]
	v_mfma_f32_16x16x32_bf16 v[72:75], v[168:171], v[208:211], v[72:75]
	v_mfma_f32_16x16x32_bf16 v[68:71], v[176:179], v[208:211], v[68:71]
	s_barrier
	s_mov_b32 m0, s25
	v_lshl_add_u64 v[212:213], s[18:19], 0, v[136:137]
	s_add_u32 s52, s18, 0x100000
	ds_read_b128 v[180:183], v148 offset:16384
	ds_read_b128 v[184:187], v148 offset:17408
	ds_read_b128 v[188:191], v148 offset:18432
	ds_read_b128 v[192:195], v148 offset:19456
	ds_read_b128 v[196:199], v148 offset:20480
	ds_read_b128 v[200:203], v148 offset:21504
	ds_read_b128 v[204:207], v148 offset:22528
	ds_read_b128 v[208:211], v148 offset:23552
	global_load_lds_dwordx4 v[212:213], off
	v_lshl_add_u64 v[214:215], s[18:19], 0, v[132:133]
	s_mov_b32 m0, s26
	s_addc_u32 s53, s19, 0
	global_load_lds_dwordx4 v[214:215], off
	v_lshl_add_u64 v[216:217], s[52:53], 0, v[136:137]
	s_mov_b32 m0, s27
	v_lshl_add_u64 v[218:219], s[20:21], 0, v[134:135]
	global_load_lds_dwordx4 v[216:217], off
	v_lshl_add_u64 v[216:217], s[52:53], 0, v[132:133]
	s_mov_b32 m0, s30
	s_nop 0
	global_load_lds_dwordx4 v[216:217], off
	v_lshl_add_u64 v[216:217], s[20:21], 0, v[138:139]
	s_mov_b32 m0, s24
	s_nop 0
	global_load_lds_dwordx4 v[216:217], off
	s_mov_b32 m0, s31
	s_nop 0
	global_load_lds_dwordx4 v[218:219], off
	s_waitcnt vmcnt(8)
	s_waitcnt lgkmcnt(0)
	s_barrier
; #define PG8_STAGE(bufoff, gbase, voff) do { _Pragma("unroll") for (int _i = 0; _i < 2; ++_i) \
;         __builtin_amdgcn_global_load_lds((const unsigned*)((const char*)(gbase) + (voff)[_i]), (LAS unsigned*)(lds + (bufoff) + ldsw + _i * 8192), 16, 0, 0); } while (0)
; #define PG8_LDA(dst, b, h) do { _Pragma("unroll") for (int m = 0; m < 4; ++m) _Pragma("unroll") for (int k = 0; k < 2; ++k) dst[m][k] = *(const LAS bf16x8*)(pA + PG8_SA(b, h) + m * 2048 + k * 1024); } while (0)
; #define PG8_LDB(dst, b, h) do { _Pragma("unroll") for (int n = 0; n < 2; ++n) _Pragma("unroll") for (int k = 0; k < 2; ++k) dst[n][k] = *(const LAS bf16x8*)(pB + (PG8_SB(b, h) - 4 * HTB) + n * 2048 + k * 1024); } while (0)
; #define PG8_MMA(ai, bj, At, Bt) do { __builtin_amdgcn_s_setprio(1); _Pragma("unroll") for (int m = 0; m < 4; ++m) _Pragma("unroll") for (int n = 0; n < 2; ++n) _Pragma("unroll") for (int k = 0; k < 2; ++k) \
;         acc[ai][bj][m][n] = __builtin_amdgcn_mfma_f32_16x16x32_bf16(Bt[n][k], At[m][k], acc[ai][bj][m][n], 0, 0, 0); __builtin_amdgcn_s_setprio(0); } while (0)
; #define PG8_WAIT_V(n) asm volatile("s_waitcnt vmcnt(" #n ")" ::: "memory")
; #define PG8_WAIT_L(n) asm volatile("s_waitcnt lgkmcnt(" #n ")" ::: "memory")
; #define PG8_BAR __builtin_amdgcn_s_barrier()
; #define PG8_SCHED __builtin_amdgcn_sched_barrier(0)
; template <class Desc, class Epi, bool ALIGN_EPI>
; __device__ __forceinline__ void gemm_phase(LAS unsigned char* lds, const Desc& D, const Epi& E, int G, int c) {
;     ...
;             PG8_WAIT_V(8); PG8_WAIT_L(0); PG8_BAR; PG8_MMA(1, 0, At, B0); PG8_MMA(1, 1, At, B1); PG8_BAR; PG8_SCHED;
;             PG8_LDB(B0, 1, 0); PG8_LDB(B1, 1, 1); PG8_SCHED; PG8_LDA(At, 1, 0); PG8_STAGE(PG8_SA(0, 1), a2 + hstepA, voffA);
;             PG8_WAIT_V(8); PG8_WAIT_L(0); PG8_BAR; PG8_MMA(0, 0, At, B0); PG8_MMA(0, 1, At, B1); PG8_BAR; PG8_SCHED;
	v_mfma_f32_16x16x32_bf16 v[64:67], v[144:147], v[180:183], v[64:67]
	v_mfma_f32_16x16x32_bf16 v[60:63], v[156:159], v[180:183], v[60:63]
	v_mfma_f32_16x16x32_bf16 v[56:59], v[144:147], v[188:191], v[56:59]
	v_mfma_f32_16x16x32_bf16 v[48:51], v[156:159], v[188:191], v[48:51]
	v_mfma_f32_16x16x32_bf16 v[40:43], v[144:147], v[196:199], v[40:43]
	v_mfma_f32_16x16x32_bf16 v[32:35], v[156:159], v[196:199], v[32:35]
	v_mfma_f32_16x16x32_bf16 v[24:27], v[144:147], v[204:207], v[24:27]
	v_mfma_f32_16x16x32_bf16 v[16:19], v[156:159], v[204:207], v[16:19]
	v_mfma_f32_16x16x32_bf16 v[64:67], v[152:155], v[184:187], v[64:67]
	v_mfma_f32_16x16x32_bf16 v[60:63], v[160:163], v[184:187], v[60:63]
	v_mfma_f32_16x16x32_bf16 v[56:59], v[152:155], v[192:195], v[56:59]
	v_mfma_f32_16x16x32_bf16 v[48:51], v[160:163], v[192:195], v[48:51]
	v_mfma_f32_16x16x32_bf16 v[40:43], v[152:155], v[200:203], v[40:43]
	v_mfma_f32_16x16x32_bf16 v[32:35], v[160:163], v[200:203], v[32:35]
	v_mfma_f32_16x16x32_bf16 v[24:27], v[152:155], v[208:211], v[24:27]
	v_mfma_f32_16x16x32_bf16 v[16:19], v[160:163], v[208:211], v[16:19]
	v_mfma_f32_16x16x32_bf16 v[52:55], v[164:167], v[180:183], v[52:55]
	v_mfma_f32_16x16x32_bf16 v[44:47], v[172:175], v[180:183], v[44:47]
	v_mfma_f32_16x16x32_bf16 v[36:39], v[164:167], v[188:191], v[36:39]
	v_mfma_f32_16x16x32_bf16 v[28:31], v[172:175], v[188:191], v[28:31]
	v_mfma_f32_16x16x32_bf16 v[20:23], v[164:167], v[196:199], v[20:23]
	v_mfma_f32_16x16x32_bf16 v[12:15], v[172:175], v[196:199], v[12:15]
	v_mfma_f32_16x16x32_bf16 v[8:11], v[164:167], v[204:207], v[8:11]
	v_mfma_f32_16x16x32_bf16 v[4:7], v[172:175], v[204:207], v[4:7]
	v_mfma_f32_16x16x32_bf16 v[52:55], v[168:171], v[184:187], v[52:55]
	v_mfma_f32_16x16x32_bf16 v[44:47], v[176:179], v[184:187], v[44:47]
	v_mfma_f32_16x16x32_bf16 v[36:39], v[168:171], v[192:195], v[36:39]
	v_mfma_f32_16x16x32_bf16 v[28:31], v[176:179], v[192:195], v[28:31]
	v_mfma_f32_16x16x32_bf16 v[20:23], v[168:171], v[200:203], v[20:23]
	v_mfma_f32_16x16x32_bf16 v[12:15], v[176:179], v[200:203], v[12:15]
	v_mfma_f32_16x16x32_bf16 v[8:11], v[168:171], v[208:211], v[8:11]
	v_mfma_f32_16x16x32_bf16 v[4:7], v[176:179], v[208:211], v[4:7]
	s_barrier
	ds_read_b128 v[144:147], v149 offset:32768
	ds_read_b128 v[152:155], v149 offset:33792
	ds_read_b128 v[156:159], v149 offset:34816
	ds_read_b128 v[160:163], v149 offset:35840
	ds_read_b128 v[164:167], v149 offset:49152
	ds_read_b128 v[168:171], v149 offset:50176
	ds_read_b128 v[172:175], v149 offset:51200
	ds_read_b128 v[176:179], v149 offset:52224
	s_add_u32 s20, s20, 0x100000
	s_addc_u32 s21, s21, 0
	s_mov_b32 m0, s33
	v_lshl_add_u64 v[220:221], s[20:21], 0, v[138:139]
	ds_read_b128 v[180:183], v148 offset:32768
	ds_read_b128 v[184:187], v148 offset:33792
	ds_read_b128 v[188:191], v148 offset:34816
	ds_read_b128 v[192:195], v148 offset:35840
	ds_read_b128 v[196:199], v148 offset:36864
	ds_read_b128 v[200:203], v148 offset:37888
	ds_read_b128 v[204:207], v148 offset:38912
	ds_read_b128 v[208:211], v148 offset:39936
	global_load_lds_dwordx4 v[220:221], off
	v_lshl_add_u64 v[220:221], s[20:21], 0, v[134:135]
	s_mov_b32 m0, s34
	s_nop 0
	global_load_lds_dwordx4 v[220:221], off
	s_waitcnt vmcnt(8)
	s_waitcnt lgkmcnt(0)
	s_barrier
	v_mfma_f32_16x16x32_bf16 v[128:131], v[144:147], v[180:183], v[128:131]
	v_mfma_f32_16x16x32_bf16 v[124:127], v[156:159], v[180:183], v[124:127]
	v_mfma_f32_16x16x32_bf16 v[120:123], v[144:147], v[188:191], v[120:123]
	v_mfma_f32_16x16x32_bf16 v[112:115], v[156:159], v[188:191], v[112:115]
	v_mfma_f32_16x16x32_bf16 v[104:107], v[144:147], v[196:199], v[104:107]
	v_mfma_f32_16x16x32_bf16 v[96:99], v[156:159], v[196:199], v[96:99]
	v_mfma_f32_16x16x32_bf16 v[88:91], v[144:147], v[204:207], v[88:91]
	v_mfma_f32_16x16x32_bf16 v[80:83], v[156:159], v[204:207], v[80:83]
	v_mfma_f32_16x16x32_bf16 v[128:131], v[152:155], v[184:187], v[128:131]
	v_mfma_f32_16x16x32_bf16 v[124:127], v[160:163], v[184:187], v[124:127]
	v_mfma_f32_16x16x32_bf16 v[120:123], v[152:155], v[192:195], v[120:123]
	v_mfma_f32_16x16x32_bf16 v[112:115], v[160:163], v[192:195], v[112:115]
	v_mfma_f32_16x16x32_bf16 v[104:107], v[152:155], v[200:203], v[104:107]
	v_mfma_f32_16x16x32_bf16 v[96:99], v[160:163], v[200:203], v[96:99]
	v_mfma_f32_16x16x32_bf16 v[88:91], v[152:155], v[208:211], v[88:91]
	v_mfma_f32_16x16x32_bf16 v[80:83], v[160:163], v[208:211], v[80:83]
	v_mfma_f32_16x16x32_bf16 v[116:119], v[164:167], v[180:183], v[116:119]
	v_mfma_f32_16x16x32_bf16 v[108:111], v[172:175], v[180:183], v[108:111]
	v_mfma_f32_16x16x32_bf16 v[100:103], v[164:167], v[188:191], v[100:103]
	v_mfma_f32_16x16x32_bf16 v[92:95], v[172:175], v[188:191], v[92:95]
	v_mfma_f32_16x16x32_bf16 v[84:87], v[164:167], v[196:199], v[84:87]
	v_mfma_f32_16x16x32_bf16 v[76:79], v[172:175], v[196:199], v[76:79]
	v_mfma_f32_16x16x32_bf16 v[72:75], v[164:167], v[204:207], v[72:75]
	v_mfma_f32_16x16x32_bf16 v[68:71], v[172:175], v[204:207], v[68:71]
	v_mfma_f32_16x16x32_bf16 v[116:119], v[168:171], v[184:187], v[116:119]
	v_mfma_f32_16x16x32_bf16 v[108:111], v[176:179], v[184:187], v[108:111]
	v_mfma_f32_16x16x32_bf16 v[100:103], v[168:171], v[192:195], v[100:103]
	v_mfma_f32_16x16x32_bf16 v[92:95], v[176:179], v[192:195], v[92:95]
	v_mfma_f32_16x16x32_bf16 v[84:87], v[168:171], v[200:203], v[84:87]
	v_mfma_f32_16x16x32_bf16 v[76:79], v[176:179], v[200:203], v[76:79]
	v_mfma_f32_16x16x32_bf16 v[72:75], v[168:171], v[208:211], v[72:75]
	v_mfma_f32_16x16x32_bf16 v[68:71], v[176:179], v[208:211], v[68:71]
	s_barrier
; #define PG8_STAGE(bufoff, gbase, voff) do { _Pragma("unroll") for (int _i = 0; _i < 2; ++_i) \
;         __builtin_amdgcn_global_load_lds((const unsigned*)((const char*)(gbase) + (voff)[_i]), (LAS unsigned*)(lds + (bufoff) + ldsw + _i * 8192), 16, 0, 0); } while (0)
; #define PG8_LDA(dst, b, h) do { _Pragma("unroll") for (int m = 0; m < 4; ++m) _Pragma("unroll") for (int k = 0; k < 2; ++k) dst[m][k] = *(const LAS bf16x8*)(pA + PG8_SA(b, h) + m * 2048 + k * 1024); } while (0)
; #define PG8_MMA(ai, bj, At, Bt) do { __builtin_amdgcn_s_setprio(1); _Pragma("unroll") for (int m = 0; m < 4; ++m) _Pragma("unroll") for (int n = 0; n < 2; ++n) _Pragma("unroll") for (int k = 0; k < 2; ++k) \
;         acc[ai][bj][m][n] = __builtin_amdgcn_mfma_f32_16x16x32_bf16(Bt[n][k], At[m][k], acc[ai][bj][m][n], 0, 0, 0); __builtin_amdgcn_s_setprio(0); } while (0)
; #define PG8_WAIT_V(n) asm volatile("s_waitcnt vmcnt(" #n ")" ::: "memory")
; #define PG8_WAIT_L(n) asm volatile("s_waitcnt lgkmcnt(" #n ")" ::: "memory")
; #define PG8_BAR __builtin_amdgcn_s_barrier()
; #define PG8_SCHED __builtin_amdgcn_sched_barrier(0)
; template <class Desc, class Epi, bool ALIGN_EPI>
; __device__ __forceinline__ void gemm_phase(LAS unsigned char* lds, const Desc& D, const Epi& E, int G, int c) {
;     ...
;             PG8_LDA(At, 1, 1); PG8_STAGE(PG8_SB(1, 0), b3, voffB); PG8_STAGE(PG8_SB(1, 1), b3 + hstepB, voffB); PG8_STAGE(PG8_SA(1, 0), a3, voffA);
;             PG8_WAIT_V(8); PG8_WAIT_L(0); PG8_BAR; PG8_MMA(1, 0, At, B0); PG8_MMA(1, 1, At, B1); PG8_BAR; PG8_SCHED;
;         }
	s_mov_b32 m0, s35
	v_lshl_add_u64 v[212:213], v[212:213], 0, s[76:77]
	s_add_u32 s18, s18, 0x100080
	ds_read_b128 v[180:183], v148 offset:49152
	ds_read_b128 v[184:187], v148 offset:50176
	ds_read_b128 v[188:191], v148 offset:51200
	ds_read_b128 v[192:195], v148 offset:52224
	ds_read_b128 v[196:199], v148 offset:53248
	ds_read_b128 v[200:203], v148 offset:54272
	ds_read_b128 v[204:207], v148 offset:55296
	ds_read_b128 v[208:211], v148 offset:56320
	global_load_lds_dwordx4 v[212:213], off
	v_lshl_add_u64 v[212:213], v[214:215], 0, s[76:77]
	s_mov_b32 m0, s38
	s_addc_u32 s19, s19, 0
	global_load_lds_dwordx4 v[212:213], off
	v_lshl_add_u64 v[212:213], s[18:19], 0, v[136:137]
	s_mov_b32 m0, s41
	s_nop 0
	global_load_lds_dwordx4 v[212:213], off
	v_lshl_add_u64 v[212:213], s[18:19], 0, v[132:133]
	s_mov_b32 m0, s42
	s_nop 0
	global_load_lds_dwordx4 v[212:213], off
	v_lshl_add_u64 v[212:213], v[216:217], 0, s[76:77]
	s_mov_b32 m0, s39
	s_nop 0
	global_load_lds_dwordx4 v[212:213], off
	v_lshl_add_u64 v[212:213], v[218:219], 0, s[76:77]
	s_mov_b32 m0, s40
	s_nop 0
	global_load_lds_dwordx4 v[212:213], off
	s_waitcnt vmcnt(8)
	s_waitcnt lgkmcnt(0)
	s_barrier
	v_mfma_f32_16x16x32_bf16 v[64:67], v[144:147], v[180:183], v[64:67]
	v_mfma_f32_16x16x32_bf16 v[60:63], v[156:159], v[180:183], v[60:63]
	v_mfma_f32_16x16x32_bf16 v[56:59], v[144:147], v[188:191], v[56:59]
	v_mfma_f32_16x16x32_bf16 v[48:51], v[156:159], v[188:191], v[48:51]
	v_mfma_f32_16x16x32_bf16 v[40:43], v[144:147], v[196:199], v[40:43]
	v_mfma_f32_16x16x32_bf16 v[32:35], v[156:159], v[196:199], v[32:35]
	v_mfma_f32_16x16x32_bf16 v[24:27], v[144:147], v[204:207], v[24:27]
	v_mfma_f32_16x16x32_bf16 v[16:19], v[156:159], v[204:207], v[16:19]
	v_mfma_f32_16x16x32_bf16 v[64:67], v[152:155], v[184:187], v[64:67]
	v_mfma_f32_16x16x32_bf16 v[60:63], v[160:163], v[184:187], v[60:63]
	v_mfma_f32_16x16x32_bf16 v[56:59], v[152:155], v[192:195], v[56:59]
	v_mfma_f32_16x16x32_bf16 v[48:51], v[160:163], v[192:195], v[48:51]
	v_mfma_f32_16x16x32_bf16 v[40:43], v[152:155], v[200:203], v[40:43]
	v_mfma_f32_16x16x32_bf16 v[32:35], v[160:163], v[200:203], v[32:35]
	v_mfma_f32_16x16x32_bf16 v[24:27], v[152:155], v[208:211], v[24:27]
	v_mfma_f32_16x16x32_bf16 v[16:19], v[160:163], v[208:211], v[16:19]
	v_mfma_f32_16x16x32_bf16 v[52:55], v[164:167], v[180:183], v[52:55]
	v_mfma_f32_16x16x32_bf16 v[44:47], v[172:175], v[180:183], v[44:47]
	v_mfma_f32_16x16x32_bf16 v[36:39], v[164:167], v[188:191], v[36:39]
	v_mfma_f32_16x16x32_bf16 v[28:31], v[172:175], v[188:191], v[28:31]
	v_mfma_f32_16x16x32_bf16 v[20:23], v[164:167], v[196:199], v[20:23]
	v_mfma_f32_16x16x32_bf16 v[12:15], v[172:175], v[196:199], v[12:15]
	v_mfma_f32_16x16x32_bf16 v[8:11], v[164:167], v[204:207], v[8:11]
	v_mfma_f32_16x16x32_bf16 v[4:7], v[172:175], v[204:207], v[4:7]
	v_mfma_f32_16x16x32_bf16 v[52:55], v[168:171], v[184:187], v[52:55]
	v_mfma_f32_16x16x32_bf16 v[44:47], v[176:179], v[184:187], v[44:47]
	v_mfma_f32_16x16x32_bf16 v[36:39], v[168:171], v[192:195], v[36:39]
	v_mfma_f32_16x16x32_bf16 v[28:31], v[176:179], v[192:195], v[28:31]
	v_mfma_f32_16x16x32_bf16 v[20:23], v[168:171], v[200:203], v[20:23]
	v_mfma_f32_16x16x32_bf16 v[12:15], v[176:179], v[200:203], v[12:15]
	v_mfma_f32_16x16x32_bf16 v[8:11], v[168:171], v[208:211], v[8:11]
	v_mfma_f32_16x16x32_bf16 v[4:7], v[176:179], v[208:211], v[4:7]
	s_barrier
	s_add_u32 s16, s16, 0x100
	s_addc_u32 s17, s17, 0
	s_add_u32 s48, s48, 0x100
	s_addc_u32 s49, s49, 0
	s_cmp_ge_u32 s50, s46
	s_mov_b32 s18, s50
	s_cbranch_scc0 .LBB0_1324
	s_and_b64 vcc, exec, s[6:7]
	s_cbranch_vccz .LBB0_1327
	s_barrier

;     __device__ __forceinline__ int nt(const Unit& u) const { return (u.pn >> 1) < 2 ? 22 : 20; }
; #define PG8_STAGE(bufoff, gbase, voff) do { _Pragma("unroll") for (int _i = 0; _i < 2; ++_i) \
;         __builtin_amdgcn_global_load_lds((const unsigned*)((const char*)(gbase) + (voff)[_i]), (LAS unsigned*)(lds + (bufoff) + ldsw + _i * 8192), 16, 0, 0); } while (0)
; #define PG8_LDA(dst, b, h) do { _Pragma("unroll") for (int m = 0; m < 4; ++m) _Pragma("unroll") for (int k = 0; k < 2; ++k) dst[m][k] = *(const LAS bf16x8*)(pA + PG8_SA(b, h) + m * 2048 + k * 1024); } while (0)
; #define PG8_LDB(dst, b, h) do { _Pragma("unroll") for (int n = 0; n < 2; ++n) _Pragma("unroll") for (int k = 0; k < 2; ++k) dst[n][k] = *(const LAS bf16x8*)(pB + (PG8_SB(b, h) - 4 * HTB) + n * 2048 + k * 1024); } while (0)
; #define PG8_MMA(ai, bj, At, Bt) do { __builtin_amdgcn_s_setprio(1); _Pragma("unroll") for (int m = 0; m < 4; ++m) _Pragma("unroll") for (int n = 0; n < 2; ++n) _Pragma("unroll") for (int k = 0; k < 2; ++k) \
;         acc[ai][bj][m][n] = __builtin_amdgcn_mfma_f32_16x16x32_bf16(Bt[n][k], At[m][k], acc[ai][bj][m][n], 0, 0, 0); __builtin_amdgcn_s_setprio(0); } while (0)
; #define PG8_WAIT_V(n) asm volatile("s_waitcnt vmcnt(" #n ")" ::: "memory")
; #define PG8_WAIT_L(n) asm volatile("s_waitcnt lgkmcnt(" #n ")" ::: "memory")
; template <class Desc, class Epi, bool ALIGN_EPI>
; __device__ __forceinline__ void gemm_phase(LAS unsigned char* lds, const Desc& D, const Epi& E, int G, int c) {
;     ...
;             const bool last = (t == nt - 2);
;             if (last && has_next) PG8_AWAIT(nxt);
;             const char* a1 = cA + (size_t)(t + 1) * kstep;
;             const char* a2 = last ? nA : cA + (size_t)(t + 2) * kstep; const char* b2 = last ? nB : cB + (size_t)(t + 2) * kstep;
;             const char* a3 = a2 + kstep; const char* b3 = b2 + kstep;
;             PG8_LDB(B0, 0, 0); PG8_LDB(B1, 0, 1); PG8_SCHED; PG8_LDA(At, 0, 0); PG8_STAGE(PG8_SA(1, 1), a1 + hstepA, voffA);
;             PG8_WAIT_V(8); PG8_WAIT_L(0); PG8_BAR; PG8_MMA(0, 0, At, B0); PG8_MMA(0, 1, At, B1); PG8_BAR; PG8_SCHED;
;             PG8_LDA(At, 0, 1); PG8_STAGE(PG8_SB(0, 0), b2, voffB); PG8_STAGE(PG8_SB(0, 1), b2 + hstepB, voffB); PG8_STAGE(PG8_SA(0, 0), a2, voffA);
;             PG8_WAIT_V(8); PG8_WAIT_L(0); PG8_BAR; PG8_MMA(1, 0, At, B0); PG8_MMA(1, 1, At, B1); PG8_BAR; PG8_SCHED;
.LBB0_1479:
	ds_read_b128 v[116:119], v225
	ds_read_b128 v[128:131], v225 offset:1024
	ds_read_b128 v[132:135], v225 offset:2048
	ds_read_b128 v[136:139], v225 offset:3072
	ds_read_b128 v[140:143], v225 offset:16384
	ds_read_b128 v[144:147], v225 offset:17408
	ds_read_b128 v[148:151], v225 offset:18432
	ds_read_b128 v[152:155], v225 offset:19456
	s_add_u32 s12, s0, 0xfffe0080
	s_addc_u32 s13, s1, -1
	s_cmp_eq_u32 s52, 4
	s_cselect_b32 s17, s37, s13
	s_cselect_b32 s16, s36, s12
	s_cselect_b32 s13, s21, s33
	s_cselect_b32 s12, s24, s27
	v_lshl_add_u64 v[208:209], s[0:1], 0, v[200:201]
	s_add_i32 m0, s31, 0xc000
	ds_read_b128 v[164:167], v224
	ds_read_b128 v[168:171], v224 offset:1024
	ds_read_b128 v[172:175], v224 offset:2048
	ds_read_b128 v[176:179], v224 offset:3072
	ds_read_b128 v[180:183], v224 offset:4096
	ds_read_b128 v[184:187], v224 offset:5120
	ds_read_b128 v[188:191], v224 offset:6144
	ds_read_b128 v[204:207], v224 offset:7168
	global_load_lds_dwordx4 v[208:209], off
	v_lshl_add_u64 v[208:209], s[0:1], 0, v[202:203]
	s_add_i32 m0, s31, 0xe000
	s_nop 0
	global_load_lds_dwordx4 v[208:209], off
	s_waitcnt vmcnt(8)
	s_waitcnt lgkmcnt(0)
	s_barrier
	v_mfma_f32_16x16x32_bf16 v[160:163], v[116:119], v[164:167], v[160:163]
	v_mfma_f32_16x16x32_bf16 v[156:159], v[132:135], v[164:167], v[156:159]
	v_mfma_f32_16x16x32_bf16 v[112:115], v[116:119], v[172:175], v[112:115]
	v_mfma_f32_16x16x32_bf16 v[108:111], v[132:135], v[172:175], v[108:111]
	v_mfma_f32_16x16x32_bf16 v[96:99], v[116:119], v[180:183], v[96:99]
	v_mfma_f32_16x16x32_bf16 v[92:95], v[132:135], v[180:183], v[92:95]
	v_mfma_f32_16x16x32_bf16 v[80:83], v[116:119], v[188:191], v[80:83]
	v_mfma_f32_16x16x32_bf16 v[76:79], v[132:135], v[188:191], v[76:79]
	v_mfma_f32_16x16x32_bf16 v[160:163], v[128:131], v[168:171], v[160:163]
	v_mfma_f32_16x16x32_bf16 v[156:159], v[136:139], v[168:171], v[156:159]
	v_mfma_f32_16x16x32_bf16 v[112:115], v[128:131], v[176:179], v[112:115]
	v_mfma_f32_16x16x32_bf16 v[108:111], v[136:139], v[176:179], v[108:111]
	v_mfma_f32_16x16x32_bf16 v[96:99], v[128:131], v[184:187], v[96:99]
	v_mfma_f32_16x16x32_bf16 v[92:95], v[136:139], v[184:187], v[92:95]
	v_mfma_f32_16x16x32_bf16 v[80:83], v[128:131], v[204:207], v[80:83]
	v_mfma_f32_16x16x32_bf16 v[76:79], v[136:139], v[204:207], v[76:79]
	v_mfma_f32_16x16x32_bf16 v[124:127], v[140:143], v[164:167], v[124:127]
	v_mfma_f32_16x16x32_bf16 v[120:123], v[148:151], v[164:167], v[120:123]
	v_mfma_f32_16x16x32_bf16 v[104:107], v[140:143], v[172:175], v[104:107]
	v_mfma_f32_16x16x32_bf16 v[100:103], v[148:151], v[172:175], v[100:103]
	v_mfma_f32_16x16x32_bf16 v[88:91], v[140:143], v[180:183], v[88:91]
	v_mfma_f32_16x16x32_bf16 v[84:87], v[148:151], v[180:183], v[84:87]
	v_mfma_f32_16x16x32_bf16 v[72:75], v[140:143], v[188:191], v[72:75]
	v_mfma_f32_16x16x32_bf16 v[68:71], v[148:151], v[188:191], v[68:71]
	v_mfma_f32_16x16x32_bf16 v[124:127], v[144:147], v[168:171], v[124:127]
	v_mfma_f32_16x16x32_bf16 v[120:123], v[152:155], v[168:171], v[120:123]
	v_mfma_f32_16x16x32_bf16 v[104:107], v[144:147], v[176:179], v[104:107]
	v_mfma_f32_16x16x32_bf16 v[100:103], v[152:155], v[176:179], v[100:103]
	v_mfma_f32_16x16x32_bf16 v[88:91], v[144:147], v[184:187], v[88:91]
	v_mfma_f32_16x16x32_bf16 v[84:87], v[152:155], v[184:187], v[84:87]
	v_mfma_f32_16x16x32_bf16 v[72:75], v[144:147], v[204:207], v[72:75]
	v_mfma_f32_16x16x32_bf16 v[68:71], v[152:155], v[204:207], v[68:71]
	s_barrier
	s_mov_b32 m0, s34
	v_lshl_add_u64 v[208:209], s[12:13], 0, v[196:197]
	s_add_u32 s54, s12, 0x20000
	ds_read_b128 v[164:167], v224 offset:16384
	ds_read_b128 v[168:171], v224 offset:17408
	ds_read_b128 v[172:175], v224 offset:18432
	ds_read_b128 v[176:179], v224 offset:19456
	ds_read_b128 v[180:183], v224 offset:20480
	ds_read_b128 v[184:187], v224 offset:21504
	ds_read_b128 v[188:191], v224 offset:22528
	ds_read_b128 v[204:207], v224 offset:23552
	global_load_lds_dwordx4 v[208:209], off
	v_lshl_add_u64 v[210:211], s[12:13], 0, v[192:193]
	s_mov_b32 m0, s35
	s_addc_u32 s55, s13, 0
	global_load_lds_dwordx4 v[210:211], off
	v_lshl_add_u64 v[212:213], s[54:55], 0, v[196:197]
	s_mov_b32 m0, s40
	v_lshl_add_u64 v[214:215], s[16:17], 0, v[194:195]
	global_load_lds_dwordx4 v[212:213], off
	v_lshl_add_u64 v[212:213], s[54:55], 0, v[192:193]
	s_mov_b32 m0, s41
	s_nop 0
	global_load_lds_dwordx4 v[212:213], off
	v_lshl_add_u64 v[212:213], s[16:17], 0, v[198:199]
	s_mov_b32 m0, s31
	s_nop 0
	global_load_lds_dwordx4 v[212:213], off
	s_mov_b32 m0, s42
	s_nop 0
	global_load_lds_dwordx4 v[214:215], off
	s_waitcnt vmcnt(8)
	s_waitcnt lgkmcnt(0)
	s_barrier
; #define PG8_STAGE(bufoff, gbase, voff) do { _Pragma("unroll") for (int _i = 0; _i < 2; ++_i) \
;         __builtin_amdgcn_global_load_lds((const unsigned*)((const char*)(gbase) + (voff)[_i]), (LAS unsigned*)(lds + (bufoff) + ldsw + _i * 8192), 16, 0, 0); } while (0)
; #define PG8_LDA(dst, b, h) do { _Pragma("unroll") for (int m = 0; m < 4; ++m) _Pragma("unroll") for (int k = 0; k < 2; ++k) dst[m][k] = *(const LAS bf16x8*)(pA + PG8_SA(b, h) + m * 2048 + k * 1024); } while (0)
; #define PG8_LDB(dst, b, h) do { _Pragma("unroll") for (int n = 0; n < 2; ++n) _Pragma("unroll") for (int k = 0; k < 2; ++k) dst[n][k] = *(const LAS bf16x8*)(pB + (PG8_SB(b, h) - 4 * HTB) + n * 2048 + k * 1024); } while (0)
; #define PG8_MMA(ai, bj, At, Bt) do { __builtin_amdgcn_s_setprio(1); _Pragma("unroll") for (int m = 0; m < 4; ++m) _Pragma("unroll") for (int n = 0; n < 2; ++n) _Pragma("unroll") for (int k = 0; k < 2; ++k) \
;         acc[ai][bj][m][n] = __builtin_amdgcn_mfma_f32_16x16x32_bf16(Bt[n][k], At[m][k], acc[ai][bj][m][n], 0, 0, 0); __builtin_amdgcn_s_setprio(0); } while (0)
; #define PG8_WAIT_V(n) asm volatile("s_waitcnt vmcnt(" #n ")" ::: "memory")
; #define PG8_WAIT_L(n) asm volatile("s_waitcnt lgkmcnt(" #n ")" ::: "memory")
; #define PG8_BAR __builtin_amdgcn_s_barrier()
; #define PG8_SCHED __builtin_amdgcn_sched_barrier(0)
; template <class Desc, class Epi, bool ALIGN_EPI>
; __device__ __forceinline__ void gemm_phase(LAS unsigned char* lds, const Desc& D, const Epi& E, int G, int c) {
;     ...
;             PG8_WAIT_V(8); PG8_WAIT_L(0); PG8_BAR; PG8_MMA(1, 0, At, B0); PG8_MMA(1, 1, At, B1); PG8_BAR; PG8_SCHED;
;             PG8_LDB(B0, 1, 0); PG8_LDB(B1, 1, 1); PG8_SCHED; PG8_LDA(At, 1, 0); PG8_STAGE(PG8_SA(0, 1), a2 + hstepA, voffA);
;             PG8_WAIT_V(8); PG8_WAIT_L(0); PG8_BAR; PG8_MMA(0, 0, At, B0); PG8_MMA(0, 1, At, B1); PG8_BAR; PG8_SCHED;
	v_mfma_f32_16x16x32_bf16 v[64:67], v[116:119], v[164:167], v[64:67]
	v_mfma_f32_16x16x32_bf16 v[60:63], v[132:135], v[164:167], v[60:63]
	v_mfma_f32_16x16x32_bf16 v[48:51], v[116:119], v[172:175], v[48:51]
	v_mfma_f32_16x16x32_bf16 v[44:47], v[132:135], v[172:175], v[44:47]
	v_mfma_f32_16x16x32_bf16 v[32:35], v[116:119], v[180:183], v[32:35]
	v_mfma_f32_16x16x32_bf16 v[28:31], v[132:135], v[180:183], v[28:31]
	v_mfma_f32_16x16x32_bf16 v[16:19], v[116:119], v[188:191], v[16:19]
	v_mfma_f32_16x16x32_bf16 v[12:15], v[132:135], v[188:191], v[12:15]
	v_mfma_f32_16x16x32_bf16 v[64:67], v[128:131], v[168:171], v[64:67]
	v_mfma_f32_16x16x32_bf16 v[60:63], v[136:139], v[168:171], v[60:63]
	v_mfma_f32_16x16x32_bf16 v[48:51], v[128:131], v[176:179], v[48:51]
	v_mfma_f32_16x16x32_bf16 v[44:47], v[136:139], v[176:179], v[44:47]
	v_mfma_f32_16x16x32_bf16 v[32:35], v[128:131], v[184:187], v[32:35]
	v_mfma_f32_16x16x32_bf16 v[28:31], v[136:139], v[184:187], v[28:31]
	v_mfma_f32_16x16x32_bf16 v[16:19], v[128:131], v[204:207], v[16:19]
	v_mfma_f32_16x16x32_bf16 v[12:15], v[136:139], v[204:207], v[12:15]
	v_mfma_f32_16x16x32_bf16 v[56:59], v[140:143], v[164:167], v[56:59]
	v_mfma_f32_16x16x32_bf16 v[52:55], v[148:151], v[164:167], v[52:55]
	v_mfma_f32_16x16x32_bf16 v[40:43], v[140:143], v[172:175], v[40:43]
	v_mfma_f32_16x16x32_bf16 v[36:39], v[148:151], v[172:175], v[36:39]
	v_mfma_f32_16x16x32_bf16 v[24:27], v[140:143], v[180:183], v[24:27]
	v_mfma_f32_16x16x32_bf16 v[20:23], v[148:151], v[180:183], v[20:23]
	v_mfma_f32_16x16x32_bf16 v[8:11], v[140:143], v[188:191], v[8:11]
	v_mfma_f32_16x16x32_bf16 v[4:7], v[148:151], v[188:191], v[4:7]
	v_mfma_f32_16x16x32_bf16 v[56:59], v[144:147], v[168:171], v[56:59]
	v_mfma_f32_16x16x32_bf16 v[52:55], v[152:155], v[168:171], v[52:55]
	v_mfma_f32_16x16x32_bf16 v[40:43], v[144:147], v[176:179], v[40:43]
	v_mfma_f32_16x16x32_bf16 v[36:39], v[152:155], v[176:179], v[36:39]
	v_mfma_f32_16x16x32_bf16 v[24:27], v[144:147], v[184:187], v[24:27]
	v_mfma_f32_16x16x32_bf16 v[20:23], v[152:155], v[184:187], v[20:23]
	v_mfma_f32_16x16x32_bf16 v[8:11], v[144:147], v[204:207], v[8:11]
	v_mfma_f32_16x16x32_bf16 v[4:7], v[152:155], v[204:207], v[4:7]
	s_barrier
	ds_read_b128 v[116:119], v225 offset:32768
	ds_read_b128 v[128:131], v225 offset:33792
	ds_read_b128 v[132:135], v225 offset:34816
	ds_read_b128 v[136:139], v225 offset:35840
	ds_read_b128 v[140:143], v225 offset:49152
	ds_read_b128 v[144:147], v225 offset:50176
	ds_read_b128 v[148:151], v225 offset:51200
	ds_read_b128 v[152:155], v225 offset:52224
	s_add_u32 s16, s16, 0x20000
	s_addc_u32 s17, s17, 0
	s_mov_b32 m0, s43
	v_lshl_add_u64 v[216:217], s[16:17], 0, v[198:199]
	ds_read_b128 v[164:167], v224 offset:32768
	ds_read_b128 v[168:171], v224 offset:33792
	ds_read_b128 v[172:175], v224 offset:34816
	ds_read_b128 v[176:179], v224 offset:35840
	ds_read_b128 v[180:183], v224 offset:36864
	ds_read_b128 v[184:187], v224 offset:37888
	ds_read_b128 v[188:191], v224 offset:38912
	ds_read_b128 v[204:207], v224 offset:39936
	global_load_lds_dwordx4 v[216:217], off
	v_lshl_add_u64 v[216:217], s[16:17], 0, v[194:195]
	s_mov_b32 m0, s44
	s_nop 0
	global_load_lds_dwordx4 v[216:217], off
	s_waitcnt vmcnt(8)
	s_waitcnt lgkmcnt(0)
	s_barrier
	v_mfma_f32_16x16x32_bf16 v[160:163], v[116:119], v[164:167], v[160:163]
	v_mfma_f32_16x16x32_bf16 v[156:159], v[132:135], v[164:167], v[156:159]
	v_mfma_f32_16x16x32_bf16 v[112:115], v[116:119], v[172:175], v[112:115]
	v_mfma_f32_16x16x32_bf16 v[108:111], v[132:135], v[172:175], v[108:111]
	v_mfma_f32_16x16x32_bf16 v[96:99], v[116:119], v[180:183], v[96:99]
	v_mfma_f32_16x16x32_bf16 v[92:95], v[132:135], v[180:183], v[92:95]
	v_mfma_f32_16x16x32_bf16 v[80:83], v[116:119], v[188:191], v[80:83]
	v_mfma_f32_16x16x32_bf16 v[76:79], v[132:135], v[188:191], v[76:79]
	v_mfma_f32_16x16x32_bf16 v[160:163], v[128:131], v[168:171], v[160:163]
	v_mfma_f32_16x16x32_bf16 v[156:159], v[136:139], v[168:171], v[156:159]
	v_mfma_f32_16x16x32_bf16 v[112:115], v[128:131], v[176:179], v[112:115]
	v_mfma_f32_16x16x32_bf16 v[108:111], v[136:139], v[176:179], v[108:111]
	v_mfma_f32_16x16x32_bf16 v[96:99], v[128:131], v[184:187], v[96:99]
	v_mfma_f32_16x16x32_bf16 v[92:95], v[136:139], v[184:187], v[92:95]
	v_mfma_f32_16x16x32_bf16 v[80:83], v[128:131], v[204:207], v[80:83]
	v_mfma_f32_16x16x32_bf16 v[76:79], v[136:139], v[204:207], v[76:79]
	v_mfma_f32_16x16x32_bf16 v[124:127], v[140:143], v[164:167], v[124:127]
	v_mfma_f32_16x16x32_bf16 v[120:123], v[148:151], v[164:167], v[120:123]
	v_mfma_f32_16x16x32_bf16 v[104:107], v[140:143], v[172:175], v[104:107]
	v_mfma_f32_16x16x32_bf16 v[100:103], v[148:151], v[172:175], v[100:103]
	v_mfma_f32_16x16x32_bf16 v[88:91], v[140:143], v[180:183], v[88:91]
	v_mfma_f32_16x16x32_bf16 v[84:87], v[148:151], v[180:183], v[84:87]
	v_mfma_f32_16x16x32_bf16 v[72:75], v[140:143], v[188:191], v[72:75]
	v_mfma_f32_16x16x32_bf16 v[68:71], v[148:151], v[188:191], v[68:71]
	v_mfma_f32_16x16x32_bf16 v[124:127], v[144:147], v[168:171], v[124:127]
	v_mfma_f32_16x16x32_bf16 v[120:123], v[152:155], v[168:171], v[120:123]
	v_mfma_f32_16x16x32_bf16 v[104:107], v[144:147], v[176:179], v[104:107]
	v_mfma_f32_16x16x32_bf16 v[100:103], v[152:155], v[176:179], v[100:103]
	v_mfma_f32_16x16x32_bf16 v[88:91], v[144:147], v[184:187], v[88:91]
	v_mfma_f32_16x16x32_bf16 v[84:87], v[152:155], v[184:187], v[84:87]
	v_mfma_f32_16x16x32_bf16 v[72:75], v[144:147], v[204:207], v[72:75]
	v_mfma_f32_16x16x32_bf16 v[68:71], v[152:155], v[204:207], v[68:71]
	s_barrier
; #define PG8_STAGE(bufoff, gbase, voff) do { _Pragma("unroll") for (int _i = 0; _i < 2; ++_i) \
;         __builtin_amdgcn_global_load_lds((const unsigned*)((const char*)(gbase) + (voff)[_i]), (LAS unsigned*)(lds + (bufoff) + ldsw + _i * 8192), 16, 0, 0); } while (0)
; #define PG8_LDA(dst, b, h) do { _Pragma("unroll") for (int m = 0; m < 4; ++m) _Pragma("unroll") for (int k = 0; k < 2; ++k) dst[m][k] = *(const LAS bf16x8*)(pA + PG8_SA(b, h) + m * 2048 + k * 1024); } while (0)
; #define PG8_MMA(ai, bj, At, Bt) do { __builtin_amdgcn_s_setprio(1); _Pragma("unroll") for (int m = 0; m < 4; ++m) _Pragma("unroll") for (int n = 0; n < 2; ++n) _Pragma("unroll") for (int k = 0; k < 2; ++k) \
;         acc[ai][bj][m][n] = __builtin_amdgcn_mfma_f32_16x16x32_bf16(Bt[n][k], At[m][k], acc[ai][bj][m][n], 0, 0, 0); __builtin_amdgcn_s_setprio(0); } while (0)
; #define PG8_WAIT_V(n) asm volatile("s_waitcnt vmcnt(" #n ")" ::: "memory")
; #define PG8_WAIT_L(n) asm volatile("s_waitcnt lgkmcnt(" #n ")" ::: "memory")
; #define PG8_BAR __builtin_amdgcn_s_barrier()
; #define PG8_SCHED __builtin_amdgcn_sched_barrier(0)
; template <class Desc, class Epi, bool ALIGN_EPI>
; __device__ __forceinline__ void gemm_phase(LAS unsigned char* lds, const Desc& D, const Epi& E, int G, int c) {
;     ...
;             PG8_LDA(At, 1, 1); PG8_STAGE(PG8_SB(1, 0), b3, voffB); PG8_STAGE(PG8_SB(1, 1), b3 + hstepB, voffB); PG8_STAGE(PG8_SA(1, 0), a3, voffA);
;             PG8_WAIT_V(8); PG8_WAIT_L(0); PG8_BAR; PG8_MMA(1, 0, At, B0); PG8_MMA(1, 1, At, B1); PG8_BAR; PG8_SCHED;
;         }
	s_mov_b32 m0, s45
	v_lshl_add_u64 v[208:209], v[208:209], 0, s[76:77]
	s_add_u32 s12, s12, 0x20080
	ds_read_b128 v[164:167], v224 offset:49152
	ds_read_b128 v[168:171], v224 offset:50176
	ds_read_b128 v[172:175], v224 offset:51200
	ds_read_b128 v[176:179], v224 offset:52224
	ds_read_b128 v[180:183], v224 offset:53248
	ds_read_b128 v[184:187], v224 offset:54272
	ds_read_b128 v[188:191], v224 offset:55296
	ds_read_b128 v[204:207], v224 offset:56320
	global_load_lds_dwordx4 v[208:209], off
	v_lshl_add_u64 v[208:209], v[210:211], 0, s[76:77]
	s_mov_b32 m0, s46
	s_addc_u32 s13, s13, 0
	global_load_lds_dwordx4 v[208:209], off
	v_lshl_add_u64 v[208:209], s[12:13], 0, v[196:197]
	s_mov_b32 m0, s49
	s_nop 0
	global_load_lds_dwordx4 v[208:209], off
	v_lshl_add_u64 v[208:209], s[12:13], 0, v[192:193]
	s_mov_b32 m0, s50
	s_nop 0
	global_load_lds_dwordx4 v[208:209], off
	v_lshl_add_u64 v[208:209], v[212:213], 0, s[76:77]
	s_mov_b32 m0, s47
	s_nop 0
	global_load_lds_dwordx4 v[208:209], off
	v_lshl_add_u64 v[208:209], v[214:215], 0, s[76:77]
	s_mov_b32 m0, s48
	s_nop 0
	global_load_lds_dwordx4 v[208:209], off
	s_waitcnt vmcnt(8)
	s_waitcnt lgkmcnt(0)
	s_barrier
	v_mfma_f32_16x16x32_bf16 v[64:67], v[116:119], v[164:167], v[64:67]
	v_mfma_f32_16x16x32_bf16 v[60:63], v[132:135], v[164:167], v[60:63]
	v_mfma_f32_16x16x32_bf16 v[48:51], v[116:119], v[172:175], v[48:51]
	v_mfma_f32_16x16x32_bf16 v[44:47], v[132:135], v[172:175], v[44:47]
	v_mfma_f32_16x16x32_bf16 v[32:35], v[116:119], v[180:183], v[32:35]
	v_mfma_f32_16x16x32_bf16 v[28:31], v[132:135], v[180:183], v[28:31]
	v_mfma_f32_16x16x32_bf16 v[16:19], v[116:119], v[188:191], v[16:19]
	v_mfma_f32_16x16x32_bf16 v[12:15], v[132:135], v[188:191], v[12:15]
	v_mfma_f32_16x16x32_bf16 v[64:67], v[128:131], v[168:171], v[64:67]
	v_mfma_f32_16x16x32_bf16 v[60:63], v[136:139], v[168:171], v[60:63]
	v_mfma_f32_16x16x32_bf16 v[48:51], v[128:131], v[176:179], v[48:51]
	v_mfma_f32_16x16x32_bf16 v[44:47], v[136:139], v[176:179], v[44:47]
	v_mfma_f32_16x16x32_bf16 v[32:35], v[128:131], v[184:187], v[32:35]
	v_mfma_f32_16x16x32_bf16 v[28:31], v[136:139], v[184:187], v[28:31]
	v_mfma_f32_16x16x32_bf16 v[16:19], v[128:131], v[204:207], v[16:19]
	v_mfma_f32_16x16x32_bf16 v[12:15], v[136:139], v[204:207], v[12:15]
	v_mfma_f32_16x16x32_bf16 v[56:59], v[140:143], v[164:167], v[56:59]
	v_mfma_f32_16x16x32_bf16 v[52:55], v[148:151], v[164:167], v[52:55]
	v_mfma_f32_16x16x32_bf16 v[40:43], v[140:143], v[172:175], v[40:43]
	v_mfma_f32_16x16x32_bf16 v[36:39], v[148:151], v[172:175], v[36:39]
	v_mfma_f32_16x16x32_bf16 v[24:27], v[140:143], v[180:183], v[24:27]
	v_mfma_f32_16x16x32_bf16 v[20:23], v[148:151], v[180:183], v[20:23]
	v_mfma_f32_16x16x32_bf16 v[8:11], v[140:143], v[188:191], v[8:11]
	v_mfma_f32_16x16x32_bf16 v[4:7], v[148:151], v[188:191], v[4:7]
	v_mfma_f32_16x16x32_bf16 v[56:59], v[144:147], v[168:171], v[56:59]
	v_mfma_f32_16x16x32_bf16 v[52:55], v[152:155], v[168:171], v[52:55]
	v_mfma_f32_16x16x32_bf16 v[40:43], v[144:147], v[176:179], v[40:43]
	v_mfma_f32_16x16x32_bf16 v[36:39], v[152:155], v[176:179], v[36:39]
	v_mfma_f32_16x16x32_bf16 v[24:27], v[144:147], v[184:187], v[24:27]
	v_mfma_f32_16x16x32_bf16 v[20:23], v[152:155], v[184:187], v[20:23]
	v_mfma_f32_16x16x32_bf16 v[8:11], v[144:147], v[204:207], v[8:11]
	v_mfma_f32_16x16x32_bf16 v[4:7], v[152:155], v[204:207], v[4:7]
	s_barrier
	s_add_i32 s52, s52, 2
	s_add_u32 s0, s0, 0x100
	s_addc_u32 s1, s1, 0
	s_add_u32 s27, s27, 0x100
	s_addc_u32 s33, s33, 0
	s_cmp_gt_u32 s52, 5
	s_cbranch_scc0 .LBB0_1479
	s_and_b64 vcc, exec, s[8:9]
	s_cbranch_vccz .LBB0_1482
	s_barrier

;     __device__ __forceinline__ int nt(const Unit& u) const { return (u.pn >> 1) < 2 ? 22 : 20; }
; #define PG8_STAGE(bufoff, gbase, voff) do { _Pragma("unroll") for (int _i = 0; _i < 2; ++_i) \
;         __builtin_amdgcn_global_load_lds((const unsigned*)((const char*)(gbase) + (voff)[_i]), (LAS unsigned*)(lds + (bufoff) + ldsw + _i * 8192), 16, 0, 0); } while (0)
; #define PG8_LDA(dst, b, h) do { _Pragma("unroll") for (int m = 0; m < 4; ++m) _Pragma("unroll") for (int k = 0; k < 2; ++k) dst[m][k] = *(const LAS bf16x8*)(pA + PG8_SA(b, h) + m * 2048 + k * 1024); } while (0)
; #define PG8_LDB(dst, b, h) do { _Pragma("unroll") for (int n = 0; n < 2; ++n) _Pragma("unroll") for (int k = 0; k < 2; ++k) dst[n][k] = *(const LAS bf16x8*)(pB + (PG8_SB(b, h) - 4 * HTB) + n * 2048 + k * 1024); } while (0)
; #define PG8_MMA(ai, bj, At, Bt) do { __builtin_amdgcn_s_setprio(1); _Pragma("unroll") for (int m = 0; m < 4; ++m) _Pragma("unroll") for (int n = 0; n < 2; ++n) _Pragma("unroll") for (int k = 0; k < 2; ++k) \
;         acc[ai][bj][m][n] = __builtin_amdgcn_mfma_f32_16x16x32_bf16(Bt[n][k], At[m][k], acc[ai][bj][m][n], 0, 0, 0); __builtin_amdgcn_s_setprio(0); } while (0)
; #define PG8_WAIT_V(n) asm volatile("s_waitcnt vmcnt(" #n ")" ::: "memory")
; #define PG8_WAIT_L(n) asm volatile("s_waitcnt lgkmcnt(" #n ")" ::: "memory")
; template <class Desc, class Epi, bool ALIGN_EPI>
; __device__ __forceinline__ void gemm_phase(LAS unsigned char* lds, const Desc& D, const Epi& E, int G, int c) {
;     ...
;             const bool last = (t == nt - 2);
;             if (last && has_next) PG8_AWAIT(nxt);
;             const char* a1 = cA + (size_t)(t + 1) * kstep;
;             const char* a2 = last ? nA : cA + (size_t)(t + 2) * kstep; const char* b2 = last ? nB : cB + (size_t)(t + 2) * kstep;
;             const char* a3 = a2 + kstep; const char* b3 = b2 + kstep;
;             PG8_LDB(B0, 0, 0); PG8_LDB(B1, 0, 1); PG8_SCHED; PG8_LDA(At, 0, 0); PG8_STAGE(PG8_SA(1, 1), a1 + hstepA, voffA);
;             PG8_WAIT_V(8); PG8_WAIT_L(0); PG8_BAR; PG8_MMA(0, 0, At, B0); PG8_MMA(0, 1, At, B1); PG8_BAR; PG8_SCHED;
;             PG8_LDA(At, 0, 1); PG8_STAGE(PG8_SB(0, 0), b2, voffB); PG8_STAGE(PG8_SB(0, 1), b2 + hstepB, voffB); PG8_STAGE(PG8_SA(0, 0), a2, voffA);
;             PG8_WAIT_V(8); PG8_WAIT_L(0); PG8_BAR; PG8_MMA(1, 0, At, B0); PG8_MMA(1, 1, At, B1); PG8_BAR; PG8_SCHED;
.LBB0_1517:
	ds_read_b128 v[116:119], v225
	ds_read_b128 v[128:131], v225 offset:1024
	ds_read_b128 v[132:135], v225 offset:2048
	ds_read_b128 v[136:139], v225 offset:3072
	ds_read_b128 v[140:143], v225 offset:16384
	ds_read_b128 v[144:147], v225 offset:17408
	ds_read_b128 v[148:151], v225 offset:18432
	ds_read_b128 v[152:155], v225 offset:19456
	s_add_u32 s12, s0, 0xfffe0080
	s_addc_u32 s13, s1, -1
	s_cmp_eq_u32 s54, 4
	s_cselect_b32 s17, s37, s13
	s_cselect_b32 s16, s36, s12
	s_cselect_b32 s13, s21, s33
	s_cselect_b32 s12, s24, s27
	v_lshl_add_u64 v[208:209], s[0:1], 0, v[200:201]
	s_add_i32 m0, s31, 0xc000
	ds_read_b128 v[164:167], v224
	ds_read_b128 v[168:171], v224 offset:1024
	ds_read_b128 v[172:175], v224 offset:2048
	ds_read_b128 v[176:179], v224 offset:3072
	ds_read_b128 v[180:183], v224 offset:4096
	ds_read_b128 v[184:187], v224 offset:5120
	ds_read_b128 v[188:191], v224 offset:6144
	ds_read_b128 v[204:207], v224 offset:7168
	global_load_lds_dwordx4 v[208:209], off
	v_lshl_add_u64 v[208:209], s[0:1], 0, v[202:203]
	s_add_i32 m0, s31, 0xe000
	s_nop 0
	global_load_lds_dwordx4 v[208:209], off
	s_waitcnt vmcnt(8)
	s_waitcnt lgkmcnt(0)
	s_barrier
	v_mfma_f32_16x16x32_bf16 v[160:163], v[116:119], v[164:167], v[160:163]
	v_mfma_f32_16x16x32_bf16 v[156:159], v[132:135], v[164:167], v[156:159]
	v_mfma_f32_16x16x32_bf16 v[112:115], v[116:119], v[172:175], v[112:115]
	v_mfma_f32_16x16x32_bf16 v[108:111], v[132:135], v[172:175], v[108:111]
	v_mfma_f32_16x16x32_bf16 v[96:99], v[116:119], v[180:183], v[96:99]
	v_mfma_f32_16x16x32_bf16 v[92:95], v[132:135], v[180:183], v[92:95]
	v_mfma_f32_16x16x32_bf16 v[80:83], v[116:119], v[188:191], v[80:83]
	v_mfma_f32_16x16x32_bf16 v[76:79], v[132:135], v[188:191], v[76:79]
	v_mfma_f32_16x16x32_bf16 v[160:163], v[128:131], v[168:171], v[160:163]
	v_mfma_f32_16x16x32_bf16 v[156:159], v[136:139], v[168:171], v[156:159]
	v_mfma_f32_16x16x32_bf16 v[112:115], v[128:131], v[176:179], v[112:115]
	v_mfma_f32_16x16x32_bf16 v[108:111], v[136:139], v[176:179], v[108:111]
	v_mfma_f32_16x16x32_bf16 v[96:99], v[128:131], v[184:187], v[96:99]
	v_mfma_f32_16x16x32_bf16 v[92:95], v[136:139], v[184:187], v[92:95]
	v_mfma_f32_16x16x32_bf16 v[80:83], v[128:131], v[204:207], v[80:83]
	v_mfma_f32_16x16x32_bf16 v[76:79], v[136:139], v[204:207], v[76:79]
	v_mfma_f32_16x16x32_bf16 v[124:127], v[140:143], v[164:167], v[124:127]
	v_mfma_f32_16x16x32_bf16 v[120:123], v[148:151], v[164:167], v[120:123]
	v_mfma_f32_16x16x32_bf16 v[104:107], v[140:143], v[172:175], v[104:107]
	v_mfma_f32_16x16x32_bf16 v[100:103], v[148:151], v[172:175], v[100:103]
	v_mfma_f32_16x16x32_bf16 v[88:91], v[140:143], v[180:183], v[88:91]
	v_mfma_f32_16x16x32_bf16 v[84:87], v[148:151], v[180:183], v[84:87]
	v_mfma_f32_16x16x32_bf16 v[72:75], v[140:143], v[188:191], v[72:75]
	v_mfma_f32_16x16x32_bf16 v[68:71], v[148:151], v[188:191], v[68:71]
	v_mfma_f32_16x16x32_bf16 v[124:127], v[144:147], v[168:171], v[124:127]
	v_mfma_f32_16x16x32_bf16 v[120:123], v[152:155], v[168:171], v[120:123]
	v_mfma_f32_16x16x32_bf16 v[104:107], v[144:147], v[176:179], v[104:107]
	v_mfma_f32_16x16x32_bf16 v[100:103], v[152:155], v[176:179], v[100:103]
	v_mfma_f32_16x16x32_bf16 v[88:91], v[144:147], v[184:187], v[88:91]
	v_mfma_f32_16x16x32_bf16 v[84:87], v[152:155], v[184:187], v[84:87]
	v_mfma_f32_16x16x32_bf16 v[72:75], v[144:147], v[204:207], v[72:75]
	v_mfma_f32_16x16x32_bf16 v[68:71], v[152:155], v[204:207], v[68:71]
	s_barrier
	s_mov_b32 m0, s34
	v_lshl_add_u64 v[208:209], s[12:13], 0, v[196:197]
	s_add_u32 s56, s12, 0x20000
	ds_read_b128 v[164:167], v224 offset:16384
	ds_read_b128 v[168:171], v224 offset:17408
	ds_read_b128 v[172:175], v224 offset:18432
	ds_read_b128 v[176:179], v224 offset:19456
	ds_read_b128 v[180:183], v224 offset:20480
	ds_read_b128 v[184:187], v224 offset:21504
	ds_read_b128 v[188:191], v224 offset:22528
	ds_read_b128 v[204:207], v224 offset:23552
	global_load_lds_dwordx4 v[208:209], off
	v_lshl_add_u64 v[210:211], s[12:13], 0, v[192:193]
	s_mov_b32 m0, s35
	s_addc_u32 s57, s13, 0
	global_load_lds_dwordx4 v[210:211], off
	v_lshl_add_u64 v[212:213], s[56:57], 0, v[196:197]
	s_mov_b32 m0, s42
	v_lshl_add_u64 v[214:215], s[16:17], 0, v[194:195]
	global_load_lds_dwordx4 v[212:213], off
	v_lshl_add_u64 v[212:213], s[56:57], 0, v[192:193]
	s_mov_b32 m0, s43
	s_nop 0
	global_load_lds_dwordx4 v[212:213], off
	v_lshl_add_u64 v[212:213], s[16:17], 0, v[198:199]
	s_mov_b32 m0, s31
	s_nop 0
	global_load_lds_dwordx4 v[212:213], off
	s_mov_b32 m0, s44
	s_nop 0
	global_load_lds_dwordx4 v[214:215], off
	s_waitcnt vmcnt(8)
	s_waitcnt lgkmcnt(0)
	s_barrier
; #define PG8_STAGE(bufoff, gbase, voff) do { _Pragma("unroll") for (int _i = 0; _i < 2; ++_i) \
;         __builtin_amdgcn_global_load_lds((const unsigned*)((const char*)(gbase) + (voff)[_i]), (LAS unsigned*)(lds + (bufoff) + ldsw + _i * 8192), 16, 0, 0); } while (0)
; #define PG8_LDA(dst, b, h) do { _Pragma("unroll") for (int m = 0; m < 4; ++m) _Pragma("unroll") for (int k = 0; k < 2; ++k) dst[m][k] = *(const LAS bf16x8*)(pA + PG8_SA(b, h) + m * 2048 + k * 1024); } while (0)
; #define PG8_LDB(dst, b, h) do { _Pragma("unroll") for (int n = 0; n < 2; ++n) _Pragma("unroll") for (int k = 0; k < 2; ++k) dst[n][k] = *(const LAS bf16x8*)(pB + (PG8_SB(b, h) - 4 * HTB) + n * 2048 + k * 1024); } while (0)
; #define PG8_MMA(ai, bj, At, Bt) do { __builtin_amdgcn_s_setprio(1); _Pragma("unroll") for (int m = 0; m < 4; ++m) _Pragma("unroll") for (int n = 0; n < 2; ++n) _Pragma("unroll") for (int k = 0; k < 2; ++k) \
;         acc[ai][bj][m][n] = __builtin_amdgcn_mfma_f32_16x16x32_bf16(Bt[n][k], At[m][k], acc[ai][bj][m][n], 0, 0, 0); __builtin_amdgcn_s_setprio(0); } while (0)
; #define PG8_WAIT_V(n) asm volatile("s_waitcnt vmcnt(" #n ")" ::: "memory")
; #define PG8_WAIT_L(n) asm volatile("s_waitcnt lgkmcnt(" #n ")" ::: "memory")
; #define PG8_BAR __builtin_amdgcn_s_barrier()
; #define PG8_SCHED __builtin_amdgcn_sched_barrier(0)
; template <class Desc, class Epi, bool ALIGN_EPI>
; __device__ __forceinline__ void gemm_phase(LAS unsigned char* lds, const Desc& D, const Epi& E, int G, int c) {
;     ...
;             PG8_WAIT_V(8); PG8_WAIT_L(0); PG8_BAR; PG8_MMA(1, 0, At, B0); PG8_MMA(1, 1, At, B1); PG8_BAR; PG8_SCHED;
;             PG8_LDB(B0, 1, 0); PG8_LDB(B1, 1, 1); PG8_SCHED; PG8_LDA(At, 1, 0); PG8_STAGE(PG8_SA(0, 1), a2 + hstepA, voffA);
;             PG8_WAIT_V(8); PG8_WAIT_L(0); PG8_BAR; PG8_MMA(0, 0, At, B0); PG8_MMA(0, 1, At, B1); PG8_BAR; PG8_SCHED;
	v_mfma_f32_16x16x32_bf16 v[64:67], v[116:119], v[164:167], v[64:67]
	v_mfma_f32_16x16x32_bf16 v[60:63], v[132:135], v[164:167], v[60:63]
	v_mfma_f32_16x16x32_bf16 v[48:51], v[116:119], v[172:175], v[48:51]
	v_mfma_f32_16x16x32_bf16 v[44:47], v[132:135], v[172:175], v[44:47]
	v_mfma_f32_16x16x32_bf16 v[32:35], v[116:119], v[180:183], v[32:35]
	v_mfma_f32_16x16x32_bf16 v[28:31], v[132:135], v[180:183], v[28:31]
	v_mfma_f32_16x16x32_bf16 v[16:19], v[116:119], v[188:191], v[16:19]
	v_mfma_f32_16x16x32_bf16 v[12:15], v[132:135], v[188:191], v[12:15]
	v_mfma_f32_16x16x32_bf16 v[64:67], v[128:131], v[168:171], v[64:67]
	v_mfma_f32_16x16x32_bf16 v[60:63], v[136:139], v[168:171], v[60:63]
	v_mfma_f32_16x16x32_bf16 v[48:51], v[128:131], v[176:179], v[48:51]
	v_mfma_f32_16x16x32_bf16 v[44:47], v[136:139], v[176:179], v[44:47]
	v_mfma_f32_16x16x32_bf16 v[32:35], v[128:131], v[184:187], v[32:35]
	v_mfma_f32_16x16x32_bf16 v[28:31], v[136:139], v[184:187], v[28:31]
	v_mfma_f32_16x16x32_bf16 v[16:19], v[128:131], v[204:207], v[16:19]
	v_mfma_f32_16x16x32_bf16 v[12:15], v[136:139], v[204:207], v[12:15]
	v_mfma_f32_16x16x32_bf16 v[56:59], v[140:143], v[164:167], v[56:59]
	v_mfma_f32_16x16x32_bf16 v[52:55], v[148:151], v[164:167], v[52:55]
	v_mfma_f32_16x16x32_bf16 v[40:43], v[140:143], v[172:175], v[40:43]
	v_mfma_f32_16x16x32_bf16 v[36:39], v[148:151], v[172:175], v[36:39]
	v_mfma_f32_16x16x32_bf16 v[24:27], v[140:143], v[180:183], v[24:27]
	v_mfma_f32_16x16x32_bf16 v[20:23], v[148:151], v[180:183], v[20:23]
	v_mfma_f32_16x16x32_bf16 v[8:11], v[140:143], v[188:191], v[8:11]
	v_mfma_f32_16x16x32_bf16 v[4:7], v[148:151], v[188:191], v[4:7]
	v_mfma_f32_16x16x32_bf16 v[56:59], v[144:147], v[168:171], v[56:59]
	v_mfma_f32_16x16x32_bf16 v[52:55], v[152:155], v[168:171], v[52:55]
	v_mfma_f32_16x16x32_bf16 v[40:43], v[144:147], v[176:179], v[40:43]
	v_mfma_f32_16x16x32_bf16 v[36:39], v[152:155], v[176:179], v[36:39]
	v_mfma_f32_16x16x32_bf16 v[24:27], v[144:147], v[184:187], v[24:27]
	v_mfma_f32_16x16x32_bf16 v[20:23], v[152:155], v[184:187], v[20:23]
	v_mfma_f32_16x16x32_bf16 v[8:11], v[144:147], v[204:207], v[8:11]
	v_mfma_f32_16x16x32_bf16 v[4:7], v[152:155], v[204:207], v[4:7]
	s_barrier
	ds_read_b128 v[116:119], v225 offset:32768
	ds_read_b128 v[128:131], v225 offset:33792
	ds_read_b128 v[132:135], v225 offset:34816
	ds_read_b128 v[136:139], v225 offset:35840
	ds_read_b128 v[140:143], v225 offset:49152
	ds_read_b128 v[144:147], v225 offset:50176
	ds_read_b128 v[148:151], v225 offset:51200
	ds_read_b128 v[152:155], v225 offset:52224
	s_add_u32 s16, s16, 0x20000
	s_addc_u32 s17, s17, 0
	s_mov_b32 m0, s45
	v_lshl_add_u64 v[216:217], s[16:17], 0, v[198:199]
	ds_read_b128 v[164:167], v224 offset:32768
	ds_read_b128 v[168:171], v224 offset:33792
	ds_read_b128 v[172:175], v224 offset:34816
	ds_read_b128 v[176:179], v224 offset:35840
	ds_read_b128 v[180:183], v224 offset:36864
	ds_read_b128 v[184:187], v224 offset:37888
	ds_read_b128 v[188:191], v224 offset:38912
	ds_read_b128 v[204:207], v224 offset:39936
	global_load_lds_dwordx4 v[216:217], off
	v_lshl_add_u64 v[216:217], s[16:17], 0, v[194:195]
	s_mov_b32 m0, s46
	s_nop 0
	global_load_lds_dwordx4 v[216:217], off
	s_waitcnt vmcnt(8)
	s_waitcnt lgkmcnt(0)
	s_barrier
	v_mfma_f32_16x16x32_bf16 v[160:163], v[116:119], v[164:167], v[160:163]
	v_mfma_f32_16x16x32_bf16 v[156:159], v[132:135], v[164:167], v[156:159]
	v_mfma_f32_16x16x32_bf16 v[112:115], v[116:119], v[172:175], v[112:115]
	v_mfma_f32_16x16x32_bf16 v[108:111], v[132:135], v[172:175], v[108:111]
	v_mfma_f32_16x16x32_bf16 v[96:99], v[116:119], v[180:183], v[96:99]
	v_mfma_f32_16x16x32_bf16 v[92:95], v[132:135], v[180:183], v[92:95]
	v_mfma_f32_16x16x32_bf16 v[80:83], v[116:119], v[188:191], v[80:83]
	v_mfma_f32_16x16x32_bf16 v[76:79], v[132:135], v[188:191], v[76:79]
	v_mfma_f32_16x16x32_bf16 v[160:163], v[128:131], v[168:171], v[160:163]
	v_mfma_f32_16x16x32_bf16 v[156:159], v[136:139], v[168:171], v[156:159]
	v_mfma_f32_16x16x32_bf16 v[112:115], v[128:131], v[176:179], v[112:115]
	v_mfma_f32_16x16x32_bf16 v[108:111], v[136:139], v[176:179], v[108:111]
	v_mfma_f32_16x16x32_bf16 v[96:99], v[128:131], v[184:187], v[96:99]
	v_mfma_f32_16x16x32_bf16 v[92:95], v[136:139], v[184:187], v[92:95]
	v_mfma_f32_16x16x32_bf16 v[80:83], v[128:131], v[204:207], v[80:83]
	v_mfma_f32_16x16x32_bf16 v[76:79], v[136:139], v[204:207], v[76:79]
	v_mfma_f32_16x16x32_bf16 v[124:127], v[140:143], v[164:167], v[124:127]
	v_mfma_f32_16x16x32_bf16 v[120:123], v[148:151], v[164:167], v[120:123]
	v_mfma_f32_16x16x32_bf16 v[104:107], v[140:143], v[172:175], v[104:107]
	v_mfma_f32_16x16x32_bf16 v[100:103], v[148:151], v[172:175], v[100:103]
	v_mfma_f32_16x16x32_bf16 v[88:91], v[140:143], v[180:183], v[88:91]
	v_mfma_f32_16x16x32_bf16 v[84:87], v[148:151], v[180:183], v[84:87]
	v_mfma_f32_16x16x32_bf16 v[72:75], v[140:143], v[188:191], v[72:75]
	v_mfma_f32_16x16x32_bf16 v[68:71], v[148:151], v[188:191], v[68:71]
	v_mfma_f32_16x16x32_bf16 v[124:127], v[144:147], v[168:171], v[124:127]
	v_mfma_f32_16x16x32_bf16 v[120:123], v[152:155], v[168:171], v[120:123]
	v_mfma_f32_16x16x32_bf16 v[104:107], v[144:147], v[176:179], v[104:107]
	v_mfma_f32_16x16x32_bf16 v[100:103], v[152:155], v[176:179], v[100:103]
	v_mfma_f32_16x16x32_bf16 v[88:91], v[144:147], v[184:187], v[88:91]
	v_mfma_f32_16x16x32_bf16 v[84:87], v[152:155], v[184:187], v[84:87]
	v_mfma_f32_16x16x32_bf16 v[72:75], v[144:147], v[204:207], v[72:75]
	v_mfma_f32_16x16x32_bf16 v[68:71], v[152:155], v[204:207], v[68:71]
	s_barrier
; #define PG8_STAGE(bufoff, gbase, voff) do { _Pragma("unroll") for (int _i = 0; _i < 2; ++_i) \
;         __builtin_amdgcn_global_load_lds((const unsigned*)((const char*)(gbase) + (voff)[_i]), (LAS unsigned*)(lds + (bufoff) + ldsw + _i * 8192), 16, 0, 0); } while (0)
; #define PG8_LDA(dst, b, h) do { _Pragma("unroll") for (int m = 0; m < 4; ++m) _Pragma("unroll") for (int k = 0; k < 2; ++k) dst[m][k] = *(const LAS bf16x8*)(pA + PG8_SA(b, h) + m * 2048 + k * 1024); } while (0)
; #define PG8_MMA(ai, bj, At, Bt) do { __builtin_amdgcn_s_setprio(1); _Pragma("unroll") for (int m = 0; m < 4; ++m) _Pragma("unroll") for (int n = 0; n < 2; ++n) _Pragma("unroll") for (int k = 0; k < 2; ++k) \
;         acc[ai][bj][m][n] = __builtin_amdgcn_mfma_f32_16x16x32_bf16(Bt[n][k], At[m][k], acc[ai][bj][m][n], 0, 0, 0); __builtin_amdgcn_s_setprio(0); } while (0)
; #define PG8_WAIT_V(n) asm volatile("s_waitcnt vmcnt(" #n ")" ::: "memory")
; #define PG8_WAIT_L(n) asm volatile("s_waitcnt lgkmcnt(" #n ")" ::: "memory")
; #define PG8_BAR __builtin_amdgcn_s_barrier()
; #define PG8_SCHED __builtin_amdgcn_sched_barrier(0)
; template <class Desc, class Epi, bool ALIGN_EPI>
; __device__ __forceinline__ void gemm_phase(LAS unsigned char* lds, const Desc& D, const Epi& E, int G, int c) {
;     ...
;             PG8_LDA(At, 1, 1); PG8_STAGE(PG8_SB(1, 0), b3, voffB); PG8_STAGE(PG8_SB(1, 1), b3 + hstepB, voffB); PG8_STAGE(PG8_SA(1, 0), a3, voffA);
;             PG8_WAIT_V(8); PG8_WAIT_L(0); PG8_BAR; PG8_MMA(1, 0, At, B0); PG8_MMA(1, 1, At, B1); PG8_BAR; PG8_SCHED;
;         }
	s_mov_b32 m0, s47
	v_lshl_add_u64 v[208:209], v[208:209], 0, s[76:77]
	s_add_u32 s12, s12, 0x20080
	ds_read_b128 v[164:167], v224 offset:49152
	ds_read_b128 v[168:171], v224 offset:50176
	ds_read_b128 v[172:175], v224 offset:51200
	ds_read_b128 v[176:179], v224 offset:52224
	ds_read_b128 v[180:183], v224 offset:53248
	ds_read_b128 v[184:187], v224 offset:54272
	ds_read_b128 v[188:191], v224 offset:55296
	ds_read_b128 v[204:207], v224 offset:56320
	global_load_lds_dwordx4 v[208:209], off
	v_lshl_add_u64 v[208:209], v[210:211], 0, s[76:77]
	s_mov_b32 m0, s48
	s_addc_u32 s13, s13, 0
	global_load_lds_dwordx4 v[208:209], off
	v_lshl_add_u64 v[208:209], s[12:13], 0, v[196:197]
	s_mov_b32 m0, s51
	s_nop 0
	global_load_lds_dwordx4 v[208:209], off
	v_lshl_add_u64 v[208:209], s[12:13], 0, v[192:193]
	s_mov_b32 m0, s52
	s_nop 0
	global_load_lds_dwordx4 v[208:209], off
	v_lshl_add_u64 v[208:209], v[212:213], 0, s[76:77]
	s_mov_b32 m0, s49
	s_nop 0
	global_load_lds_dwordx4 v[208:209], off
	v_lshl_add_u64 v[208:209], v[214:215], 0, s[76:77]
	s_mov_b32 m0, s50
	s_nop 0
	global_load_lds_dwordx4 v[208:209], off
	s_waitcnt vmcnt(8)
	s_waitcnt lgkmcnt(0)
	s_barrier
	v_mfma_f32_16x16x32_bf16 v[64:67], v[116:119], v[164:167], v[64:67]
	v_mfma_f32_16x16x32_bf16 v[60:63], v[132:135], v[164:167], v[60:63]
	v_mfma_f32_16x16x32_bf16 v[48:51], v[116:119], v[172:175], v[48:51]
	v_mfma_f32_16x16x32_bf16 v[44:47], v[132:135], v[172:175], v[44:47]
	v_mfma_f32_16x16x32_bf16 v[32:35], v[116:119], v[180:183], v[32:35]
	v_mfma_f32_16x16x32_bf16 v[28:31], v[132:135], v[180:183], v[28:31]
	v_mfma_f32_16x16x32_bf16 v[16:19], v[116:119], v[188:191], v[16:19]
	v_mfma_f32_16x16x32_bf16 v[12:15], v[132:135], v[188:191], v[12:15]
	v_mfma_f32_16x16x32_bf16 v[64:67], v[128:131], v[168:171], v[64:67]
	v_mfma_f32_16x16x32_bf16 v[60:63], v[136:139], v[168:171], v[60:63]
	v_mfma_f32_16x16x32_bf16 v[48:51], v[128:131], v[176:179], v[48:51]
	v_mfma_f32_16x16x32_bf16 v[44:47], v[136:139], v[176:179], v[44:47]
	v_mfma_f32_16x16x32_bf16 v[32:35], v[128:131], v[184:187], v[32:35]
	v_mfma_f32_16x16x32_bf16 v[28:31], v[136:139], v[184:187], v[28:31]
	v_mfma_f32_16x16x32_bf16 v[16:19], v[128:131], v[204:207], v[16:19]
	v_mfma_f32_16x16x32_bf16 v[12:15], v[136:139], v[204:207], v[12:15]
	v_mfma_f32_16x16x32_bf16 v[56:59], v[140:143], v[164:167], v[56:59]
	v_mfma_f32_16x16x32_bf16 v[52:55], v[148:151], v[164:167], v[52:55]
	v_mfma_f32_16x16x32_bf16 v[40:43], v[140:143], v[172:175], v[40:43]
	v_mfma_f32_16x16x32_bf16 v[36:39], v[148:151], v[172:175], v[36:39]
	v_mfma_f32_16x16x32_bf16 v[24:27], v[140:143], v[180:183], v[24:27]
	v_mfma_f32_16x16x32_bf16 v[20:23], v[148:151], v[180:183], v[20:23]
	v_mfma_f32_16x16x32_bf16 v[8:11], v[140:143], v[188:191], v[8:11]
	v_mfma_f32_16x16x32_bf16 v[4:7], v[148:151], v[188:191], v[4:7]
	v_mfma_f32_16x16x32_bf16 v[56:59], v[144:147], v[168:171], v[56:59]
	v_mfma_f32_16x16x32_bf16 v[52:55], v[152:155], v[168:171], v[52:55]
	v_mfma_f32_16x16x32_bf16 v[40:43], v[144:147], v[176:179], v[40:43]
	v_mfma_f32_16x16x32_bf16 v[36:39], v[152:155], v[176:179], v[36:39]
	v_mfma_f32_16x16x32_bf16 v[24:27], v[144:147], v[184:187], v[24:27]
	v_mfma_f32_16x16x32_bf16 v[20:23], v[152:155], v[184:187], v[20:23]
	v_mfma_f32_16x16x32_bf16 v[8:11], v[144:147], v[204:207], v[8:11]
	v_mfma_f32_16x16x32_bf16 v[4:7], v[152:155], v[204:207], v[4:7]
	s_barrier
	s_add_i32 s54, s54, 2
	s_add_u32 s0, s0, 0x100
	s_addc_u32 s1, s1, 0
	s_add_u32 s27, s27, 0x100
	s_addc_u32 s33, s33, 0
	s_cmp_gt_u32 s54, 5
	s_cbranch_scc0 .LBB0_1517
	s_and_b64 vcc, exec, s[10:11]
	s_cbranch_vccz .LBB0_1520
	s_barrier

;     __device__ __forceinline__ int nt(const Unit& u) const { return (u.pn >> 1) < 2 ? 22 : 20; }
; #define PG8_STAGE(bufoff, gbase, voff) do { _Pragma("unroll") for (int _i = 0; _i < 2; ++_i) \
;         __builtin_amdgcn_global_load_lds((const unsigned*)((const char*)(gbase) + (voff)[_i]), (LAS unsigned*)(lds + (bufoff) + ldsw + _i * 8192), 16, 0, 0); } while (0)
; #define PG8_LDA(dst, b, h) do { _Pragma("unroll") for (int m = 0; m < 4; ++m) _Pragma("unroll") for (int k = 0; k < 2; ++k) dst[m][k] = *(const LAS bf16x8*)(pA + PG8_SA(b, h) + m * 2048 + k * 1024); } while (0)
; #define PG8_LDB(dst, b, h) do { _Pragma("unroll") for (int n = 0; n < 2; ++n) _Pragma("unroll") for (int k = 0; k < 2; ++k) dst[n][k] = *(const LAS bf16x8*)(pB + (PG8_SB(b, h) - 4 * HTB) + n * 2048 + k * 1024); } while (0)
; #define PG8_MMA(ai, bj, At, Bt) do { __builtin_amdgcn_s_setprio(1); _Pragma("unroll") for (int m = 0; m < 4; ++m) _Pragma("unroll") for (int n = 0; n < 2; ++n) _Pragma("unroll") for (int k = 0; k < 2; ++k) \
;         acc[ai][bj][m][n] = __builtin_amdgcn_mfma_f32_16x16x32_bf16(Bt[n][k], At[m][k], acc[ai][bj][m][n], 0, 0, 0); __builtin_amdgcn_s_setprio(0); } while (0)
; #define PG8_WAIT_V(n) asm volatile("s_waitcnt vmcnt(" #n ")" ::: "memory")
; #define PG8_WAIT_L(n) asm volatile("s_waitcnt lgkmcnt(" #n ")" ::: "memory")
; template <class Desc, class Epi, bool ALIGN_EPI>
; __device__ __forceinline__ void gemm_phase(LAS unsigned char* lds, const Desc& D, const Epi& E, int G, int c) {
;     ...
;             const bool last = (t == nt - 2);
;             if (last && has_next) PG8_AWAIT(nxt);
;             const char* a1 = cA + (size_t)(t + 1) * kstep;
;             const char* a2 = last ? nA : cA + (size_t)(t + 2) * kstep; const char* b2 = last ? nB : cB + (size_t)(t + 2) * kstep;
;             const char* a3 = a2 + kstep; const char* b3 = b2 + kstep;
;             PG8_LDB(B0, 0, 0); PG8_LDB(B1, 0, 1); PG8_SCHED; PG8_LDA(At, 0, 0); PG8_STAGE(PG8_SA(1, 1), a1 + hstepA, voffA);
;             PG8_WAIT_V(8); PG8_WAIT_L(0); PG8_BAR; PG8_MMA(0, 0, At, B0); PG8_MMA(0, 1, At, B1); PG8_BAR; PG8_SCHED;
;             PG8_LDA(At, 0, 1); PG8_STAGE(PG8_SB(0, 0), b2, voffB); PG8_STAGE(PG8_SB(0, 1), b2 + hstepB, voffB); PG8_STAGE(PG8_SA(0, 0), a2, voffA);
;             PG8_WAIT_V(8); PG8_WAIT_L(0); PG8_BAR; PG8_MMA(1, 0, At, B0); PG8_MMA(1, 1, At, B1); PG8_BAR; PG8_SCHED;
.LBB0_1580:
	s_or_b32 s14, s30, 1
	s_add_i32 s30, s30, 2
	s_mov_b32 s31, s15
	s_lshl_b64 s[72:73], s[14:15], 7
	s_lshl_b64 s[74:75], s[30:31], 7
	s_add_u32 s14, s18, s74
	ds_read_b128 v[140:143], v163
	ds_read_b128 v[144:147], v163 offset:1024
	ds_read_b128 v[148:151], v163 offset:2048
	ds_read_b128 v[152:155], v163 offset:3072
	ds_read_b128 v[156:159], v163 offset:16384
	ds_read_b128 v[166:169], v163 offset:17408
	ds_read_b128 v[170:173], v163 offset:18432
	ds_read_b128 v[174:177], v163 offset:19456
	s_addc_u32 s31, s19, s75
	s_and_b64 s[46:47], s[34:35], exec
	s_cselect_b32 s47, s43, s31
	s_cselect_b32 s46, s42, s14
	s_add_u32 s14, s20, s74
	s_addc_u32 s31, s21, s75
	s_and_b64 s[34:35], s[34:35], exec
	s_cselect_b32 s35, s3, s31
	s_cselect_b32 s34, s13, s14
	s_add_u32 s14, s18, s72
	s_addc_u32 s31, s19, s73
	s_add_u32 s72, s14, 0x100000
	s_addc_u32 s73, s31, 0
	s_add_i32 m0, s52, 0xc000
	ds_read_b128 v[178:181], v162
	ds_read_b128 v[182:185], v162 offset:1024
	ds_read_b128 v[186:189], v162 offset:2048
	ds_read_b128 v[190:193], v162 offset:3072
	ds_read_b128 v[194:197], v162 offset:4096
	ds_read_b128 v[198:201], v162 offset:5120
	ds_read_b128 v[202:205], v162 offset:6144
	ds_read_b128 v[206:209], v162 offset:7168
	global_load_lds_dwordx4 v132, s[72:73]
	s_add_i32 m0, s52, 0xe000
	s_nop 0
	global_load_lds_dwordx4 v136, s[72:73]
	s_waitcnt vmcnt(8)
	s_waitcnt lgkmcnt(0)
	s_barrier
	v_mfma_f32_16x16x32_bf16 v[128:131], v[140:143], v[178:181], v[128:131]
	v_mfma_f32_16x16x32_bf16 v[124:127], v[148:151], v[178:181], v[124:127]
	v_mfma_f32_16x16x32_bf16 v[120:123], v[140:143], v[186:189], v[120:123]
	v_mfma_f32_16x16x32_bf16 v[116:119], v[148:151], v[186:189], v[116:119]
	v_mfma_f32_16x16x32_bf16 v[112:115], v[140:143], v[194:197], v[112:115]
	v_mfma_f32_16x16x32_bf16 v[108:111], v[148:151], v[194:197], v[108:111]
	v_mfma_f32_16x16x32_bf16 v[104:107], v[140:143], v[202:205], v[104:107]
	v_mfma_f32_16x16x32_bf16 v[100:103], v[148:151], v[202:205], v[100:103]
	v_mfma_f32_16x16x32_bf16 v[128:131], v[144:147], v[182:185], v[128:131]
	v_mfma_f32_16x16x32_bf16 v[124:127], v[152:155], v[182:185], v[124:127]
	v_mfma_f32_16x16x32_bf16 v[120:123], v[144:147], v[190:193], v[120:123]
	v_mfma_f32_16x16x32_bf16 v[116:119], v[152:155], v[190:193], v[116:119]
	v_mfma_f32_16x16x32_bf16 v[112:115], v[144:147], v[198:201], v[112:115]
	v_mfma_f32_16x16x32_bf16 v[108:111], v[152:155], v[198:201], v[108:111]
	v_mfma_f32_16x16x32_bf16 v[104:107], v[144:147], v[206:209], v[104:107]
	v_mfma_f32_16x16x32_bf16 v[100:103], v[152:155], v[206:209], v[100:103]
	v_mfma_f32_16x16x32_bf16 v[96:99], v[156:159], v[178:181], v[96:99]
	v_mfma_f32_16x16x32_bf16 v[92:95], v[170:173], v[178:181], v[92:95]
	v_mfma_f32_16x16x32_bf16 v[88:91], v[156:159], v[186:189], v[88:91]
	v_mfma_f32_16x16x32_bf16 v[84:87], v[170:173], v[186:189], v[84:87]
	v_mfma_f32_16x16x32_bf16 v[80:83], v[156:159], v[194:197], v[80:83]
	v_mfma_f32_16x16x32_bf16 v[76:79], v[170:173], v[194:197], v[76:79]
	v_mfma_f32_16x16x32_bf16 v[72:75], v[156:159], v[202:205], v[72:75]
	v_mfma_f32_16x16x32_bf16 v[68:71], v[170:173], v[202:205], v[68:71]
	v_mfma_f32_16x16x32_bf16 v[96:99], v[166:169], v[182:185], v[96:99]
	v_mfma_f32_16x16x32_bf16 v[92:95], v[174:177], v[182:185], v[92:95]
	v_mfma_f32_16x16x32_bf16 v[88:91], v[166:169], v[190:193], v[88:91]
	v_mfma_f32_16x16x32_bf16 v[84:87], v[174:177], v[190:193], v[84:87]
	v_mfma_f32_16x16x32_bf16 v[80:83], v[166:169], v[198:201], v[80:83]
	v_mfma_f32_16x16x32_bf16 v[76:79], v[174:177], v[198:201], v[76:79]
	v_mfma_f32_16x16x32_bf16 v[72:75], v[166:169], v[206:209], v[72:75]
	v_mfma_f32_16x16x32_bf16 v[68:71], v[174:177], v[206:209], v[68:71]
	s_barrier
	s_mov_b32 m0, s53
	s_add_u32 s72, s34, 0x100000
	s_addc_u32 s73, s35, 0
	ds_read_b128 v[178:181], v162 offset:16384
	ds_read_b128 v[182:185], v162 offset:17408
	ds_read_b128 v[186:189], v162 offset:18432
	ds_read_b128 v[190:193], v162 offset:19456
	ds_read_b128 v[194:197], v162 offset:20480
	ds_read_b128 v[198:201], v162 offset:21504
	ds_read_b128 v[202:205], v162 offset:22528
	ds_read_b128 v[206:209], v162 offset:23552
	global_load_lds_dwordx4 v134, s[34:35]
	s_mov_b32 m0, s54
	s_nop 0
	global_load_lds_dwordx4 v138, s[34:35]
	s_mov_b32 m0, s55
	s_nop 0
	global_load_lds_dwordx4 v134, s[72:73]
	s_mov_b32 m0, s56
	s_nop 0
	global_load_lds_dwordx4 v138, s[72:73]
	s_mov_b32 m0, s52
	s_nop 0
	global_load_lds_dwordx4 v132, s[46:47]
	s_mov_b32 m0, s57
	s_nop 0
	global_load_lds_dwordx4 v136, s[46:47]
	s_waitcnt vmcnt(8)
	s_waitcnt lgkmcnt(0)
	s_barrier
; #define PG8_STAGE(bufoff, gbase, voff) do { _Pragma("unroll") for (int _i = 0; _i < 2; ++_i) \
;         __builtin_amdgcn_global_load_lds((const unsigned*)((const char*)(gbase) + (voff)[_i]), (LAS unsigned*)(lds + (bufoff) + ldsw + _i * 8192), 16, 0, 0); } while (0)
; #define PG8_LDA(dst, b, h) do { _Pragma("unroll") for (int m = 0; m < 4; ++m) _Pragma("unroll") for (int k = 0; k < 2; ++k) dst[m][k] = *(const LAS bf16x8*)(pA + PG8_SA(b, h) + m * 2048 + k * 1024); } while (0)
; #define PG8_LDB(dst, b, h) do { _Pragma("unroll") for (int n = 0; n < 2; ++n) _Pragma("unroll") for (int k = 0; k < 2; ++k) dst[n][k] = *(const LAS bf16x8*)(pB + (PG8_SB(b, h) - 4 * HTB) + n * 2048 + k * 1024); } while (0)
; #define PG8_MMA(ai, bj, At, Bt) do { __builtin_amdgcn_s_setprio(1); _Pragma("unroll") for (int m = 0; m < 4; ++m) _Pragma("unroll") for (int n = 0; n < 2; ++n) _Pragma("unroll") for (int k = 0; k < 2; ++k) \
;         acc[ai][bj][m][n] = __builtin_amdgcn_mfma_f32_16x16x32_bf16(Bt[n][k], At[m][k], acc[ai][bj][m][n], 0, 0, 0); __builtin_amdgcn_s_setprio(0); } while (0)
; #define PG8_WAIT_V(n) asm volatile("s_waitcnt vmcnt(" #n ")" ::: "memory")
; #define PG8_WAIT_L(n) asm volatile("s_waitcnt lgkmcnt(" #n ")" ::: "memory")
; #define PG8_BAR __builtin_amdgcn_s_barrier()
; #define PG8_SCHED __builtin_amdgcn_sched_barrier(0)
; template <class Desc, class Epi, bool ALIGN_EPI>
; __device__ __forceinline__ void gemm_phase(LAS unsigned char* lds, const Desc& D, const Epi& E, int G, int c) {
;     ...
;             PG8_WAIT_V(8); PG8_WAIT_L(0); PG8_BAR; PG8_MMA(1, 0, At, B0); PG8_MMA(1, 1, At, B1); PG8_BAR; PG8_SCHED;
;             PG8_LDB(B0, 1, 0); PG8_LDB(B1, 1, 1); PG8_SCHED; PG8_LDA(At, 1, 0); PG8_STAGE(PG8_SA(0, 1), a2 + hstepA, voffA);
;             PG8_WAIT_V(8); PG8_WAIT_L(0); PG8_BAR; PG8_MMA(0, 0, At, B0); PG8_MMA(0, 1, At, B1); PG8_BAR; PG8_SCHED;
	v_mfma_f32_16x16x32_bf16 v[64:67], v[140:143], v[178:181], v[64:67]
	v_mfma_f32_16x16x32_bf16 v[52:55], v[148:151], v[178:181], v[52:55]
	v_mfma_f32_16x16x32_bf16 v[32:35], v[140:143], v[186:189], v[32:35]
	v_mfma_f32_16x16x32_bf16 v[20:23], v[148:151], v[186:189], v[20:23]
	v_mfma_f32_16x16x32_bf16 v[16:19], v[140:143], v[194:197], v[16:19]
	v_mfma_f32_16x16x32_bf16 v[12:15], v[148:151], v[194:197], v[12:15]
	v_mfma_f32_16x16x32_bf16 v[8:11], v[140:143], v[202:205], v[8:11]
	v_mfma_f32_16x16x32_bf16 v[4:7], v[148:151], v[202:205], v[4:7]
	v_mfma_f32_16x16x32_bf16 v[64:67], v[144:147], v[182:185], v[64:67]
	v_mfma_f32_16x16x32_bf16 v[52:55], v[152:155], v[182:185], v[52:55]
	v_mfma_f32_16x16x32_bf16 v[32:35], v[144:147], v[190:193], v[32:35]
	v_mfma_f32_16x16x32_bf16 v[20:23], v[152:155], v[190:193], v[20:23]
	v_mfma_f32_16x16x32_bf16 v[16:19], v[144:147], v[198:201], v[16:19]
	v_mfma_f32_16x16x32_bf16 v[12:15], v[152:155], v[198:201], v[12:15]
	v_mfma_f32_16x16x32_bf16 v[8:11], v[144:147], v[206:209], v[8:11]
	v_mfma_f32_16x16x32_bf16 v[4:7], v[152:155], v[206:209], v[4:7]
	v_mfma_f32_16x16x32_bf16 v[60:63], v[156:159], v[178:181], v[60:63]
	v_mfma_f32_16x16x32_bf16 v[56:59], v[170:173], v[178:181], v[56:59]
	v_mfma_f32_16x16x32_bf16 v[48:51], v[156:159], v[186:189], v[48:51]
	v_mfma_f32_16x16x32_bf16 v[44:47], v[170:173], v[186:189], v[44:47]
	v_mfma_f32_16x16x32_bf16 v[40:43], v[156:159], v[194:197], v[40:43]
	v_mfma_f32_16x16x32_bf16 v[36:39], v[170:173], v[194:197], v[36:39]
	v_mfma_f32_16x16x32_bf16 v[28:31], v[156:159], v[202:205], v[28:31]
	v_mfma_f32_16x16x32_bf16 v[24:27], v[170:173], v[202:205], v[24:27]
	v_mfma_f32_16x16x32_bf16 v[60:63], v[166:169], v[182:185], v[60:63]
	v_mfma_f32_16x16x32_bf16 v[56:59], v[174:177], v[182:185], v[56:59]
	v_mfma_f32_16x16x32_bf16 v[48:51], v[166:169], v[190:193], v[48:51]
	v_mfma_f32_16x16x32_bf16 v[44:47], v[174:177], v[190:193], v[44:47]
	v_mfma_f32_16x16x32_bf16 v[40:43], v[166:169], v[198:201], v[40:43]
	v_mfma_f32_16x16x32_bf16 v[36:39], v[174:177], v[198:201], v[36:39]
	v_mfma_f32_16x16x32_bf16 v[28:31], v[166:169], v[206:209], v[28:31]
	v_mfma_f32_16x16x32_bf16 v[24:27], v[174:177], v[206:209], v[24:27]
	s_barrier
	ds_read_b128 v[140:143], v163 offset:32768
	ds_read_b128 v[144:147], v163 offset:33792
	ds_read_b128 v[148:151], v163 offset:34816
	ds_read_b128 v[152:155], v163 offset:35840
	ds_read_b128 v[156:159], v163 offset:49152
	ds_read_b128 v[166:169], v163 offset:50176
	ds_read_b128 v[170:173], v163 offset:51200
	ds_read_b128 v[174:177], v163 offset:52224
	s_add_u32 s46, s46, 0x100000
	s_addc_u32 s47, s47, 0
	s_mov_b32 m0, s58
	ds_read_b128 v[178:181], v162 offset:32768
	ds_read_b128 v[182:185], v162 offset:33792
	ds_read_b128 v[186:189], v162 offset:34816
	ds_read_b128 v[190:193], v162 offset:35840
	ds_read_b128 v[194:197], v162 offset:36864
	ds_read_b128 v[198:201], v162 offset:37888
	ds_read_b128 v[202:205], v162 offset:38912
	ds_read_b128 v[206:209], v162 offset:39936
	global_load_lds_dwordx4 v132, s[46:47]
	s_mov_b32 m0, s59
	s_nop 0
	global_load_lds_dwordx4 v136, s[46:47]
	s_waitcnt vmcnt(8)
	s_waitcnt lgkmcnt(0)
	s_barrier
	v_mfma_f32_16x16x32_bf16 v[128:131], v[140:143], v[178:181], v[128:131]
	v_mfma_f32_16x16x32_bf16 v[124:127], v[148:151], v[178:181], v[124:127]
	v_mfma_f32_16x16x32_bf16 v[120:123], v[140:143], v[186:189], v[120:123]
	v_mfma_f32_16x16x32_bf16 v[116:119], v[148:151], v[186:189], v[116:119]
	v_mfma_f32_16x16x32_bf16 v[112:115], v[140:143], v[194:197], v[112:115]
	v_mfma_f32_16x16x32_bf16 v[108:111], v[148:151], v[194:197], v[108:111]
	v_mfma_f32_16x16x32_bf16 v[104:107], v[140:143], v[202:205], v[104:107]
	v_mfma_f32_16x16x32_bf16 v[100:103], v[148:151], v[202:205], v[100:103]
	v_mfma_f32_16x16x32_bf16 v[128:131], v[144:147], v[182:185], v[128:131]
	v_mfma_f32_16x16x32_bf16 v[124:127], v[152:155], v[182:185], v[124:127]
	v_mfma_f32_16x16x32_bf16 v[120:123], v[144:147], v[190:193], v[120:123]
	v_mfma_f32_16x16x32_bf16 v[116:119], v[152:155], v[190:193], v[116:119]
	v_mfma_f32_16x16x32_bf16 v[112:115], v[144:147], v[198:201], v[112:115]
	v_mfma_f32_16x16x32_bf16 v[108:111], v[152:155], v[198:201], v[108:111]
	v_mfma_f32_16x16x32_bf16 v[104:107], v[144:147], v[206:209], v[104:107]
	v_mfma_f32_16x16x32_bf16 v[100:103], v[152:155], v[206:209], v[100:103]
	v_mfma_f32_16x16x32_bf16 v[96:99], v[156:159], v[178:181], v[96:99]
	v_mfma_f32_16x16x32_bf16 v[92:95], v[170:173], v[178:181], v[92:95]
	v_mfma_f32_16x16x32_bf16 v[88:91], v[156:159], v[186:189], v[88:91]
	v_mfma_f32_16x16x32_bf16 v[84:87], v[170:173], v[186:189], v[84:87]
	v_mfma_f32_16x16x32_bf16 v[80:83], v[156:159], v[194:197], v[80:83]
	v_mfma_f32_16x16x32_bf16 v[76:79], v[170:173], v[194:197], v[76:79]
	v_mfma_f32_16x16x32_bf16 v[72:75], v[156:159], v[202:205], v[72:75]
	v_mfma_f32_16x16x32_bf16 v[68:71], v[170:173], v[202:205], v[68:71]
	v_mfma_f32_16x16x32_bf16 v[96:99], v[166:169], v[182:185], v[96:99]
	v_mfma_f32_16x16x32_bf16 v[92:95], v[174:177], v[182:185], v[92:95]
	v_mfma_f32_16x16x32_bf16 v[88:91], v[166:169], v[190:193], v[88:91]
	v_mfma_f32_16x16x32_bf16 v[84:87], v[174:177], v[190:193], v[84:87]
	v_mfma_f32_16x16x32_bf16 v[80:83], v[166:169], v[198:201], v[80:83]
	v_mfma_f32_16x16x32_bf16 v[76:79], v[174:177], v[198:201], v[76:79]
	v_mfma_f32_16x16x32_bf16 v[72:75], v[166:169], v[206:209], v[72:75]
	v_mfma_f32_16x16x32_bf16 v[68:71], v[174:177], v[206:209], v[68:71]
	s_barrier
; #define PG8_STAGE(bufoff, gbase, voff) do { _Pragma("unroll") for (int _i = 0; _i < 2; ++_i) \
;         __builtin_amdgcn_global_load_lds((const unsigned*)((const char*)(gbase) + (voff)[_i]), (LAS unsigned*)(lds + (bufoff) + ldsw + _i * 8192), 16, 0, 0); } while (0)
; #define PG8_LDA(dst, b, h) do { _Pragma("unroll") for (int m = 0; m < 4; ++m) _Pragma("unroll") for (int k = 0; k < 2; ++k) dst[m][k] = *(const LAS bf16x8*)(pA + PG8_SA(b, h) + m * 2048 + k * 1024); } while (0)
; #define PG8_MMA(ai, bj, At, Bt) do { __builtin_amdgcn_s_setprio(1); _Pragma("unroll") for (int m = 0; m < 4; ++m) _Pragma("unroll") for (int n = 0; n < 2; ++n) _Pragma("unroll") for (int k = 0; k < 2; ++k) \
;         acc[ai][bj][m][n] = __builtin_amdgcn_mfma_f32_16x16x32_bf16(Bt[n][k], At[m][k], acc[ai][bj][m][n], 0, 0, 0); __builtin_amdgcn_s_setprio(0); } while (0)
; #define PG8_WAIT_V(n) asm volatile("s_waitcnt vmcnt(" #n ")" ::: "memory")
; #define PG8_WAIT_L(n) asm volatile("s_waitcnt lgkmcnt(" #n ")" ::: "memory")
; #define PG8_BAR __builtin_amdgcn_s_barrier()
; #define PG8_SCHED __builtin_amdgcn_sched_barrier(0)
; template <class Desc, class Epi, bool ALIGN_EPI>
; __device__ __forceinline__ void gemm_phase(LAS unsigned char* lds, const Desc& D, const Epi& E, int G, int c) {
;     ...
;             PG8_LDA(At, 1, 1); PG8_STAGE(PG8_SB(1, 0), b3, voffB); PG8_STAGE(PG8_SB(1, 1), b3 + hstepB, voffB); PG8_STAGE(PG8_SA(1, 0), a3, voffA);
;             PG8_WAIT_V(8); PG8_WAIT_L(0); PG8_BAR; PG8_MMA(1, 0, At, B0); PG8_MMA(1, 1, At, B1); PG8_BAR; PG8_SCHED;
;         }
	s_mov_b32 m0, s61
	s_add_u32 s74, s34, 0x80
	s_addc_u32 s75, s35, 0
	s_add_u32 s34, s34, 0x100080
	s_addc_u32 s35, s35, 0
	ds_read_b128 v[178:181], v162 offset:49152
	ds_read_b128 v[182:185], v162 offset:50176
	ds_read_b128 v[186:189], v162 offset:51200
	ds_read_b128 v[190:193], v162 offset:52224
	ds_read_b128 v[194:197], v162 offset:53248
	ds_read_b128 v[198:201], v162 offset:54272
	ds_read_b128 v[202:205], v162 offset:55296
	ds_read_b128 v[206:209], v162 offset:56320
	global_load_lds_dwordx4 v134, s[74:75]
	s_mov_b32 m0, s62
	s_nop 0
	global_load_lds_dwordx4 v138, s[74:75]
	s_mov_b32 m0, s65
	s_nop 0
	global_load_lds_dwordx4 v134, s[34:35]
	s_mov_b32 m0, s67
	s_nop 0
	global_load_lds_dwordx4 v138, s[34:35]
	s_sub_u32 s74, s46, 0xfff80
	s_subb_u32 s75, s47, 0
	s_mov_b32 m0, s63
	s_nop 0
	global_load_lds_dwordx4 v132, s[74:75]
	s_mov_b32 m0, s64
	s_nop 0
	global_load_lds_dwordx4 v136, s[74:75]
	s_waitcnt vmcnt(8)
	s_waitcnt lgkmcnt(0)
	s_barrier
	v_mfma_f32_16x16x32_bf16 v[64:67], v[140:143], v[178:181], v[64:67]
	v_mfma_f32_16x16x32_bf16 v[52:55], v[148:151], v[178:181], v[52:55]
	v_mfma_f32_16x16x32_bf16 v[32:35], v[140:143], v[186:189], v[32:35]
	v_mfma_f32_16x16x32_bf16 v[20:23], v[148:151], v[186:189], v[20:23]
	v_mfma_f32_16x16x32_bf16 v[16:19], v[140:143], v[194:197], v[16:19]
	v_mfma_f32_16x16x32_bf16 v[12:15], v[148:151], v[194:197], v[12:15]
	v_mfma_f32_16x16x32_bf16 v[8:11], v[140:143], v[202:205], v[8:11]
	v_mfma_f32_16x16x32_bf16 v[4:7], v[148:151], v[202:205], v[4:7]
	v_mfma_f32_16x16x32_bf16 v[64:67], v[144:147], v[182:185], v[64:67]
	v_mfma_f32_16x16x32_bf16 v[52:55], v[152:155], v[182:185], v[52:55]
	v_mfma_f32_16x16x32_bf16 v[32:35], v[144:147], v[190:193], v[32:35]
	v_mfma_f32_16x16x32_bf16 v[20:23], v[152:155], v[190:193], v[20:23]
	v_mfma_f32_16x16x32_bf16 v[16:19], v[144:147], v[198:201], v[16:19]
	v_mfma_f32_16x16x32_bf16 v[12:15], v[152:155], v[198:201], v[12:15]
	v_mfma_f32_16x16x32_bf16 v[8:11], v[144:147], v[206:209], v[8:11]
	v_mfma_f32_16x16x32_bf16 v[4:7], v[152:155], v[206:209], v[4:7]
	v_mfma_f32_16x16x32_bf16 v[60:63], v[156:159], v[178:181], v[60:63]
	v_mfma_f32_16x16x32_bf16 v[56:59], v[170:173], v[178:181], v[56:59]
	v_mfma_f32_16x16x32_bf16 v[48:51], v[156:159], v[186:189], v[48:51]
	v_mfma_f32_16x16x32_bf16 v[44:47], v[170:173], v[186:189], v[44:47]
	v_mfma_f32_16x16x32_bf16 v[40:43], v[156:159], v[194:197], v[40:43]
	v_mfma_f32_16x16x32_bf16 v[36:39], v[170:173], v[194:197], v[36:39]
	v_mfma_f32_16x16x32_bf16 v[28:31], v[156:159], v[202:205], v[28:31]
	v_mfma_f32_16x16x32_bf16 v[24:27], v[170:173], v[202:205], v[24:27]
	v_mfma_f32_16x16x32_bf16 v[60:63], v[166:169], v[182:185], v[60:63]
	v_mfma_f32_16x16x32_bf16 v[56:59], v[174:177], v[182:185], v[56:59]
	v_mfma_f32_16x16x32_bf16 v[48:51], v[166:169], v[190:193], v[48:51]
	v_mfma_f32_16x16x32_bf16 v[44:47], v[174:177], v[190:193], v[44:47]
	v_mfma_f32_16x16x32_bf16 v[40:43], v[166:169], v[198:201], v[40:43]
	v_mfma_f32_16x16x32_bf16 v[36:39], v[174:177], v[198:201], v[36:39]
	v_mfma_f32_16x16x32_bf16 v[28:31], v[166:169], v[206:209], v[28:31]
	v_mfma_f32_16x16x32_bf16 v[24:27], v[174:177], v[206:209], v[24:27]
	s_barrier
	s_cmp_ge_u32 s30, s2
	s_cbranch_scc1 .LBB0_1591

;     __device__ __forceinline__ int nt(const Unit& u) const { return (u.pn >> 1) < 2 ? 22 : 20; }
; #define PG8_STAGE(bufoff, gbase, voff) do { _Pragma("unroll") for (int _i = 0; _i < 2; ++_i) \
;         __builtin_amdgcn_global_load_lds((const unsigned*)((const char*)(gbase) + (voff)[_i]), (LAS unsigned*)(lds + (bufoff) + ldsw + _i * 8192), 16, 0, 0); } while (0)
; #define PG8_LDA(dst, b, h) do { _Pragma("unroll") for (int m = 0; m < 4; ++m) _Pragma("unroll") for (int k = 0; k < 2; ++k) dst[m][k] = *(const LAS bf16x8*)(pA + PG8_SA(b, h) + m * 2048 + k * 1024); } while (0)
; #define PG8_LDB(dst, b, h) do { _Pragma("unroll") for (int n = 0; n < 2; ++n) _Pragma("unroll") for (int k = 0; k < 2; ++k) dst[n][k] = *(const LAS bf16x8*)(pB + (PG8_SB(b, h) - 4 * HTB) + n * 2048 + k * 1024); } while (0)
; #define PG8_MMA(ai, bj, At, Bt) do { __builtin_amdgcn_s_setprio(1); _Pragma("unroll") for (int m = 0; m < 4; ++m) _Pragma("unroll") for (int n = 0; n < 2; ++n) _Pragma("unroll") for (int k = 0; k < 2; ++k) \
;         acc[ai][bj][m][n] = __builtin_amdgcn_mfma_f32_16x16x32_bf16(Bt[n][k], At[m][k], acc[ai][bj][m][n], 0, 0, 0); __builtin_amdgcn_s_setprio(0); } while (0)
; #define PG8_WAIT_V(n) asm volatile("s_waitcnt vmcnt(" #n ")" ::: "memory")
; #define PG8_WAIT_L(n) asm volatile("s_waitcnt lgkmcnt(" #n ")" ::: "memory")
; template <class Desc, class Epi, bool ALIGN_EPI>
; __device__ __forceinline__ void gemm_phase(LAS unsigned char* lds, const Desc& D, const Epi& E, int G, int c) {
;     ...
;             const bool last = (t == nt - 2);
;             if (last && has_next) PG8_AWAIT(nxt);
;             const char* a1 = cA + (size_t)(t + 1) * kstep;
;             const char* a2 = last ? nA : cA + (size_t)(t + 2) * kstep; const char* b2 = last ? nB : cB + (size_t)(t + 2) * kstep;
;             const char* a3 = a2 + kstep; const char* b3 = b2 + kstep;
;             PG8_LDB(B0, 0, 0); PG8_LDB(B1, 0, 1); PG8_SCHED; PG8_LDA(At, 0, 0); PG8_STAGE(PG8_SA(1, 1), a1 + hstepA, voffA);
;             PG8_WAIT_V(8); PG8_WAIT_L(0); PG8_BAR; PG8_MMA(0, 0, At, B0); PG8_MMA(0, 1, At, B1); PG8_BAR; PG8_SCHED;
;             PG8_LDA(At, 0, 1); PG8_STAGE(PG8_SB(0, 0), b2, voffB); PG8_STAGE(PG8_SB(0, 1), b2 + hstepB, voffB); PG8_STAGE(PG8_SA(0, 0), a2, voffA);
;             PG8_WAIT_V(8); PG8_WAIT_L(0); PG8_BAR; PG8_MMA(1, 0, At, B0); PG8_MMA(1, 1, At, B1); PG8_BAR; PG8_SCHED;
.LBB0_1765:
	s_or_b32 s14, s39, 1
	s_lshl_b64 s[40:41], s[14:15], 7
	s_add_i32 s14, s39, 2
	s_lshl_b64 s[42:43], s[14:15], 7
	s_add_u32 s39, s12, s42
	s_waitcnt lgkmcnt(0)
	ds_read_b128 v[132:135], v248
	ds_read_b128 v[136:139], v248 offset:1024
	ds_read_b128 v[140:143], v248 offset:2048
	ds_read_b128 v[144:147], v248 offset:3072
	ds_read_b128 v[148:151], v248 offset:16384
	ds_read_b128 v[152:155], v248 offset:17408
	ds_read_b128 v[156:159], v248 offset:18432
	ds_read_b128 v[160:163], v248 offset:19456
	s_addc_u32 s78, s13, s43
	s_and_b64 s[30:31], s[20:21], exec
	s_cselect_b32 s31, s49, s78
	s_cselect_b32 s30, s48, s39
	s_add_u32 s39, s16, s42
	s_addc_u32 s42, s17, s43
	s_and_b64 s[20:21], s[20:21], exec
	s_cselect_b32 s21, s51, s42
	s_cselect_b32 s20, s50, s39
	s_add_u32 s39, s12, s40
	s_addc_u32 s41, s13, s41
	s_add_u32 s40, s39, 0x2b0000
	s_addc_u32 s41, s41, 0
	v_lshl_add_u64 v[196:197], s[40:41], 0, v[200:201]
	s_add_i32 m0, s56, 0xc000
	ds_read_b128 v[164:167], v247
	ds_read_b128 v[168:171], v247 offset:1024
	ds_read_b128 v[172:175], v247 offset:2048
	ds_read_b128 v[176:179], v247 offset:3072
	ds_read_b128 v[180:183], v247 offset:4096
	ds_read_b128 v[184:187], v247 offset:5120
	ds_read_b128 v[188:191], v247 offset:6144
	ds_read_b128 v[192:195], v247 offset:7168
	global_load_lds_dwordx4 v[196:197], off
	v_lshl_add_u64 v[196:197], s[40:41], 0, v[204:205]
	s_add_i32 m0, s56, 0xe000
	s_nop 0
	global_load_lds_dwordx4 v[196:197], off
	s_waitcnt vmcnt(8)
	s_waitcnt lgkmcnt(0)
	s_barrier
	v_mfma_f32_16x16x32_bf16 v[128:131], v[132:135], v[164:167], v[128:131]
	v_mfma_f32_16x16x32_bf16 v[124:127], v[140:143], v[164:167], v[124:127]
	v_mfma_f32_16x16x32_bf16 v[120:123], v[132:135], v[172:175], v[120:123]
	v_mfma_f32_16x16x32_bf16 v[116:119], v[140:143], v[172:175], v[116:119]
	v_mfma_f32_16x16x32_bf16 v[112:115], v[132:135], v[180:183], v[112:115]
	v_mfma_f32_16x16x32_bf16 v[108:111], v[140:143], v[180:183], v[108:111]
	v_mfma_f32_16x16x32_bf16 v[104:107], v[132:135], v[188:191], v[104:107]
	v_mfma_f32_16x16x32_bf16 v[100:103], v[140:143], v[188:191], v[100:103]
	v_mfma_f32_16x16x32_bf16 v[128:131], v[136:139], v[168:171], v[128:131]
	v_mfma_f32_16x16x32_bf16 v[124:127], v[144:147], v[168:171], v[124:127]
	v_mfma_f32_16x16x32_bf16 v[120:123], v[136:139], v[176:179], v[120:123]
	v_mfma_f32_16x16x32_bf16 v[116:119], v[144:147], v[176:179], v[116:119]
	v_mfma_f32_16x16x32_bf16 v[112:115], v[136:139], v[184:187], v[112:115]
	v_mfma_f32_16x16x32_bf16 v[108:111], v[144:147], v[184:187], v[108:111]
	v_mfma_f32_16x16x32_bf16 v[104:107], v[136:139], v[192:195], v[104:107]
	v_mfma_f32_16x16x32_bf16 v[100:103], v[144:147], v[192:195], v[100:103]
	v_mfma_f32_16x16x32_bf16 v[96:99], v[148:151], v[164:167], v[96:99]
	v_mfma_f32_16x16x32_bf16 v[92:95], v[156:159], v[164:167], v[92:95]
	v_mfma_f32_16x16x32_bf16 v[88:91], v[148:151], v[172:175], v[88:91]
	v_mfma_f32_16x16x32_bf16 v[80:83], v[156:159], v[172:175], v[80:83]
	v_mfma_f32_16x16x32_bf16 v[64:67], v[148:151], v[180:183], v[64:67]
	v_mfma_f32_16x16x32_bf16 v[52:55], v[156:159], v[180:183], v[52:55]
	v_mfma_f32_16x16x32_bf16 v[32:35], v[148:151], v[188:191], v[32:35]
	v_mfma_f32_16x16x32_bf16 v[20:23], v[156:159], v[188:191], v[20:23]
	v_mfma_f32_16x16x32_bf16 v[96:99], v[152:155], v[168:171], v[96:99]
	v_mfma_f32_16x16x32_bf16 v[92:95], v[160:163], v[168:171], v[92:95]
	v_mfma_f32_16x16x32_bf16 v[88:91], v[152:155], v[176:179], v[88:91]
	v_mfma_f32_16x16x32_bf16 v[80:83], v[160:163], v[176:179], v[80:83]
	v_mfma_f32_16x16x32_bf16 v[64:67], v[152:155], v[184:187], v[64:67]
	v_mfma_f32_16x16x32_bf16 v[52:55], v[160:163], v[184:187], v[52:55]
	v_mfma_f32_16x16x32_bf16 v[32:35], v[152:155], v[192:195], v[32:35]
	v_mfma_f32_16x16x32_bf16 v[20:23], v[160:163], v[192:195], v[20:23]
	s_barrier
	s_mov_b32 m0, s57
	v_lshl_add_u64 v[196:197], s[20:21], 0, v[202:203]
	s_add_u32 s40, s20, 0x2b0000
	ds_read_b128 v[164:167], v247 offset:16384
	ds_read_b128 v[168:171], v247 offset:17408
	ds_read_b128 v[172:175], v247 offset:18432
	ds_read_b128 v[176:179], v247 offset:19456
	ds_read_b128 v[180:183], v247 offset:20480
	ds_read_b128 v[184:187], v247 offset:21504
	ds_read_b128 v[188:191], v247 offset:22528
	ds_read_b128 v[192:195], v247 offset:23552
	global_load_lds_dwordx4 v[196:197], off
	v_lshl_add_u64 v[198:199], s[20:21], 0, v[206:207]
	s_mov_b32 m0, s58
	s_addc_u32 s41, s21, 0
	global_load_lds_dwordx4 v[198:199], off
	v_lshl_add_u64 v[208:209], s[40:41], 0, v[202:203]
	s_mov_b32 m0, s59
	v_lshl_add_u64 v[210:211], s[30:31], 0, v[204:205]
	global_load_lds_dwordx4 v[208:209], off
	v_lshl_add_u64 v[208:209], s[40:41], 0, v[206:207]
	s_mov_b32 m0, s60
	s_nop 0
	global_load_lds_dwordx4 v[208:209], off
	v_lshl_add_u64 v[208:209], s[30:31], 0, v[200:201]
	s_mov_b32 m0, s56
	s_nop 0
	global_load_lds_dwordx4 v[208:209], off
	s_mov_b32 m0, s61
	s_nop 0
	global_load_lds_dwordx4 v[210:211], off
	s_waitcnt vmcnt(8)
	s_waitcnt lgkmcnt(0)
	s_barrier
; #define PG8_STAGE(bufoff, gbase, voff) do { _Pragma("unroll") for (int _i = 0; _i < 2; ++_i) \
;         __builtin_amdgcn_global_load_lds((const unsigned*)((const char*)(gbase) + (voff)[_i]), (LAS unsigned*)(lds + (bufoff) + ldsw + _i * 8192), 16, 0, 0); } while (0)
; #define PG8_LDA(dst, b, h) do { _Pragma("unroll") for (int m = 0; m < 4; ++m) _Pragma("unroll") for (int k = 0; k < 2; ++k) dst[m][k] = *(const LAS bf16x8*)(pA + PG8_SA(b, h) + m * 2048 + k * 1024); } while (0)
; #define PG8_LDB(dst, b, h) do { _Pragma("unroll") for (int n = 0; n < 2; ++n) _Pragma("unroll") for (int k = 0; k < 2; ++k) dst[n][k] = *(const LAS bf16x8*)(pB + (PG8_SB(b, h) - 4 * HTB) + n * 2048 + k * 1024); } while (0)
; #define PG8_MMA(ai, bj, At, Bt) do { __builtin_amdgcn_s_setprio(1); _Pragma("unroll") for (int m = 0; m < 4; ++m) _Pragma("unroll") for (int n = 0; n < 2; ++n) _Pragma("unroll") for (int k = 0; k < 2; ++k) \
;         acc[ai][bj][m][n] = __builtin_amdgcn_mfma_f32_16x16x32_bf16(Bt[n][k], At[m][k], acc[ai][bj][m][n], 0, 0, 0); __builtin_amdgcn_s_setprio(0); } while (0)
; #define PG8_WAIT_V(n) asm volatile("s_waitcnt vmcnt(" #n ")" ::: "memory")
; #define PG8_WAIT_L(n) asm volatile("s_waitcnt lgkmcnt(" #n ")" ::: "memory")
; #define PG8_BAR __builtin_amdgcn_s_barrier()
; #define PG8_SCHED __builtin_amdgcn_sched_barrier(0)
; template <class Desc, class Epi, bool ALIGN_EPI>
; __device__ __forceinline__ void gemm_phase(LAS unsigned char* lds, const Desc& D, const Epi& E, int G, int c) {
;     ...
;             PG8_WAIT_V(8); PG8_WAIT_L(0); PG8_BAR; PG8_MMA(1, 0, At, B0); PG8_MMA(1, 1, At, B1); PG8_BAR; PG8_SCHED;
;             PG8_LDB(B0, 1, 0); PG8_LDB(B1, 1, 1); PG8_SCHED; PG8_LDA(At, 1, 0); PG8_STAGE(PG8_SA(0, 1), a2 + hstepA, voffA);
;             PG8_WAIT_V(8); PG8_WAIT_L(0); PG8_BAR; PG8_MMA(0, 0, At, B0); PG8_MMA(0, 1, At, B1); PG8_BAR; PG8_SCHED;
	v_mfma_f32_16x16x32_bf16 v[84:87], v[132:135], v[164:167], v[84:87]
	v_mfma_f32_16x16x32_bf16 v[76:79], v[140:143], v[164:167], v[76:79]
	v_mfma_f32_16x16x32_bf16 v[72:75], v[132:135], v[172:175], v[72:75]
	v_mfma_f32_16x16x32_bf16 v[68:71], v[140:143], v[172:175], v[68:71]
	v_mfma_f32_16x16x32_bf16 v[60:63], v[132:135], v[180:183], v[60:63]
	v_mfma_f32_16x16x32_bf16 v[56:59], v[140:143], v[180:183], v[56:59]
	v_mfma_f32_16x16x32_bf16 v[48:51], v[132:135], v[188:191], v[48:51]
	v_mfma_f32_16x16x32_bf16 v[44:47], v[140:143], v[188:191], v[44:47]
	v_mfma_f32_16x16x32_bf16 v[84:87], v[136:139], v[168:171], v[84:87]
	v_mfma_f32_16x16x32_bf16 v[76:79], v[144:147], v[168:171], v[76:79]
	v_mfma_f32_16x16x32_bf16 v[72:75], v[136:139], v[176:179], v[72:75]
	v_mfma_f32_16x16x32_bf16 v[68:71], v[144:147], v[176:179], v[68:71]
	v_mfma_f32_16x16x32_bf16 v[60:63], v[136:139], v[184:187], v[60:63]
	v_mfma_f32_16x16x32_bf16 v[56:59], v[144:147], v[184:187], v[56:59]
	v_mfma_f32_16x16x32_bf16 v[48:51], v[136:139], v[192:195], v[48:51]
	v_mfma_f32_16x16x32_bf16 v[44:47], v[144:147], v[192:195], v[44:47]
	v_mfma_f32_16x16x32_bf16 v[40:43], v[148:151], v[164:167], v[40:43]
	v_mfma_f32_16x16x32_bf16 v[36:39], v[156:159], v[164:167], v[36:39]
	v_mfma_f32_16x16x32_bf16 v[28:31], v[148:151], v[172:175], v[28:31]
	v_mfma_f32_16x16x32_bf16 v[24:27], v[156:159], v[172:175], v[24:27]
	v_mfma_f32_16x16x32_bf16 v[16:19], v[148:151], v[180:183], v[16:19]
	v_mfma_f32_16x16x32_bf16 v[12:15], v[156:159], v[180:183], v[12:15]
	v_mfma_f32_16x16x32_bf16 v[8:11], v[148:151], v[188:191], v[8:11]
	v_mfma_f32_16x16x32_bf16 v[4:7], v[156:159], v[188:191], v[4:7]
	v_mfma_f32_16x16x32_bf16 v[40:43], v[152:155], v[168:171], v[40:43]
	v_mfma_f32_16x16x32_bf16 v[36:39], v[160:163], v[168:171], v[36:39]
	v_mfma_f32_16x16x32_bf16 v[28:31], v[152:155], v[176:179], v[28:31]
	v_mfma_f32_16x16x32_bf16 v[24:27], v[160:163], v[176:179], v[24:27]
	v_mfma_f32_16x16x32_bf16 v[16:19], v[152:155], v[184:187], v[16:19]
	v_mfma_f32_16x16x32_bf16 v[12:15], v[160:163], v[184:187], v[12:15]
	v_mfma_f32_16x16x32_bf16 v[8:11], v[152:155], v[192:195], v[8:11]
	v_mfma_f32_16x16x32_bf16 v[4:7], v[160:163], v[192:195], v[4:7]
	s_barrier
	ds_read_b128 v[132:135], v248 offset:32768
	ds_read_b128 v[136:139], v248 offset:33792
	ds_read_b128 v[140:143], v248 offset:34816
	ds_read_b128 v[144:147], v248 offset:35840
	ds_read_b128 v[148:151], v248 offset:49152
	ds_read_b128 v[152:155], v248 offset:50176
	ds_read_b128 v[156:159], v248 offset:51200
	ds_read_b128 v[160:163], v248 offset:52224
	s_add_u32 s30, s30, 0x2b0000
	s_addc_u32 s31, s31, 0
	s_mov_b32 m0, s62
	v_lshl_add_u64 v[212:213], s[30:31], 0, v[200:201]
	ds_read_b128 v[164:167], v247 offset:32768
	ds_read_b128 v[168:171], v247 offset:33792
	ds_read_b128 v[172:175], v247 offset:34816
	ds_read_b128 v[176:179], v247 offset:35840
	ds_read_b128 v[180:183], v247 offset:36864
	ds_read_b128 v[184:187], v247 offset:37888
	ds_read_b128 v[188:191], v247 offset:38912
	ds_read_b128 v[192:195], v247 offset:39936
	global_load_lds_dwordx4 v[212:213], off
	v_lshl_add_u64 v[212:213], s[30:31], 0, v[204:205]
	s_mov_b32 m0, s63
	s_nop 0
	global_load_lds_dwordx4 v[212:213], off
	s_waitcnt vmcnt(8)
	s_waitcnt lgkmcnt(0)
	s_barrier
	v_mfma_f32_16x16x32_bf16 v[128:131], v[132:135], v[164:167], v[128:131]
	v_mfma_f32_16x16x32_bf16 v[124:127], v[140:143], v[164:167], v[124:127]
	v_mfma_f32_16x16x32_bf16 v[120:123], v[132:135], v[172:175], v[120:123]
	v_mfma_f32_16x16x32_bf16 v[116:119], v[140:143], v[172:175], v[116:119]
	v_mfma_f32_16x16x32_bf16 v[112:115], v[132:135], v[180:183], v[112:115]
	v_mfma_f32_16x16x32_bf16 v[108:111], v[140:143], v[180:183], v[108:111]
	v_mfma_f32_16x16x32_bf16 v[104:107], v[132:135], v[188:191], v[104:107]
	v_mfma_f32_16x16x32_bf16 v[100:103], v[140:143], v[188:191], v[100:103]
	v_mfma_f32_16x16x32_bf16 v[128:131], v[136:139], v[168:171], v[128:131]
	v_mfma_f32_16x16x32_bf16 v[124:127], v[144:147], v[168:171], v[124:127]
	v_mfma_f32_16x16x32_bf16 v[120:123], v[136:139], v[176:179], v[120:123]
	v_mfma_f32_16x16x32_bf16 v[116:119], v[144:147], v[176:179], v[116:119]
	v_mfma_f32_16x16x32_bf16 v[112:115], v[136:139], v[184:187], v[112:115]
	v_mfma_f32_16x16x32_bf16 v[108:111], v[144:147], v[184:187], v[108:111]
	v_mfma_f32_16x16x32_bf16 v[104:107], v[136:139], v[192:195], v[104:107]
	v_mfma_f32_16x16x32_bf16 v[100:103], v[144:147], v[192:195], v[100:103]
	v_mfma_f32_16x16x32_bf16 v[96:99], v[148:151], v[164:167], v[96:99]
	v_mfma_f32_16x16x32_bf16 v[92:95], v[156:159], v[164:167], v[92:95]
	v_mfma_f32_16x16x32_bf16 v[88:91], v[148:151], v[172:175], v[88:91]
	v_mfma_f32_16x16x32_bf16 v[80:83], v[156:159], v[172:175], v[80:83]
	v_mfma_f32_16x16x32_bf16 v[64:67], v[148:151], v[180:183], v[64:67]
	v_mfma_f32_16x16x32_bf16 v[52:55], v[156:159], v[180:183], v[52:55]
	v_mfma_f32_16x16x32_bf16 v[32:35], v[148:151], v[188:191], v[32:35]
	v_mfma_f32_16x16x32_bf16 v[20:23], v[156:159], v[188:191], v[20:23]
	v_mfma_f32_16x16x32_bf16 v[96:99], v[152:155], v[168:171], v[96:99]
	v_mfma_f32_16x16x32_bf16 v[92:95], v[160:163], v[168:171], v[92:95]
	v_mfma_f32_16x16x32_bf16 v[88:91], v[152:155], v[176:179], v[88:91]
	v_mfma_f32_16x16x32_bf16 v[80:83], v[160:163], v[176:179], v[80:83]
	v_mfma_f32_16x16x32_bf16 v[64:67], v[152:155], v[184:187], v[64:67]
	v_mfma_f32_16x16x32_bf16 v[52:55], v[160:163], v[184:187], v[52:55]
	v_mfma_f32_16x16x32_bf16 v[32:35], v[152:155], v[192:195], v[32:35]
	v_mfma_f32_16x16x32_bf16 v[20:23], v[160:163], v[192:195], v[20:23]
	s_barrier
; #define PG8_STAGE(bufoff, gbase, voff) do { _Pragma("unroll") for (int _i = 0; _i < 2; ++_i) \
;         __builtin_amdgcn_global_load_lds((const unsigned*)((const char*)(gbase) + (voff)[_i]), (LAS unsigned*)(lds + (bufoff) + ldsw + _i * 8192), 16, 0, 0); } while (0)
; #define PG8_LDA(dst, b, h) do { _Pragma("unroll") for (int m = 0; m < 4; ++m) _Pragma("unroll") for (int k = 0; k < 2; ++k) dst[m][k] = *(const LAS bf16x8*)(pA + PG8_SA(b, h) + m * 2048 + k * 1024); } while (0)
; #define PG8_MMA(ai, bj, At, Bt) do { __builtin_amdgcn_s_setprio(1); _Pragma("unroll") for (int m = 0; m < 4; ++m) _Pragma("unroll") for (int n = 0; n < 2; ++n) _Pragma("unroll") for (int k = 0; k < 2; ++k) \
;         acc[ai][bj][m][n] = __builtin_amdgcn_mfma_f32_16x16x32_bf16(Bt[n][k], At[m][k], acc[ai][bj][m][n], 0, 0, 0); __builtin_amdgcn_s_setprio(0); } while (0)
; #define PG8_WAIT_V(n) asm volatile("s_waitcnt vmcnt(" #n ")" ::: "memory")
; #define PG8_WAIT_L(n) asm volatile("s_waitcnt lgkmcnt(" #n ")" ::: "memory")
; #define PG8_BAR __builtin_amdgcn_s_barrier()
; #define PG8_SCHED __builtin_amdgcn_sched_barrier(0)
; template <class Desc, class Epi, bool ALIGN_EPI>
; __device__ __forceinline__ void gemm_phase(LAS unsigned char* lds, const Desc& D, const Epi& E, int G, int c) {
;     ...
;             PG8_LDA(At, 1, 1); PG8_STAGE(PG8_SB(1, 0), b3, voffB); PG8_STAGE(PG8_SB(1, 1), b3 + hstepB, voffB); PG8_STAGE(PG8_SA(1, 0), a3, voffA);
;             PG8_WAIT_V(8); PG8_WAIT_L(0); PG8_BAR; PG8_MMA(1, 0, At, B0); PG8_MMA(1, 1, At, B1); PG8_BAR; PG8_SCHED;
;         }
	s_mov_b32 m0, s64
	v_lshl_add_u64 v[196:197], v[196:197], 0, s[76:77]
	s_add_u32 s20, s20, 0x2b0080
	ds_read_b128 v[164:167], v247 offset:49152
	ds_read_b128 v[168:171], v247 offset:50176
	ds_read_b128 v[172:175], v247 offset:51200
	ds_read_b128 v[176:179], v247 offset:52224
	ds_read_b128 v[180:183], v247 offset:53248
	ds_read_b128 v[184:187], v247 offset:54272
	ds_read_b128 v[188:191], v247 offset:55296
	ds_read_b128 v[192:195], v247 offset:56320
	global_load_lds_dwordx4 v[196:197], off
	v_lshl_add_u64 v[196:197], v[198:199], 0, s[76:77]
	s_mov_b32 m0, s65
	s_addc_u32 s21, s21, 0
	global_load_lds_dwordx4 v[196:197], off
	v_lshl_add_u64 v[196:197], s[20:21], 0, v[202:203]
	s_mov_b32 m0, s69
	s_nop 0
	global_load_lds_dwordx4 v[196:197], off
	v_lshl_add_u64 v[196:197], s[20:21], 0, v[206:207]
	s_mov_b32 m0, s70
	s_nop 0
	global_load_lds_dwordx4 v[196:197], off
	v_lshl_add_u64 v[196:197], v[208:209], 0, s[76:77]
	s_mov_b32 m0, s66
	s_nop 0
	global_load_lds_dwordx4 v[196:197], off
	v_lshl_add_u64 v[196:197], v[210:211], 0, s[76:77]
	s_mov_b32 m0, s67
	s_nop 0
	global_load_lds_dwordx4 v[196:197], off
	s_waitcnt vmcnt(8)
	s_waitcnt lgkmcnt(0)
	s_barrier
	v_mfma_f32_16x16x32_bf16 v[84:87], v[132:135], v[164:167], v[84:87]
	v_mfma_f32_16x16x32_bf16 v[76:79], v[140:143], v[164:167], v[76:79]
	v_mfma_f32_16x16x32_bf16 v[72:75], v[132:135], v[172:175], v[72:75]
	v_mfma_f32_16x16x32_bf16 v[68:71], v[140:143], v[172:175], v[68:71]
	v_mfma_f32_16x16x32_bf16 v[60:63], v[132:135], v[180:183], v[60:63]
	v_mfma_f32_16x16x32_bf16 v[56:59], v[140:143], v[180:183], v[56:59]
	v_mfma_f32_16x16x32_bf16 v[48:51], v[132:135], v[188:191], v[48:51]
	v_mfma_f32_16x16x32_bf16 v[44:47], v[140:143], v[188:191], v[44:47]
	v_mfma_f32_16x16x32_bf16 v[84:87], v[136:139], v[168:171], v[84:87]
	v_mfma_f32_16x16x32_bf16 v[76:79], v[144:147], v[168:171], v[76:79]
	v_mfma_f32_16x16x32_bf16 v[72:75], v[136:139], v[176:179], v[72:75]
	v_mfma_f32_16x16x32_bf16 v[68:71], v[144:147], v[176:179], v[68:71]
	v_mfma_f32_16x16x32_bf16 v[60:63], v[136:139], v[184:187], v[60:63]
	v_mfma_f32_16x16x32_bf16 v[56:59], v[144:147], v[184:187], v[56:59]
	v_mfma_f32_16x16x32_bf16 v[48:51], v[136:139], v[192:195], v[48:51]
	v_mfma_f32_16x16x32_bf16 v[44:47], v[144:147], v[192:195], v[44:47]
	v_mfma_f32_16x16x32_bf16 v[40:43], v[148:151], v[164:167], v[40:43]
	v_mfma_f32_16x16x32_bf16 v[36:39], v[156:159], v[164:167], v[36:39]
	v_mfma_f32_16x16x32_bf16 v[28:31], v[148:151], v[172:175], v[28:31]
	v_mfma_f32_16x16x32_bf16 v[24:27], v[156:159], v[172:175], v[24:27]
	v_mfma_f32_16x16x32_bf16 v[16:19], v[148:151], v[180:183], v[16:19]
	v_mfma_f32_16x16x32_bf16 v[12:15], v[156:159], v[180:183], v[12:15]
	v_mfma_f32_16x16x32_bf16 v[8:11], v[148:151], v[188:191], v[8:11]
	v_mfma_f32_16x16x32_bf16 v[4:7], v[156:159], v[188:191], v[4:7]
	v_mfma_f32_16x16x32_bf16 v[40:43], v[152:155], v[168:171], v[40:43]
	v_mfma_f32_16x16x32_bf16 v[36:39], v[160:163], v[168:171], v[36:39]
	v_mfma_f32_16x16x32_bf16 v[28:31], v[152:155], v[176:179], v[28:31]
	v_mfma_f32_16x16x32_bf16 v[24:27], v[160:163], v[176:179], v[24:27]
	v_mfma_f32_16x16x32_bf16 v[16:19], v[152:155], v[184:187], v[16:19]
	v_mfma_f32_16x16x32_bf16 v[12:15], v[160:163], v[184:187], v[12:15]
	v_mfma_f32_16x16x32_bf16 v[8:11], v[152:155], v[192:195], v[8:11]
	v_mfma_f32_16x16x32_bf16 v[4:7], v[160:163], v[192:195], v[4:7]
	s_barrier
	s_cmp_ge_u32 s14, s24
	s_mov_b32 s39, s14
	s_cbranch_scc1 .LBB0_1776
